# plus: self-max canonicalisations removed in B/C/D row-max trees; redundant counted vmcnt waits after vmcnt(0) removed
# baseline (speedup 1.0000x reference)
; __device__ __forceinline__ void pv_d0(f32x16* o, int vb, bf16x8 pa0, bf16x8 pa1, bf16x8 pa2, bf16x8 pa3) {
;     ...
;   const s16x4 l0 = tr_read<v_rd_off(0, 0, 0)>(vb), h0 = tr_read<v_rd_off(0, 0, 1)>(vb);
;   const s16x4 l1 = tr_read<v_rd_off(0, 1, 0)>(vb), h1 = tr_read<v_rd_off(0, 1, 1)>(vb);
;   const s16x4 l2 = tr_read<v_rd_off(0, 2, 0)>(vb), h2 = tr_read<v_rd_off(0, 2, 1)>(vb);
;   const s16x4 l3 = tr_read<v_rd_off(0, 3, 0)>(vb), h3 = tr_read<v_rd_off(0, 3, 1)>(vb);
;   const s16x4 l4 = tr_read<v_rd_off(1, 0, 0)>(vb), h4 = tr_read<v_rd_off(1, 0, 1)>(vb);
;   asm volatile("s_waitcnt lgkmcnt(8)" ::: "memory"); SBAR();
;   o[0] = __builtin_amdgcn_mfma_f32_32x32x16_bf16(pa0, PK(l0, h0), o[0], 0, 0, 0);
;   const s16x4 l5 = tr_read<v_rd_off(1, 1, 0)>(vb), h5 = tr_read<v_rd_off(1, 1, 1)>(vb);
;   asm volatile("s_waitcnt lgkmcnt(8)" ::: "memory"); SBAR();
;   o[0] = __builtin_amdgcn_mfma_f32_32x32x16_bf16(pa1, PK(l1, h1), o[0], 0, 0, 0);
;   const s16x4 l6 = tr_read<v_rd_off(1, 2, 0)>(vb), h6 = tr_read<v_rd_off(1, 2, 1)>(vb);
;   asm volatile("s_waitcnt lgkmcnt(8)" ::: "memory"); SBAR();
;   o[0] = __builtin_amdgcn_mfma_f32_32x32x16_bf16(pa2, PK(l2, h2), o[0], 0, 0, 0);
;   const s16x4 l7 = tr_read<v_rd_off(1, 3, 0)>(vb), h7 = tr_read<v_rd_off(1, 3, 1)>(vb);
;   asm volatile("s_waitcnt lgkmcnt(8)" ::: "memory"); SBAR();
;   o[0] = __builtin_amdgcn_mfma_f32_32x32x16_bf16(pa3, PK(l3, h3), o[0], 0, 0, 0);
;   const s16x4 l8 = tr_read<v_rd_off(2, 0, 0)>(vb), h8 = tr_read<v_rd_off(2, 0, 1)>(vb);
;   asm volatile("s_waitcnt lgkmcnt(8)" ::: "memory"); SBAR();
;   o[1] = __builtin_amdgcn_mfma_f32_32x32x16_bf16(pa0, PK(l4, h4), o[1], 0, 0, 0);
;   const s16x4 l9 = tr_read<v_rd_off(2, 1, 0)>(vb), h9 = tr_read<v_rd_off(2, 1, 1)>(vb);
;   asm volatile("s_waitcnt lgkmcnt(8)" ::: "memory"); SBAR();
;   o[1] = __builtin_amdgcn_mfma_f32_32x32x16_bf16(pa1, PK(l5, h5), o[1], 0, 0, 0);
;   const s16x4 l10 = tr_read<v_rd_off(2, 2, 0)>(vb), h10 = tr_read<v_rd_off(2, 2, 1)>(vb);
;   asm volatile("s_waitcnt lgkmcnt(8)" ::: "memory"); SBAR();
;   o[1] = __builtin_amdgcn_mfma_f32_32x32x16_bf16(pa2, PK(l6, h6), o[1], 0, 0, 0);
;   const s16x4 l11 = tr_read<v_rd_off(2, 3, 0)>(vb), h11 = tr_read<v_rd_off(2, 3, 1)>(vb);
;   asm volatile("s_waitcnt lgkmcnt(8)" ::: "memory"); SBAR();
;   o[1] = __builtin_amdgcn_mfma_f32_32x32x16_bf16(pa3, PK(l7, h7), o[1], 0, 0, 0);
.LBB0_349:
	ds_read_b64_tr_b16 v[150:151], v222 offset:0
	ds_read_b64_tr_b16 v[152:153], v222 offset:0x800
	ds_read_b64_tr_b16 v[154:155], v222 offset:0x1000
	ds_read_b64_tr_b16 v[156:157], v222 offset:0x1800
	ds_read_b64_tr_b16 v[158:159], v222 offset:0x2000
	ds_read_b64_tr_b16 v[160:161], v222 offset:0x2800
	ds_read_b64_tr_b16 v[162:163], v222 offset:0x3000
	ds_read_b64_tr_b16 v[164:165], v222 offset:0x3800
	ds_read_b64_tr_b16 v[166:167], v222 offset:0x200
	ds_read_b64_tr_b16 v[168:169], v222 offset:0xa00
	s_waitcnt lgkmcnt(8)
	s_nop 0
	v_mfma_f32_32x32x16_bf16 v[112:127], v[2:5], v[150:153], v[112:127]
	ds_read_b64_tr_b16 v[150:151], v222 offset:0x1200
	ds_read_b64_tr_b16 v[152:153], v222 offset:0x1a00
	s_waitcnt lgkmcnt(8)
	v_mfma_f32_32x32x16_bf16 v[112:127], v[6:9], v[154:157], v[112:127]
	ds_read_b64_tr_b16 v[154:155], v222 offset:0x2200
	ds_read_b64_tr_b16 v[156:157], v222 offset:0x2a00
	s_waitcnt lgkmcnt(8)
	v_mfma_f32_32x32x16_bf16 v[112:127], v[10:13], v[158:161], v[112:127]
	ds_read_b64_tr_b16 v[158:159], v222 offset:0x3200
	ds_read_b64_tr_b16 v[160:161], v222 offset:0x3a00
	s_waitcnt lgkmcnt(8)
	v_mfma_f32_32x32x16_bf16 v[112:127], v[144:147], v[162:165], v[112:127]
	ds_read_b64_tr_b16 v[162:163], v222 offset:0x400
	ds_read_b64_tr_b16 v[164:165], v222 offset:0xc00
	s_waitcnt lgkmcnt(8)
	v_mfma_f32_32x32x16_bf16 v[64:79], v[2:5], v[166:169], v[64:79]
	ds_read_b64_tr_b16 v[166:167], v222 offset:0x1400
	ds_read_b64_tr_b16 v[168:169], v222 offset:0x1c00
	s_waitcnt lgkmcnt(8)
	v_mfma_f32_32x32x16_bf16 v[64:79], v[6:9], v[150:153], v[64:79]
	ds_read_b64_tr_b16 v[150:151], v222 offset:0x2400
	ds_read_b64_tr_b16 v[152:153], v222 offset:0x2c00
	s_waitcnt lgkmcnt(8)
	v_mfma_f32_32x32x16_bf16 v[64:79], v[10:13], v[154:157], v[64:79]
	ds_read_b64_tr_b16 v[154:155], v222 offset:0x3400
	ds_read_b64_tr_b16 v[156:157], v222 offset:0x3c00
	s_waitcnt lgkmcnt(8)
	v_mfma_f32_32x32x16_bf16 v[64:79], v[144:147], v[158:161], v[64:79]
	ds_read_b64_tr_b16 v[158:159], v222 offset:0x600
	ds_read_b64_tr_b16 v[160:161], v222 offset:0xe00
	s_waitcnt lgkmcnt(8)
	v_mfma_f32_32x32x16_bf16 v[16:31], v[2:5], v[162:165], v[16:31]
	ds_read_b64_tr_b16 v[162:163], v222 offset:0x1600
	ds_read_b64_tr_b16 v[164:165], v222 offset:0x1e00
	s_waitcnt lgkmcnt(8)
	v_mfma_f32_32x32x16_bf16 v[16:31], v[6:9], v[166:169], v[16:31]
	ds_read_b64_tr_b16 v[166:167], v222 offset:0x2600
	ds_read_b64_tr_b16 v[168:169], v222 offset:0x2e00
	s_waitcnt lgkmcnt(8)
	v_mfma_f32_32x32x16_bf16 v[16:31], v[10:13], v[150:153], v[16:31]
	ds_read_b64_tr_b16 v[150:151], v222 offset:0x3600
	ds_read_b64_tr_b16 v[152:153], v222 offset:0x3e00
	s_waitcnt lgkmcnt(8)
	v_mfma_f32_32x32x16_bf16 v[16:31], v[144:147], v[154:157], v[16:31]
	s_waitcnt lgkmcnt(6)
	v_mfma_f32_32x32x16_bf16 v[32:47], v[2:5], v[158:161], v[32:47]
	s_waitcnt lgkmcnt(4)
	v_mfma_f32_32x32x16_bf16 v[32:47], v[6:9], v[162:165], v[32:47]
	s_waitcnt lgkmcnt(2)
	v_mfma_f32_32x32x16_bf16 v[32:47], v[10:13], v[166:169], v[32:47]
	s_waitcnt lgkmcnt(0)
	v_mfma_f32_32x32x16_bf16 v[32:47], v[144:147], v[150:153], v[32:47]
	s_andn2_b64 vcc, exec, s[6:7]
	s_cbranch_vccnz .LBB0_351
	s_xor_b32 s6, s64, 0x4000
	s_add_i32 s6, s6, 0
	v_add_u32_e32 v2, s6, v209
	s_waitcnt vmcnt(0)
	ds_write_b128 v2, v[176:179]
	v_add_u32_e32 v2, s6, v210
	ds_write_b128 v2, v[180:183]
	v_add_u32_e32 v2, s6, v212
	ds_write_b128 v2, v[184:187] offset:32768
	v_add_u32_e32 v2, s6, v213
	ds_write_b128 v2, v[188:191] offset:32768

; __device__ __forceinline__ void qkt12_roll(f32x16& p0, f32x16& p1, const f32x16& negm, int kb, int qa, const bf16x8* qr) {
;   const int a0 = kb ^ (0 << 5); const bf16x8 x0 = lds_rd128<0>(a0), y0 = lds_rd128<12288>(a0);
;   const int a1 = kb ^ (1 << 5); const bf16x8 x1 = lds_rd128<0>(a1), y1 = lds_rd128<12288>(a1);
;   asm volatile("s_waitcnt lgkmcnt(2)" ::: "memory"); SBAR();
;   p0 = __builtin_amdgcn_mfma_f32_32x32x16_bf16(x0, qr[0], negm, 0, 0, 0); p1 = __builtin_amdgcn_mfma_f32_32x32x16_bf16(y0, qr[0], negm, 0, 0, 0);
;   const int a2 = kb ^ (2 << 5); const bf16x8 x2 = lds_rd128<0>(a2), y2 = lds_rd128<12288>(a2);
;   asm volatile("s_waitcnt lgkmcnt(2)" ::: "memory"); SBAR();
;   p0 = __builtin_amdgcn_mfma_f32_32x32x16_bf16(x1, qr[1], p0, 0, 0, 0); p1 = __builtin_amdgcn_mfma_f32_32x32x16_bf16(y1, qr[1], p1, 0, 0, 0);
;   const int a3 = kb ^ (3 << 5); const bf16x8 x3 = lds_rd128<0>(a3), y3 = lds_rd128<12288>(a3);
;   asm volatile("s_waitcnt lgkmcnt(2)" ::: "memory"); SBAR();
;   p0 = __builtin_amdgcn_mfma_f32_32x32x16_bf16(x2, qr[2], p0, 0, 0, 0); p1 = __builtin_amdgcn_mfma_f32_32x32x16_bf16(y2, qr[2], p1, 0, 0, 0);
;   const int a4 = kb ^ (0 << 5); const bf16x8 x4 = lds_rd128<128>(a4), y4 = lds_rd128<12416>(a4);
;   asm volatile("s_waitcnt lgkmcnt(2)" ::: "memory"); SBAR();
;   p0 = __builtin_amdgcn_mfma_f32_32x32x16_bf16(x3, qr[3], p0, 0, 0, 0); p1 = __builtin_amdgcn_mfma_f32_32x32x16_bf16(y3, qr[3], p1, 0, 0, 0);
;   const int a5 = kb ^ (1 << 5); const bf16x8 x5 = lds_rd128<128>(a5), y5 = lds_rd128<12416>(a5);
;   asm volatile("s_waitcnt lgkmcnt(2)" ::: "memory"); SBAR();
;   p0 = __builtin_amdgcn_mfma_f32_32x32x16_bf16(x4, qr[4], p0, 0, 0, 0); p1 = __builtin_amdgcn_mfma_f32_32x32x16_bf16(y4, qr[4], p1, 0, 0, 0);
;   const int a6 = kb ^ (2 << 5); const bf16x8 x6 = lds_rd128<128>(a6), y6 = lds_rd128<12416>(a6);
;   asm volatile("s_waitcnt lgkmcnt(2)" ::: "memory"); SBAR();
;   p0 = __builtin_amdgcn_mfma_f32_32x32x16_bf16(x5, qr[5], p0, 0, 0, 0); p1 = __builtin_amdgcn_mfma_f32_32x32x16_bf16(y5, qr[5], p1, 0, 0, 0);
;   const int a7 = kb ^ (3 << 5); const bf16x8 x7 = lds_rd128<128>(a7), y7 = lds_rd128<12416>(a7);
;   asm volatile("s_waitcnt lgkmcnt(2)" ::: "memory"); SBAR();
;   p0 = __builtin_amdgcn_mfma_f32_32x32x16_bf16(x6, qr[6], p0, 0, 0, 0); p1 = __builtin_amdgcn_mfma_f32_32x32x16_bf16(y6, qr[6], p1, 0, 0, 0);
.LBB0_360:
	v_exp_f32_e32 v66, v66
	v_exp_f32_e32 v67, v67
	v_exp_f32_e32 v68, v68
	v_exp_f32_e32 v69, v69
	v_exp_f32_e32 v70, v70
	v_exp_f32_e32 v71, v71
	v_exp_f32_e32 v72, v72
	v_exp_f32_e32 v73, v73
	v_add_f32_e32 v98, v148, v146
	v_add_f32_e32 v99, v159, v161
	v_add_f32_e32 v100, v149, v147
	v_add_f32_e32 v101, v158, v160
	v_exp_f32_e32 v74, v74
	v_exp_f32_e32 v75, v75
	v_exp_f32_e32 v76, v76
	v_exp_f32_e32 v77, v77
	v_add_f32_e32 v98, v150, v98
	v_add_f32_e32 v99, v157, v99
	v_add_f32_e32 v100, v151, v100
	v_add_f32_e32 v101, v156, v101
	v_exp_f32_e32 v78, v78
	v_exp_f32_e32 v79, v79
	v_exp_f32_e32 v80, v80
	v_exp_f32_e32 v81, v81
	v_add_f32_e32 v98, v152, v98
	v_add_f32_e32 v99, v155, v99
	v_add_f32_e32 v100, v153, v100
	v_add_f32_e32 v101, v154, v101
	v_add_f32_e32 v98, v66, v98
	v_add_f32_e32 v99, v67, v99
	v_add_f32_e32 v100, v68, v100
	v_add_f32_e32 v101, v69, v101
	v_add_f32_e32 v98, v70, v98
	v_add_f32_e32 v99, v71, v99
	v_add_f32_e32 v100, v72, v100
	v_add_f32_e32 v101, v73, v101
	v_add_f32_e32 v98, v74, v98
	v_add_f32_e32 v99, v75, v99
	v_add_f32_e32 v100, v76, v100
	v_add_f32_e32 v101, v77, v101
	v_add_f32_e32 v98, v78, v98
	v_add_f32_e32 v99, v79, v99
	v_add_f32_e32 v100, v80, v100
	v_add_f32_e32 v101, v81, v101
	v_add_f32_e32 v98, v98, v99
	v_add_f32_e32 v99, v100, v101
	v_add_f32_e32 v224, v98, v99
	v_mov_b32_e32 v225, v224
	v_cvt_pk_bf16_f32 v146, v146, v161
	v_cvt_pk_bf16_f32 v147, v147, v160
	v_cvt_pk_bf16_f32 v148, v148, v159
	v_cvt_pk_bf16_f32 v149, v149, v158
	v_cvt_pk_bf16_f32 v150, v150, v157
	v_cvt_pk_bf16_f32 v151, v151, v156
	v_cvt_pk_bf16_f32 v152, v152, v155
	v_cvt_pk_bf16_f32 v153, v153, v154
	v_cvt_pk_bf16_f32 v158, v66, v67
	v_cvt_pk_bf16_f32 v159, v68, v69
	v_cvt_pk_bf16_f32 v160, v70, v71
	v_cvt_pk_bf16_f32 v161, v72, v73
	v_cvt_pk_bf16_f32 v154, v74, v75
	v_cvt_pk_bf16_f32 v155, v76, v77
	v_cvt_pk_bf16_f32 v156, v78, v79
	v_cvt_pk_bf16_f32 v157, v80, v81
	s_nop 1
	v_permlane32_swap_b32_e32 v224, v225
	v_permlane32_swap_b32_e32 v146, v148
	v_permlane32_swap_b32_e32 v147, v149
	v_permlane32_swap_b32_e32 v150, v152
	v_permlane32_swap_b32_e32 v151, v153
	v_permlane32_swap_b32_e32 v158, v160
	v_permlane32_swap_b32_e32 v159, v161
	v_permlane32_swap_b32_e32 v154, v156
	v_permlane32_swap_b32_e32 v155, v157
	v_cmp_neq_f32_e64 s[6:7], v229, -v226
	s_cmp_eq_u64 s[6:7], 0
	s_cselect_b64 s[6:7], -1, 0
	v_cndmask_b32_e64 v81, -v226, v97, s[6:7]
	v_cndmask_b32_e64 v80, -v226, v96, s[6:7]
	v_cndmask_b32_e64 v79, -v226, v95, s[6:7]
	v_cndmask_b32_e64 v78, -v226, v94, s[6:7]
	v_cndmask_b32_e64 v77, -v226, v93, s[6:7]
	v_cndmask_b32_e64 v76, -v226, v92, s[6:7]
	v_cndmask_b32_e64 v75, -v226, v91, s[6:7]
	v_cndmask_b32_e64 v74, -v226, v90, s[6:7]
	v_cndmask_b32_e64 v73, -v226, v89, s[6:7]
	v_cndmask_b32_e64 v72, -v226, v88, s[6:7]
	v_cndmask_b32_e64 v71, -v226, v87, s[6:7]
	v_cndmask_b32_e64 v70, -v226, v86, s[6:7]
	v_cndmask_b32_e64 v69, -v226, v85, s[6:7]
	v_cndmask_b32_e64 v68, -v226, v84, s[6:7]
	v_cndmask_b32_e64 v67, -v226, v83, s[6:7]
	v_cndmask_b32_e64 v66, -v226, v82, s[6:7]
	ds_read_b128 v[82:85], v221 offset:0
	ds_read_b128 v[162:165], v221 offset:0x3000
	ds_read_b128 v[166:169], v220 offset:0
	ds_read_b128 v[170:173], v220 offset:0x3000
	s_waitcnt lgkmcnt(2)
	s_nop 1
	v_mfma_f32_32x32x16_bf16 v[98:113], v[82:85], v[142:145], v[66:81]
	v_mfma_f32_32x32x16_bf16 v[82:97], v[162:165], v[142:145], v[66:81]
	ds_read_b128 v[162:165], v219 offset:0
	ds_read_b128 v[174:177], v219 offset:0x3000
	s_waitcnt lgkmcnt(2)
	v_mfma_f32_32x32x16_bf16 v[98:113], v[166:169], v[138:141], v[98:113]
	ds_read_b128 v[166:169], v218 offset:0
	v_mfma_f32_32x32x16_bf16 v[82:97], v[170:173], v[138:141], v[82:97]
	ds_read_b128 v[170:173], v218 offset:0x3000
	s_waitcnt lgkmcnt(2)
	v_mfma_f32_32x32x16_bf16 v[98:113], v[162:165], v[134:137], v[98:113]
	ds_read_b128 v[162:165], v221 offset:0x80
	v_mfma_f32_32x32x16_bf16 v[82:97], v[174:177], v[134:137], v[82:97]
	ds_read_b128 v[174:177], v221 offset:0x3080
	s_waitcnt lgkmcnt(2)
	v_mfma_f32_32x32x16_bf16 v[98:113], v[166:169], v[130:133], v[98:113]
	ds_read_b128 v[166:169], v220 offset:0x80
	v_mfma_f32_32x32x16_bf16 v[82:97], v[170:173], v[130:133], v[82:97]
	ds_read_b128 v[170:173], v220 offset:0x3080
	s_waitcnt lgkmcnt(2)
	v_mfma_f32_32x32x16_bf16 v[98:113], v[162:165], v[126:129], v[98:113]
	ds_read_b128 v[162:165], v219 offset:0x80
	v_mfma_f32_32x32x16_bf16 v[82:97], v[174:177], v[126:129], v[82:97]
	ds_read_b128 v[174:177], v219 offset:0x3080
	s_waitcnt lgkmcnt(2)
	v_mfma_f32_32x32x16_bf16 v[98:113], v[166:169], v[122:125], v[98:113]
	ds_read_b128 v[166:169], v218 offset:0x80
	v_mfma_f32_32x32x16_bf16 v[82:97], v[170:173], v[122:125], v[82:97]
	ds_read_b128 v[170:173], v218 offset:0x3080
	s_waitcnt lgkmcnt(2)
	v_mfma_f32_32x32x16_bf16 v[98:113], v[162:165], v[118:121], v[98:113]
	ds_read_b128 v[162:165], v221 offset:0x100
	v_mfma_f32_32x32x16_bf16 v[82:97], v[174:177], v[118:121], v[82:97]
	ds_read_b128 v[174:177], v221 offset:0x3100
	ds_read_b128 v[178:181], v199 offset:0
	s_waitcnt lgkmcnt(3)
	v_mfma_f32_32x32x16_bf16 v[98:113], v[166:169], v[114:117], v[98:113]
	ds_read_b128 v[166:169], v220 offset:0x100
	v_mfma_f32_32x32x16_bf16 v[82:97], v[170:173], v[114:117], v[82:97]
	ds_read_b128 v[170:173], v220 offset:0x3100
	ds_read_b128 v[230:233], v199 offset:0x400
	s_waitcnt lgkmcnt(3)
	v_mfma_f32_32x32x16_bf16 v[98:113], v[162:165], v[178:181], v[98:113]
	ds_read_b128 v[162:165], v219 offset:0x100
	v_mfma_f32_32x32x16_bf16 v[82:97], v[174:177], v[178:181], v[82:97]
	ds_read_b128 v[174:177], v219 offset:0x3100
	ds_read_b128 v[178:181], v199 offset:0x800
	s_waitcnt lgkmcnt(3)
	v_mfma_f32_32x32x16_bf16 v[98:113], v[166:169], v[230:233], v[98:113]
	ds_read_b128 v[166:169], v218 offset:0x100
	v_mfma_f32_32x32x16_bf16 v[82:97], v[170:173], v[230:233], v[82:97]
	ds_read_b128 v[170:173], v218 offset:0x3100
	ds_read_b128 v[230:233], v199 offset:0xc00
	s_waitcnt lgkmcnt(3)
	v_mfma_f32_32x32x16_bf16 v[98:113], v[162:165], v[178:181], v[98:113]
	s_waitcnt lgkmcnt(0)
	v_mfma_f32_32x32x16_bf16 v[82:97], v[174:177], v[178:181], v[82:97]
	v_mfma_f32_32x32x16_bf16 v[98:113], v[166:169], v[230:233], v[98:113]
	v_mfma_f32_32x32x16_bf16 v[82:97], v[170:173], v[230:233], v[82:97]
	s_nop 10
	v_max_f32_e32 v162, v98, v102
	v_max_f32_e32 v163, v99, v103
	v_max_f32_e32 v164, v101, v105
	v_max3_f32 v165, v100, v104, v108
	v_max3_f32 v164, v164, v109, v113
	v_max3_f32 v162, v162, v106, v110
	v_max3_f32 v163, v163, v107, v111
	v_max3_f32 v165, v165, v112, v84
	v_max3_f32 v164, v164, v85, v89
	v_max3_f32 v162, v162, v82, v86
	v_max3_f32 v163, v163, v83, v87
	v_max3_f32 v165, v165, v88, v92
	v_max3_f32 v164, v164, v93, v97
	v_max3_f32 v162, v162, v90, v94
	v_max3_f32 v163, v163, v91, v95
	v_max3_f32 v164, v165, v96, v164
	v_max3_f32 v162, v162, v163, v164
	v_mov_b32_e32 v163, v162
	s_nop 1
	v_permlane32_swap_b32_e32 v162, v163
	v_max_f32_e32 v162, v162, v163
	v_cmp_ge_f32_e32 vcc, s48, v162
	s_cmp_eq_u64 vcc, exec
	s_cbranch_scc0 .LBB0_374
	v_mov_b32_e32 v228, v226
	v_mov_b32_e32 v227, 1.0
; __device__ __forceinline__ void pv_d0(f32x16* o, int vb, bf16x8 pa0, bf16x8 pa1, bf16x8 pa2, bf16x8 pa3) {
;     ...
;   const s16x4 l0 = tr_read<v_rd_off(0, 0, 0)>(vb), h0 = tr_read<v_rd_off(0, 0, 1)>(vb);
;   const s16x4 l1 = tr_read<v_rd_off(0, 1, 0)>(vb), h1 = tr_read<v_rd_off(0, 1, 1)>(vb);
;   const s16x4 l2 = tr_read<v_rd_off(0, 2, 0)>(vb), h2 = tr_read<v_rd_off(0, 2, 1)>(vb);
;   const s16x4 l3 = tr_read<v_rd_off(0, 3, 0)>(vb), h3 = tr_read<v_rd_off(0, 3, 1)>(vb);
;   const s16x4 l4 = tr_read<v_rd_off(1, 0, 0)>(vb), h4 = tr_read<v_rd_off(1, 0, 1)>(vb);
;   asm volatile("s_waitcnt lgkmcnt(8)" ::: "memory"); SBAR();
;   o[0] = __builtin_amdgcn_mfma_f32_32x32x16_bf16(pa0, PK(l0, h0), o[0], 0, 0, 0);
;   const s16x4 l5 = tr_read<v_rd_off(1, 1, 0)>(vb), h5 = tr_read<v_rd_off(1, 1, 1)>(vb);
;   asm volatile("s_waitcnt lgkmcnt(8)" ::: "memory"); SBAR();
;   o[0] = __builtin_amdgcn_mfma_f32_32x32x16_bf16(pa1, PK(l1, h1), o[0], 0, 0, 0);
;   const s16x4 l6 = tr_read<v_rd_off(1, 2, 0)>(vb), h6 = tr_read<v_rd_off(1, 2, 1)>(vb);
;   asm volatile("s_waitcnt lgkmcnt(8)" ::: "memory"); SBAR();
;   o[0] = __builtin_amdgcn_mfma_f32_32x32x16_bf16(pa2, PK(l2, h2), o[0], 0, 0, 0);
;   const s16x4 l7 = tr_read<v_rd_off(1, 3, 0)>(vb), h7 = tr_read<v_rd_off(1, 3, 1)>(vb);
;   asm volatile("s_waitcnt lgkmcnt(8)" ::: "memory"); SBAR();
;   o[0] = __builtin_amdgcn_mfma_f32_32x32x16_bf16(pa3, PK(l3, h3), o[0], 0, 0, 0);
;   const s16x4 l8 = tr_read<v_rd_off(2, 0, 0)>(vb), h8 = tr_read<v_rd_off(2, 0, 1)>(vb);
;   asm volatile("s_waitcnt lgkmcnt(8)" ::: "memory"); SBAR();
;   o[1] = __builtin_amdgcn_mfma_f32_32x32x16_bf16(pa0, PK(l4, h4), o[1], 0, 0, 0);
;   const s16x4 l9 = tr_read<v_rd_off(2, 1, 0)>(vb), h9 = tr_read<v_rd_off(2, 1, 1)>(vb);
;   asm volatile("s_waitcnt lgkmcnt(8)" ::: "memory"); SBAR();
;   o[1] = __builtin_amdgcn_mfma_f32_32x32x16_bf16(pa1, PK(l5, h5), o[1], 0, 0, 0);
;   const s16x4 l10 = tr_read<v_rd_off(2, 2, 0)>(vb), h10 = tr_read<v_rd_off(2, 2, 1)>(vb);
;   asm volatile("s_waitcnt lgkmcnt(8)" ::: "memory"); SBAR();
;   o[1] = __builtin_amdgcn_mfma_f32_32x32x16_bf16(pa2, PK(l6, h6), o[1], 0, 0, 0);
;   const s16x4 l11 = tr_read<v_rd_off(2, 3, 0)>(vb), h11 = tr_read<v_rd_off(2, 3, 1)>(vb);
;   asm volatile("s_waitcnt lgkmcnt(8)" ::: "memory"); SBAR();
;   o[1] = __builtin_amdgcn_mfma_f32_32x32x16_bf16(pa3, PK(l7, h7), o[1], 0, 0, 0);
.LBB0_362:
	v_lshl_add_u64 v[190:191], s[42:43], 0, v[188:189]
	v_add_co_u32_e32 v166, vcc, s49, v190
	v_lshl_add_u64 v[196:197], s[42:43], 0, v[186:187]
	s_nop 0
	v_addc_co_u32_e32 v167, vcc, 0, v191, vcc
	v_add_co_u32_e32 v170, vcc, s28, v190
	s_nop 1
	v_addc_co_u32_e32 v171, vcc, 0, v191, vcc
	global_load_dwordx4 v[162:165], v[166:167], off offset:256
	s_nop 0
	global_load_dwordx4 v[166:169], v[166:167], off
	s_nop 0
	global_load_dwordx4 v[174:177], v[170:171], off offset:256
	s_nop 0
	global_load_dwordx4 v[170:173], v[170:171], off
	v_add_co_u32_e32 v178, vcc, s68, v196
	s_nop 1
	v_addc_co_u32_e32 v179, vcc, 0, v197, vcc
	global_load_dwordx4 v[178:181], v[178:179], off
	ds_read_b64_tr_b16 v[230:231], v201 offset:0
	ds_read_b64_tr_b16 v[232:233], v201 offset:0x800
	ds_read_b64_tr_b16 v[234:235], v201 offset:0x1000
	ds_read_b64_tr_b16 v[236:237], v201 offset:0x1800
	ds_read_b64_tr_b16 v[238:239], v201 offset:0x2000
	ds_read_b64_tr_b16 v[240:241], v201 offset:0x2800
	ds_read_b64_tr_b16 v[242:243], v201 offset:0x3000
	ds_read_b64_tr_b16 v[244:245], v201 offset:0x3800
	ds_read_b64_tr_b16 v[246:247], v201 offset:0x200
	ds_read_b64_tr_b16 v[248:249], v201 offset:0xa00
	s_waitcnt lgkmcnt(8)
	s_nop 0
	v_mfma_f32_32x32x16_bf16 v[2:17], v[146:149], v[230:233], v[2:17]
	ds_read_b64_tr_b16 v[230:231], v201 offset:0x1200
	ds_read_b64_tr_b16 v[232:233], v201 offset:0x1a00
	s_waitcnt lgkmcnt(8)
	v_mfma_f32_32x32x16_bf16 v[2:17], v[150:153], v[234:237], v[2:17]
	ds_read_b64_tr_b16 v[234:235], v201 offset:0x2200
	ds_read_b64_tr_b16 v[236:237], v201 offset:0x2a00
	s_waitcnt lgkmcnt(8)
	v_mfma_f32_32x32x16_bf16 v[2:17], v[158:161], v[238:241], v[2:17]
	ds_read_b64_tr_b16 v[238:239], v201 offset:0x3200
	ds_read_b64_tr_b16 v[240:241], v201 offset:0x3a00
	s_waitcnt lgkmcnt(8)
	v_mfma_f32_32x32x16_bf16 v[2:17], v[154:157], v[242:245], v[2:17]
	ds_read_b64_tr_b16 v[242:243], v201 offset:0x400
	ds_read_b64_tr_b16 v[244:245], v201 offset:0xc00
	s_waitcnt lgkmcnt(8)
	v_mfma_f32_32x32x16_bf16 v[50:65], v[146:149], v[246:249], v[50:65]
	ds_read_b64_tr_b16 v[246:247], v201 offset:0x1400
	ds_read_b64_tr_b16 v[248:249], v201 offset:0x1c00
	s_waitcnt lgkmcnt(8)
	v_mfma_f32_32x32x16_bf16 v[50:65], v[150:153], v[230:233], v[50:65]
	ds_read_b64_tr_b16 v[230:231], v201 offset:0x2400
	ds_read_b64_tr_b16 v[232:233], v201 offset:0x2c00
	s_waitcnt lgkmcnt(8)
	v_mfma_f32_32x32x16_bf16 v[50:65], v[158:161], v[234:237], v[50:65]
	ds_read_b64_tr_b16 v[234:235], v201 offset:0x3400
	ds_read_b64_tr_b16 v[236:237], v201 offset:0x3c00
	s_waitcnt lgkmcnt(8)
	v_mfma_f32_32x32x16_bf16 v[50:65], v[154:157], v[238:241], v[50:65]
	ds_read_b64_tr_b16 v[238:239], v201 offset:0x600
	ds_read_b64_tr_b16 v[240:241], v201 offset:0xe00
	s_waitcnt lgkmcnt(8)
	v_mfma_f32_32x32x16_bf16 v[34:49], v[146:149], v[242:245], v[34:49]
	ds_read_b64_tr_b16 v[242:243], v201 offset:0x1600
	ds_read_b64_tr_b16 v[244:245], v201 offset:0x1e00
	s_waitcnt lgkmcnt(8)
	v_mfma_f32_32x32x16_bf16 v[34:49], v[150:153], v[246:249], v[34:49]
	ds_read_b64_tr_b16 v[246:247], v201 offset:0x2600
	ds_read_b64_tr_b16 v[248:249], v201 offset:0x2e00
	s_waitcnt lgkmcnt(8)
	v_mfma_f32_32x32x16_bf16 v[34:49], v[158:161], v[230:233], v[34:49]
	ds_read_b64_tr_b16 v[230:231], v201 offset:0x3600
	ds_read_b64_tr_b16 v[232:233], v201 offset:0x3e00
	s_waitcnt lgkmcnt(8)
	v_mfma_f32_32x32x16_bf16 v[34:49], v[154:157], v[234:237], v[34:49]
	s_waitcnt lgkmcnt(6)
	v_mfma_f32_32x32x16_bf16 v[18:33], v[146:149], v[238:241], v[18:33]
	s_waitcnt lgkmcnt(4)
	v_mfma_f32_32x32x16_bf16 v[18:33], v[150:153], v[242:245], v[18:33]
	s_waitcnt lgkmcnt(2)
	v_mfma_f32_32x32x16_bf16 v[18:33], v[158:161], v[246:249], v[18:33]
	s_waitcnt lgkmcnt(0)
	v_mfma_f32_32x32x16_bf16 v[18:33], v[154:157], v[230:233], v[18:33]
	s_barrier
	s_waitcnt vmcnt(0)
	v_cmp_gt_f32_e32 vcc, 1.0, v227
	ds_write_b128 v210, v[162:165]
	ds_write_b128 v211, v[174:177]
	ds_write_b128 v212, v[166:169] offset:32768
	ds_write_b128 v212, v[170:173] offset:45056
	ds_write_b128 v214, v[178:181] offset:32768
	s_cbranch_vccz .LBB0_366
	s_and_saveexec_b64 s[10:11], s[4:5]
	ds_write_b32 v200, v227 offset:128
	s_or_b64 exec, exec, s[10:11]
	s_waitcnt lgkmcnt(0)
	ds_read_b128 v[146:149], v185 offset:224
	ds_read_b128 v[150:153], v185 offset:192
	ds_read_b128 v[154:157], v185 offset:160
	ds_read_b128 v[158:161], v185 offset:128
	s_waitcnt lgkmcnt(3)
	v_pk_mul_f32 v[16:17], v[16:17], v[148:149]
	s_waitcnt lgkmcnt(2)
	v_pk_mul_f32 v[12:13], v[12:13], v[152:153]
	s_waitcnt lgkmcnt(1)
	v_pk_mul_f32 v[8:9], v[8:9], v[156:157]
	s_waitcnt lgkmcnt(0)
	v_pk_mul_f32 v[4:5], v[4:5], v[160:161]
	v_pk_mul_f32 v[14:15], v[14:15], v[146:147]
	v_pk_mul_f32 v[10:11], v[10:11], v[150:151]
	v_pk_mul_f32 v[6:7], v[6:7], v[154:155]
	v_pk_mul_f32 v[2:3], v[2:3], v[158:159]
	v_pk_mul_f32 v[64:65], v[64:65], v[148:149]
	v_pk_mul_f32 v[60:61], v[60:61], v[152:153]
	v_pk_mul_f32 v[56:57], v[56:57], v[156:157]
	v_pk_mul_f32 v[52:53], v[52:53], v[160:161]
	v_pk_mul_f32 v[62:63], v[62:63], v[146:147]
	v_pk_mul_f32 v[58:59], v[58:59], v[150:151]
	v_pk_mul_f32 v[54:55], v[54:55], v[154:155]
	v_pk_mul_f32 v[50:51], v[50:51], v[158:159]
	v_pk_mul_f32 v[48:49], v[48:49], v[148:149]
	v_pk_mul_f32 v[44:45], v[44:45], v[152:153]
	v_pk_mul_f32 v[40:41], v[40:41], v[156:157]
	v_pk_mul_f32 v[36:37], v[36:37], v[160:161]
	v_pk_mul_f32 v[46:47], v[46:47], v[146:147]
	v_pk_mul_f32 v[42:43], v[42:43], v[150:151]
	v_pk_mul_f32 v[38:39], v[38:39], v[154:155]
	v_pk_mul_f32 v[34:35], v[34:35], v[158:159]
	v_pk_mul_f32 v[32:33], v[32:33], v[148:149]
	v_pk_mul_f32 v[28:29], v[28:29], v[152:153]
	v_pk_mul_f32 v[24:25], v[24:25], v[156:157]
	v_pk_mul_f32 v[20:21], v[20:21], v[160:161]
	v_pk_mul_f32 v[30:31], v[30:31], v[146:147]
	v_pk_mul_f32 v[26:27], v[26:27], v[150:151]
	v_pk_mul_f32 v[22:23], v[22:23], v[154:155]
	v_pk_mul_f32 v[18:19], v[18:19], v[158:159]
; template <bool EXP1 = true>
; __device__ __forceinline__ void finishSM(f32x16& p0, f32x16& p1, float alpha, float& l_reg, bf16x8& pa0, bf16x8& pa1, bf16x8& pa2, bf16x8& pa3) {
;   if constexpr (EXP1) {
; #pragma unroll
;   for (int r = 0; r < 16; ++r) p1[r] = __builtin_amdgcn_exp2f(p1[r]);
;   }
;   float sm_[4] = {p0[0], p0[1], p0[2], p0[3]};
; #pragma unroll
;   for (int r = 4; r < 16; ++r) sm_[r & 3] += p0[r];
; #pragma unroll
;   for (int r = 0; r < 16; ++r) sm_[r & 3] += p1[r];
;   float ps = (sm_[0] + sm_[1]) + (sm_[2] + sm_[3]);
;   { auto rr = __builtin_amdgcn_permlane32_swap(__float_as_uint(ps), __float_as_uint(ps), false, false);
;     ps = __uint_as_float(rr[0]) + __uint_as_float(rr[1]); }
;   l_reg = l_reg * alpha + ps;
;     ...
;   PK4(p0, 0, pa0); PK4(p0, 8, pa1); PK4(p1, 0, pa2); PK4(p1, 8, pa3);
; __device__ __forceinline__ void qkt12_roll(f32x16& p0, f32x16& p1, const f32x16& negm, int kb, int qa, const bf16x8* qr) {
;   const int a0 = kb ^ (0 << 5); const bf16x8 x0 = lds_rd128<0>(a0), y0 = lds_rd128<12288>(a0);
;   const int a1 = kb ^ (1 << 5); const bf16x8 x1 = lds_rd128<0>(a1), y1 = lds_rd128<12288>(a1);
;   asm volatile("s_waitcnt lgkmcnt(2)" ::: "memory"); SBAR();
;   p0 = __builtin_amdgcn_mfma_f32_32x32x16_bf16(x0, qr[0], negm, 0, 0, 0); p1 = __builtin_amdgcn_mfma_f32_32x32x16_bf16(y0, qr[0], negm, 0, 0, 0);
;   const int a2 = kb ^ (2 << 5); const bf16x8 x2 = lds_rd128<0>(a2), y2 = lds_rd128<12288>(a2);
;   asm volatile("s_waitcnt lgkmcnt(2)" ::: "memory"); SBAR();
;   p0 = __builtin_amdgcn_mfma_f32_32x32x16_bf16(x1, qr[1], p0, 0, 0, 0); p1 = __builtin_amdgcn_mfma_f32_32x32x16_bf16(y1, qr[1], p1, 0, 0, 0);
;   const int a3 = kb ^ (3 << 5); const bf16x8 x3 = lds_rd128<0>(a3), y3 = lds_rd128<12288>(a3);
;   asm volatile("s_waitcnt lgkmcnt(2)" ::: "memory"); SBAR();
;   p0 = __builtin_amdgcn_mfma_f32_32x32x16_bf16(x2, qr[2], p0, 0, 0, 0); p1 = __builtin_amdgcn_mfma_f32_32x32x16_bf16(y2, qr[2], p1, 0, 0, 0);
;   const int a4 = kb ^ (0 << 5); const bf16x8 x4 = lds_rd128<128>(a4), y4 = lds_rd128<12416>(a4);
;   asm volatile("s_waitcnt lgkmcnt(2)" ::: "memory"); SBAR();
;   p0 = __builtin_amdgcn_mfma_f32_32x32x16_bf16(x3, qr[3], p0, 0, 0, 0); p1 = __builtin_amdgcn_mfma_f32_32x32x16_bf16(y3, qr[3], p1, 0, 0, 0);
;   const int a5 = kb ^ (1 << 5); const bf16x8 x5 = lds_rd128<128>(a5), y5 = lds_rd128<12416>(a5);
.LBB0_366:
	v_exp_f32_e32 v146, v98
	v_exp_f32_e32 v153, v99
	v_exp_f32_e32 v147, v100
	v_exp_f32_e32 v152, v101
	v_exp_f32_e32 v148, v102
	v_exp_f32_e32 v151, v103
	v_exp_f32_e32 v149, v104
	v_exp_f32_e32 v150, v105
	v_exp_f32_e32 v103, v106
	v_exp_f32_e32 v105, v107
	v_exp_f32_e32 v101, v108
	v_exp_f32_e32 v104, v109
	v_exp_f32_e32 v99, v110
	v_exp_f32_e32 v102, v111
	v_exp_f32_e32 v98, v112
	v_exp_f32_e32 v100, v113
	v_xor_b32_e32 v106, 0x80000000, v226
	v_exp_f32_e32 v82, v82
	v_exp_f32_e32 v83, v83
	v_exp_f32_e32 v84, v84
	v_exp_f32_e32 v85, v85
	v_cndmask_b32_e64 v229, v106, v229, s[6:7]
	v_exp_f32_e32 v86, v86
	v_exp_f32_e32 v87, v87
	v_exp_f32_e32 v88, v88
	v_exp_f32_e32 v89, v89
	v_add_f32_e32 v106, v148, v146
	v_add_f32_e32 v107, v151, v153
	v_add_f32_e32 v108, v149, v147
	v_add_f32_e32 v109, v150, v152
	v_exp_f32_e32 v90, v90
	v_exp_f32_e32 v91, v91
	v_exp_f32_e32 v92, v92
	v_exp_f32_e32 v93, v93
	v_add_f32_e32 v106, v103, v106
	v_add_f32_e32 v107, v105, v107
	v_add_f32_e32 v108, v101, v108
	v_add_f32_e32 v109, v104, v109
	v_exp_f32_e32 v94, v94
	v_exp_f32_e32 v95, v95
	v_exp_f32_e32 v96, v96
	v_exp_f32_e32 v97, v97
	v_add_f32_e32 v106, v99, v106
	v_add_f32_e32 v107, v102, v107
	v_add_f32_e32 v108, v98, v108
	v_add_f32_e32 v109, v100, v109
	v_add_f32_e32 v106, v82, v106
	v_add_f32_e32 v107, v107, v83
	v_add_f32_e32 v108, v108, v84
	v_add_f32_e32 v109, v109, v85
	v_add_f32_e32 v106, v86, v106
	v_add_f32_e32 v107, v87, v107
	v_add_f32_e32 v108, v88, v108
	v_add_f32_e32 v109, v89, v109
	v_add_f32_e32 v106, v90, v106
	v_add_f32_e32 v107, v91, v107
	v_add_f32_e32 v108, v92, v108
	v_add_f32_e32 v109, v93, v109
	v_add_f32_e32 v106, v94, v106
	v_add_f32_e32 v107, v95, v107
	v_add_f32_e32 v108, v96, v108
	v_add_f32_e32 v109, v97, v109
	v_add_f32_e32 v106, v106, v107
	v_add_f32_e32 v107, v108, v109
	v_add_f32_e32 v230, v106, v107
	s_waitcnt lgkmcnt(0)
	s_barrier
	v_mov_b32_e32 v231, v230
	v_cvt_pk_bf16_f32 v146, v146, v153
	v_cvt_pk_bf16_f32 v147, v147, v152
	v_cvt_pk_bf16_f32 v148, v148, v151
	v_cvt_pk_bf16_f32 v149, v149, v150
	v_cvt_pk_bf16_f32 v150, v103, v105
	v_cvt_pk_bf16_f32 v151, v101, v104
	v_cvt_pk_bf16_f32 v152, v99, v102
	v_cvt_pk_bf16_f32 v153, v98, v100
	v_cvt_pk_bf16_f32 v158, v82, v83
	v_cvt_pk_bf16_f32 v159, v84, v85
	v_cvt_pk_bf16_f32 v160, v86, v87
	v_cvt_pk_bf16_f32 v161, v88, v89
	v_cvt_pk_bf16_f32 v154, v90, v91
	v_cvt_pk_bf16_f32 v155, v92, v93
	v_cvt_pk_bf16_f32 v156, v94, v95
	v_cvt_pk_bf16_f32 v157, v96, v97
	s_nop 1
	v_permlane32_swap_b32_e32 v230, v231
	v_permlane32_swap_b32_e32 v146, v148
	v_permlane32_swap_b32_e32 v147, v149
	v_permlane32_swap_b32_e32 v150, v152
	v_permlane32_swap_b32_e32 v151, v153
	v_permlane32_swap_b32_e32 v158, v160
	v_permlane32_swap_b32_e32 v159, v161
	v_permlane32_swap_b32_e32 v154, v156
	v_permlane32_swap_b32_e32 v155, v157
	v_cmp_neq_f32_e64 s[6:7], v229, -v228
	s_cmp_eq_u64 s[6:7], 0
	s_cselect_b64 s[6:7], -1, 0
	v_cndmask_b32_e64 v97, -v228, v81, s[6:7]
	v_cndmask_b32_e64 v96, -v228, v80, s[6:7]
	v_cndmask_b32_e64 v95, -v228, v79, s[6:7]
	v_cndmask_b32_e64 v94, -v228, v78, s[6:7]
	v_cndmask_b32_e64 v93, -v228, v77, s[6:7]
	v_cndmask_b32_e64 v92, -v228, v76, s[6:7]
	v_cndmask_b32_e64 v91, -v228, v75, s[6:7]
	v_cndmask_b32_e64 v90, -v228, v74, s[6:7]
	v_cndmask_b32_e64 v89, -v228, v73, s[6:7]
	v_cndmask_b32_e64 v88, -v228, v72, s[6:7]
	v_cndmask_b32_e64 v87, -v228, v71, s[6:7]
	v_cndmask_b32_e64 v86, -v228, v70, s[6:7]
	v_cndmask_b32_e64 v85, -v228, v69, s[6:7]
	v_cndmask_b32_e64 v84, -v228, v68, s[6:7]
	v_cndmask_b32_e64 v83, -v228, v67, s[6:7]
	v_cndmask_b32_e64 v82, -v228, v66, s[6:7]
	ds_read_b128 v[66:69], v209 offset:0
	ds_read_b128 v[162:165], v209 offset:0x3000
	ds_read_b128 v[166:169], v215 offset:0
	ds_read_b128 v[170:173], v215 offset:0x3000
	s_waitcnt lgkmcnt(2)
	s_nop 1
	v_mfma_f32_32x32x16_bf16 v[98:113], v[66:69], v[142:145], v[82:97]
	v_mfma_f32_32x32x16_bf16 v[66:81], v[162:165], v[142:145], v[82:97]
	ds_read_b128 v[162:165], v216 offset:0
	ds_read_b128 v[174:177], v216 offset:0x3000
	s_waitcnt lgkmcnt(2)
	v_mfma_f32_32x32x16_bf16 v[98:113], v[166:169], v[138:141], v[98:113]
	ds_read_b128 v[166:169], v217 offset:0
	v_mfma_f32_32x32x16_bf16 v[66:81], v[170:173], v[138:141], v[66:81]
	ds_read_b128 v[170:173], v217 offset:0x3000
	s_waitcnt lgkmcnt(2)
	v_mfma_f32_32x32x16_bf16 v[98:113], v[162:165], v[134:137], v[98:113]
	ds_read_b128 v[162:165], v209 offset:0x80
	v_mfma_f32_32x32x16_bf16 v[66:81], v[174:177], v[134:137], v[66:81]
	ds_read_b128 v[174:177], v209 offset:0x3080
	s_waitcnt lgkmcnt(2)
	v_mfma_f32_32x32x16_bf16 v[98:113], v[166:169], v[130:133], v[98:113]
	ds_read_b128 v[166:169], v215 offset:0x80
	v_mfma_f32_32x32x16_bf16 v[66:81], v[170:173], v[130:133], v[66:81]
	ds_read_b128 v[170:173], v215 offset:0x3080
	s_waitcnt lgkmcnt(2)
	v_mfma_f32_32x32x16_bf16 v[98:113], v[162:165], v[126:129], v[98:113]
	ds_read_b128 v[162:165], v216 offset:0x80
	v_mfma_f32_32x32x16_bf16 v[66:81], v[174:177], v[126:129], v[66:81]
	ds_read_b128 v[174:177], v216 offset:0x3080
	s_waitcnt lgkmcnt(2)
	v_mfma_f32_32x32x16_bf16 v[98:113], v[166:169], v[122:125], v[98:113]
	ds_read_b128 v[166:169], v217 offset:0x80
	v_mfma_f32_32x32x16_bf16 v[66:81], v[170:173], v[122:125], v[66:81]
	ds_read_b128 v[170:173], v217 offset:0x3080
	s_waitcnt lgkmcnt(2)
	v_mfma_f32_32x32x16_bf16 v[98:113], v[162:165], v[118:121], v[98:113]
	ds_read_b128 v[162:165], v209 offset:0x100
	v_mfma_f32_32x32x16_bf16 v[66:81], v[174:177], v[118:121], v[66:81]
	ds_read_b128 v[174:177], v209 offset:0x3100
	ds_read_b128 v[178:181], v199 offset:0
	s_waitcnt lgkmcnt(3)
; __device__ __forceinline__ void qkt12_roll(f32x16& p0, f32x16& p1, const f32x16& negm, int kb, int qa, const bf16x8* qr) {
;   const int a0 = kb ^ (0 << 5); const bf16x8 x0 = lds_rd128<0>(a0), y0 = lds_rd128<12288>(a0);
;   const int a1 = kb ^ (1 << 5); const bf16x8 x1 = lds_rd128<0>(a1), y1 = lds_rd128<12288>(a1);
;   asm volatile("s_waitcnt lgkmcnt(2)" ::: "memory"); SBAR();
;   p0 = __builtin_amdgcn_mfma_f32_32x32x16_bf16(x0, qr[0], negm, 0, 0, 0); p1 = __builtin_amdgcn_mfma_f32_32x32x16_bf16(y0, qr[0], negm, 0, 0, 0);
;   const int a2 = kb ^ (2 << 5); const bf16x8 x2 = lds_rd128<0>(a2), y2 = lds_rd128<12288>(a2);
;   asm volatile("s_waitcnt lgkmcnt(2)" ::: "memory"); SBAR();
;   p0 = __builtin_amdgcn_mfma_f32_32x32x16_bf16(x1, qr[1], p0, 0, 0, 0); p1 = __builtin_amdgcn_mfma_f32_32x32x16_bf16(y1, qr[1], p1, 0, 0, 0);
;   const int a3 = kb ^ (3 << 5); const bf16x8 x3 = lds_rd128<0>(a3), y3 = lds_rd128<12288>(a3);
;   asm volatile("s_waitcnt lgkmcnt(2)" ::: "memory"); SBAR();
;   p0 = __builtin_amdgcn_mfma_f32_32x32x16_bf16(x2, qr[2], p0, 0, 0, 0); p1 = __builtin_amdgcn_mfma_f32_32x32x16_bf16(y2, qr[2], p1, 0, 0, 0);
;   const int a4 = kb ^ (0 << 5); const bf16x8 x4 = lds_rd128<128>(a4), y4 = lds_rd128<12416>(a4);
;   asm volatile("s_waitcnt lgkmcnt(2)" ::: "memory"); SBAR();
;   p0 = __builtin_amdgcn_mfma_f32_32x32x16_bf16(x3, qr[3], p0, 0, 0, 0); p1 = __builtin_amdgcn_mfma_f32_32x32x16_bf16(y3, qr[3], p1, 0, 0, 0);
;   const int a5 = kb ^ (1 << 5); const bf16x8 x5 = lds_rd128<128>(a5), y5 = lds_rd128<12416>(a5);
;   asm volatile("s_waitcnt lgkmcnt(2)" ::: "memory"); SBAR();
;   p0 = __builtin_amdgcn_mfma_f32_32x32x16_bf16(x4, qr[4], p0, 0, 0, 0); p1 = __builtin_amdgcn_mfma_f32_32x32x16_bf16(y4, qr[4], p1, 0, 0, 0);
;   const int a6 = kb ^ (2 << 5); const bf16x8 x6 = lds_rd128<128>(a6), y6 = lds_rd128<12416>(a6);
;   asm volatile("s_waitcnt lgkmcnt(2)" ::: "memory"); SBAR();
;   p0 = __builtin_amdgcn_mfma_f32_32x32x16_bf16(x5, qr[5], p0, 0, 0, 0); p1 = __builtin_amdgcn_mfma_f32_32x32x16_bf16(y5, qr[5], p1, 0, 0, 0);
;   const int a7 = kb ^ (3 << 5); const bf16x8 x7 = lds_rd128<128>(a7), y7 = lds_rd128<12416>(a7);
;   asm volatile("s_waitcnt lgkmcnt(2)" ::: "memory"); SBAR();
;   p0 = __builtin_amdgcn_mfma_f32_32x32x16_bf16(x6, qr[6], p0, 0, 0, 0); p1 = __builtin_amdgcn_mfma_f32_32x32x16_bf16(y6, qr[6], p1, 0, 0, 0);
	v_mfma_f32_32x32x16_bf16 v[98:113], v[166:169], v[114:117], v[98:113]
	ds_read_b128 v[166:169], v215 offset:0x100
	v_mfma_f32_32x32x16_bf16 v[66:81], v[170:173], v[114:117], v[66:81]
	ds_read_b128 v[170:173], v215 offset:0x3100
	ds_read_b128 v[232:235], v199 offset:0x400
	s_waitcnt lgkmcnt(3)
	v_mfma_f32_32x32x16_bf16 v[98:113], v[162:165], v[178:181], v[98:113]
	ds_read_b128 v[162:165], v216 offset:0x100
	v_mfma_f32_32x32x16_bf16 v[66:81], v[174:177], v[178:181], v[66:81]
	ds_read_b128 v[174:177], v216 offset:0x3100
	ds_read_b128 v[178:181], v199 offset:0x800
	s_waitcnt lgkmcnt(3)
	v_mfma_f32_32x32x16_bf16 v[98:113], v[166:169], v[232:235], v[98:113]
	ds_read_b128 v[166:169], v217 offset:0x100
	v_mfma_f32_32x32x16_bf16 v[66:81], v[170:173], v[232:235], v[66:81]
	ds_read_b128 v[170:173], v217 offset:0x3100
	ds_read_b128 v[232:235], v199 offset:0xc00
	s_waitcnt lgkmcnt(3)
	v_mfma_f32_32x32x16_bf16 v[98:113], v[162:165], v[178:181], v[98:113]
	s_waitcnt lgkmcnt(0)
	v_mfma_f32_32x32x16_bf16 v[66:81], v[174:177], v[178:181], v[66:81]
	v_mfma_f32_32x32x16_bf16 v[98:113], v[166:169], v[232:235], v[98:113]
	v_mfma_f32_32x32x16_bf16 v[66:81], v[170:173], v[232:235], v[66:81]
	s_nop 10
	v_max_f32_e32 v162, v98, v102
	v_max_f32_e32 v163, v99, v103
	v_max_f32_e32 v164, v101, v105
	v_max3_f32 v165, v100, v104, v108
	v_max3_f32 v164, v164, v109, v113
	v_max3_f32 v162, v162, v106, v110
	v_max3_f32 v163, v163, v107, v111
	v_max3_f32 v165, v165, v112, v68
	v_max3_f32 v164, v164, v69, v73
	v_max3_f32 v162, v162, v66, v70
	v_max3_f32 v163, v163, v67, v71
	v_max3_f32 v165, v165, v72, v76
	v_max3_f32 v164, v164, v77, v81
	v_max3_f32 v162, v162, v74, v78
	v_max3_f32 v163, v163, v75, v79
	v_max3_f32 v164, v165, v80, v164
	v_max3_f32 v162, v162, v163, v164
	v_mov_b32_e32 v163, v162
	s_nop 1
	v_permlane32_swap_b32_e32 v162, v163
	v_max_f32_e32 v162, v162, v163
	v_cmp_ge_f32_e32 vcc, s48, v162
	s_cmp_eq_u64 vcc, exec
	v_mov_b32_e32 v223, 1.0
	s_cbranch_scc0 .LBB0_375
	v_mov_b32_e32 v226, v228
; __device__ __forceinline__ void pv_d0(f32x16* o, int vb, bf16x8 pa0, bf16x8 pa1, bf16x8 pa2, bf16x8 pa3) {
;     ...
;   const s16x4 l0 = tr_read<v_rd_off(0, 0, 0)>(vb), h0 = tr_read<v_rd_off(0, 0, 1)>(vb);
;   const s16x4 l1 = tr_read<v_rd_off(0, 1, 0)>(vb), h1 = tr_read<v_rd_off(0, 1, 1)>(vb);
;   const s16x4 l2 = tr_read<v_rd_off(0, 2, 0)>(vb), h2 = tr_read<v_rd_off(0, 2, 1)>(vb);
;   const s16x4 l3 = tr_read<v_rd_off(0, 3, 0)>(vb), h3 = tr_read<v_rd_off(0, 3, 1)>(vb);
;   const s16x4 l4 = tr_read<v_rd_off(1, 0, 0)>(vb), h4 = tr_read<v_rd_off(1, 0, 1)>(vb);
;   asm volatile("s_waitcnt lgkmcnt(8)" ::: "memory"); SBAR();
;   o[0] = __builtin_amdgcn_mfma_f32_32x32x16_bf16(pa0, PK(l0, h0), o[0], 0, 0, 0);
;   const s16x4 l5 = tr_read<v_rd_off(1, 1, 0)>(vb), h5 = tr_read<v_rd_off(1, 1, 1)>(vb);
;   asm volatile("s_waitcnt lgkmcnt(8)" ::: "memory"); SBAR();
;   o[0] = __builtin_amdgcn_mfma_f32_32x32x16_bf16(pa1, PK(l1, h1), o[0], 0, 0, 0);
;   const s16x4 l6 = tr_read<v_rd_off(1, 2, 0)>(vb), h6 = tr_read<v_rd_off(1, 2, 1)>(vb);
;   asm volatile("s_waitcnt lgkmcnt(8)" ::: "memory"); SBAR();
;   o[0] = __builtin_amdgcn_mfma_f32_32x32x16_bf16(pa2, PK(l2, h2), o[0], 0, 0, 0);
;   const s16x4 l7 = tr_read<v_rd_off(1, 3, 0)>(vb), h7 = tr_read<v_rd_off(1, 3, 1)>(vb);
;   asm volatile("s_waitcnt lgkmcnt(8)" ::: "memory"); SBAR();
;   o[0] = __builtin_amdgcn_mfma_f32_32x32x16_bf16(pa3, PK(l3, h3), o[0], 0, 0, 0);
;   const s16x4 l8 = tr_read<v_rd_off(2, 0, 0)>(vb), h8 = tr_read<v_rd_off(2, 0, 1)>(vb);
;   asm volatile("s_waitcnt lgkmcnt(8)" ::: "memory"); SBAR();
;   o[1] = __builtin_amdgcn_mfma_f32_32x32x16_bf16(pa0, PK(l4, h4), o[1], 0, 0, 0);
;   const s16x4 l9 = tr_read<v_rd_off(2, 1, 0)>(vb), h9 = tr_read<v_rd_off(2, 1, 1)>(vb);
;   asm volatile("s_waitcnt lgkmcnt(8)" ::: "memory"); SBAR();
;   o[1] = __builtin_amdgcn_mfma_f32_32x32x16_bf16(pa1, PK(l5, h5), o[1], 0, 0, 0);
;   const s16x4 l10 = tr_read<v_rd_off(2, 2, 0)>(vb), h10 = tr_read<v_rd_off(2, 2, 1)>(vb);
;   asm volatile("s_waitcnt lgkmcnt(8)" ::: "memory"); SBAR();
;   o[1] = __builtin_amdgcn_mfma_f32_32x32x16_bf16(pa2, PK(l6, h6), o[1], 0, 0, 0);
;   const s16x4 l11 = tr_read<v_rd_off(2, 3, 0)>(vb), h11 = tr_read<v_rd_off(2, 3, 1)>(vb);
;   asm volatile("s_waitcnt lgkmcnt(8)" ::: "memory"); SBAR();
;   o[1] = __builtin_amdgcn_mfma_f32_32x32x16_bf16(pa3, PK(l7, h7), o[1], 0, 0, 0);
.LBB0_368:
	v_add_co_u32_e32 v166, vcc, s69, v190
	s_nop 1
	v_addc_co_u32_e32 v167, vcc, 0, v191, vcc
	v_add_co_u32_e32 v170, vcc, s74, v190
	s_nop 1
	v_addc_co_u32_e32 v171, vcc, 0, v191, vcc
	global_load_dwordx4 v[162:165], v[166:167], off offset:256
	s_nop 0
	global_load_dwordx4 v[166:169], v[166:167], off
	s_nop 0
	global_load_dwordx4 v[174:177], v[170:171], off offset:256
	s_nop 0
	global_load_dwordx4 v[170:173], v[170:171], off
	v_add_co_u32_e32 v178, vcc, s75, v196
	s_nop 1
	v_addc_co_u32_e32 v179, vcc, 0, v197, vcc
	global_load_dwordx4 v[178:181], v[178:179], off
	ds_read_b64_tr_b16 v[232:233], v208 offset:0
	ds_read_b64_tr_b16 v[234:235], v208 offset:0x800
	ds_read_b64_tr_b16 v[236:237], v208 offset:0x1000
	ds_read_b64_tr_b16 v[238:239], v208 offset:0x1800
	ds_read_b64_tr_b16 v[240:241], v208 offset:0x2000
	ds_read_b64_tr_b16 v[242:243], v208 offset:0x2800
	ds_read_b64_tr_b16 v[244:245], v208 offset:0x3000
	ds_read_b64_tr_b16 v[246:247], v208 offset:0x3800
	ds_read_b64_tr_b16 v[248:249], v208 offset:0x200
	ds_read_b64_tr_b16 v[250:251], v208 offset:0xa00
	s_waitcnt lgkmcnt(8)
	s_nop 0
	v_mfma_f32_32x32x16_bf16 v[2:17], v[146:149], v[232:235], v[2:17]
	ds_read_b64_tr_b16 v[232:233], v208 offset:0x1200
	ds_read_b64_tr_b16 v[234:235], v208 offset:0x1a00
	s_waitcnt lgkmcnt(8)
	v_mfma_f32_32x32x16_bf16 v[2:17], v[150:153], v[236:239], v[2:17]
	ds_read_b64_tr_b16 v[236:237], v208 offset:0x2200
	ds_read_b64_tr_b16 v[238:239], v208 offset:0x2a00
	s_waitcnt lgkmcnt(8)
	v_mfma_f32_32x32x16_bf16 v[2:17], v[158:161], v[240:243], v[2:17]
	ds_read_b64_tr_b16 v[240:241], v208 offset:0x3200
	ds_read_b64_tr_b16 v[242:243], v208 offset:0x3a00
	s_waitcnt lgkmcnt(8)
	v_mfma_f32_32x32x16_bf16 v[2:17], v[154:157], v[244:247], v[2:17]
	ds_read_b64_tr_b16 v[244:245], v208 offset:0x400
	ds_read_b64_tr_b16 v[246:247], v208 offset:0xc00
	s_waitcnt lgkmcnt(8)
	v_mfma_f32_32x32x16_bf16 v[50:65], v[146:149], v[248:251], v[50:65]
	ds_read_b64_tr_b16 v[248:249], v208 offset:0x1400
	ds_read_b64_tr_b16 v[250:251], v208 offset:0x1c00
	s_waitcnt lgkmcnt(8)
	v_mfma_f32_32x32x16_bf16 v[50:65], v[150:153], v[232:235], v[50:65]
	ds_read_b64_tr_b16 v[232:233], v208 offset:0x2400
	ds_read_b64_tr_b16 v[234:235], v208 offset:0x2c00
	s_waitcnt lgkmcnt(8)
	v_mfma_f32_32x32x16_bf16 v[50:65], v[158:161], v[236:239], v[50:65]
	ds_read_b64_tr_b16 v[236:237], v208 offset:0x3400
	ds_read_b64_tr_b16 v[238:239], v208 offset:0x3c00
	s_waitcnt lgkmcnt(8)
	v_mfma_f32_32x32x16_bf16 v[50:65], v[154:157], v[240:243], v[50:65]
	ds_read_b64_tr_b16 v[240:241], v208 offset:0x600
	ds_read_b64_tr_b16 v[242:243], v208 offset:0xe00
	s_waitcnt lgkmcnt(8)
	v_mfma_f32_32x32x16_bf16 v[34:49], v[146:149], v[244:247], v[34:49]
	ds_read_b64_tr_b16 v[244:245], v208 offset:0x1600
	ds_read_b64_tr_b16 v[246:247], v208 offset:0x1e00
	s_waitcnt lgkmcnt(8)
	v_mfma_f32_32x32x16_bf16 v[34:49], v[150:153], v[248:251], v[34:49]
	ds_read_b64_tr_b16 v[248:249], v208 offset:0x2600
	ds_read_b64_tr_b16 v[250:251], v208 offset:0x2e00
	s_waitcnt lgkmcnt(8)
	v_mfma_f32_32x32x16_bf16 v[34:49], v[158:161], v[232:235], v[34:49]
	ds_read_b64_tr_b16 v[232:233], v208 offset:0x3600
	ds_read_b64_tr_b16 v[234:235], v208 offset:0x3e00
	s_waitcnt lgkmcnt(8)
	v_mfma_f32_32x32x16_bf16 v[34:49], v[154:157], v[236:239], v[34:49]
	s_waitcnt lgkmcnt(6)
	v_mfma_f32_32x32x16_bf16 v[18:33], v[146:149], v[240:243], v[18:33]
	s_waitcnt lgkmcnt(4)
	v_mfma_f32_32x32x16_bf16 v[18:33], v[150:153], v[244:247], v[18:33]
	s_waitcnt lgkmcnt(2)
	v_mfma_f32_32x32x16_bf16 v[18:33], v[158:161], v[248:251], v[18:33]
	s_waitcnt lgkmcnt(0)
	v_mfma_f32_32x32x16_bf16 v[18:33], v[154:157], v[232:235], v[18:33]
	s_barrier
	s_waitcnt vmcnt(0)
	v_cmp_gt_f32_e32 vcc, 1.0, v223
	ds_write_b128 v210, v[162:165] offset:16384
	ds_write_b128 v211, v[174:177] offset:16384
	ds_write_b128 v212, v[166:169] offset:57344
	ds_write_b128 v213, v[170:173] offset:57344
	ds_write_b128 v214, v[178:181] offset:57344
	s_cbranch_vccz .LBB0_372
	s_and_saveexec_b64 s[10:11], s[4:5]
	ds_write_b32 v200, v223 offset:128
	s_or_b64 exec, exec, s[10:11]
	s_waitcnt lgkmcnt(0)
	ds_read_b128 v[146:149], v185 offset:224
	ds_read_b128 v[150:153], v185 offset:192
	ds_read_b128 v[154:157], v185 offset:160
	ds_read_b128 v[158:161], v185 offset:128
	s_waitcnt lgkmcnt(3)
	v_pk_mul_f32 v[16:17], v[16:17], v[148:149]
	s_waitcnt lgkmcnt(2)
	v_pk_mul_f32 v[12:13], v[12:13], v[152:153]
	s_waitcnt lgkmcnt(1)
	v_pk_mul_f32 v[8:9], v[8:9], v[156:157]
	s_waitcnt lgkmcnt(0)
	v_pk_mul_f32 v[4:5], v[4:5], v[160:161]
	v_pk_mul_f32 v[14:15], v[14:15], v[146:147]
	v_pk_mul_f32 v[10:11], v[10:11], v[150:151]
	v_pk_mul_f32 v[6:7], v[6:7], v[154:155]
	v_pk_mul_f32 v[2:3], v[2:3], v[158:159]
	v_pk_mul_f32 v[64:65], v[64:65], v[148:149]
	v_pk_mul_f32 v[60:61], v[60:61], v[152:153]
	v_pk_mul_f32 v[56:57], v[56:57], v[156:157]
	v_pk_mul_f32 v[52:53], v[52:53], v[160:161]
	v_pk_mul_f32 v[62:63], v[62:63], v[146:147]
	v_pk_mul_f32 v[58:59], v[58:59], v[150:151]
	v_pk_mul_f32 v[54:55], v[54:55], v[154:155]
	v_pk_mul_f32 v[50:51], v[50:51], v[158:159]
	v_pk_mul_f32 v[48:49], v[48:49], v[148:149]
	v_pk_mul_f32 v[44:45], v[44:45], v[152:153]
	v_pk_mul_f32 v[40:41], v[40:41], v[156:157]
	v_pk_mul_f32 v[36:37], v[36:37], v[160:161]
	v_pk_mul_f32 v[46:47], v[46:47], v[146:147]
	v_pk_mul_f32 v[42:43], v[42:43], v[150:151]
	v_pk_mul_f32 v[38:39], v[38:39], v[154:155]
	v_pk_mul_f32 v[34:35], v[34:35], v[158:159]
	v_pk_mul_f32 v[32:33], v[32:33], v[148:149]
	v_pk_mul_f32 v[28:29], v[28:29], v[152:153]
	v_pk_mul_f32 v[24:25], v[24:25], v[156:157]
	v_pk_mul_f32 v[20:21], v[20:21], v[160:161]
	v_pk_mul_f32 v[30:31], v[30:31], v[146:147]
	v_pk_mul_f32 v[26:27], v[26:27], v[150:151]
	v_pk_mul_f32 v[22:23], v[22:23], v[154:155]
	v_pk_mul_f32 v[18:19], v[18:19], v[158:159]

; __device__ __forceinline__ void qkt12_roll(f32x16& p0, f32x16& p1, const f32x16& negm, int kb, int qa, const bf16x8* qr) {
;   const int a0 = kb ^ (0 << 5); const bf16x8 x0 = lds_rd128<0>(a0), y0 = lds_rd128<12288>(a0);
;   const int a1 = kb ^ (1 << 5); const bf16x8 x1 = lds_rd128<0>(a1), y1 = lds_rd128<12288>(a1);
;   asm volatile("s_waitcnt lgkmcnt(2)" ::: "memory"); SBAR();
;   p0 = __builtin_amdgcn_mfma_f32_32x32x16_bf16(x0, qr[0], negm, 0, 0, 0); p1 = __builtin_amdgcn_mfma_f32_32x32x16_bf16(y0, qr[0], negm, 0, 0, 0);
;   const int a2 = kb ^ (2 << 5); const bf16x8 x2 = lds_rd128<0>(a2), y2 = lds_rd128<12288>(a2);
;   asm volatile("s_waitcnt lgkmcnt(2)" ::: "memory"); SBAR();
;   p0 = __builtin_amdgcn_mfma_f32_32x32x16_bf16(x1, qr[1], p0, 0, 0, 0); p1 = __builtin_amdgcn_mfma_f32_32x32x16_bf16(y1, qr[1], p1, 0, 0, 0);
;   const int a3 = kb ^ (3 << 5); const bf16x8 x3 = lds_rd128<0>(a3), y3 = lds_rd128<12288>(a3);
;   asm volatile("s_waitcnt lgkmcnt(2)" ::: "memory"); SBAR();
;   p0 = __builtin_amdgcn_mfma_f32_32x32x16_bf16(x2, qr[2], p0, 0, 0, 0); p1 = __builtin_amdgcn_mfma_f32_32x32x16_bf16(y2, qr[2], p1, 0, 0, 0);
;   const int a4 = kb ^ (0 << 5); const bf16x8 x4 = lds_rd128<128>(a4), y4 = lds_rd128<12416>(a4);
;   asm volatile("s_waitcnt lgkmcnt(2)" ::: "memory"); SBAR();
;   p0 = __builtin_amdgcn_mfma_f32_32x32x16_bf16(x3, qr[3], p0, 0, 0, 0); p1 = __builtin_amdgcn_mfma_f32_32x32x16_bf16(y3, qr[3], p1, 0, 0, 0);
;   const int a5 = kb ^ (1 << 5); const bf16x8 x5 = lds_rd128<128>(a5), y5 = lds_rd128<12416>(a5);
;   asm volatile("s_waitcnt lgkmcnt(2)" ::: "memory"); SBAR();
;   p0 = __builtin_amdgcn_mfma_f32_32x32x16_bf16(x4, qr[4], p0, 0, 0, 0); p1 = __builtin_amdgcn_mfma_f32_32x32x16_bf16(y4, qr[4], p1, 0, 0, 0);
;   const int a6 = kb ^ (2 << 5); const bf16x8 x6 = lds_rd128<128>(a6), y6 = lds_rd128<12416>(a6);
;   asm volatile("s_waitcnt lgkmcnt(2)" ::: "memory"); SBAR();
;   p0 = __builtin_amdgcn_mfma_f32_32x32x16_bf16(x5, qr[5], p0, 0, 0, 0); p1 = __builtin_amdgcn_mfma_f32_32x32x16_bf16(y5, qr[5], p1, 0, 0, 0);
;   const int a7 = kb ^ (3 << 5); const bf16x8 x7 = lds_rd128<128>(a7), y7 = lds_rd128<12416>(a7);
;   asm volatile("s_waitcnt lgkmcnt(2)" ::: "memory"); SBAR();
;   p0 = __builtin_amdgcn_mfma_f32_32x32x16_bf16(x6, qr[6], p0, 0, 0, 0); p1 = __builtin_amdgcn_mfma_f32_32x32x16_bf16(y6, qr[6], p1, 0, 0, 0);
.LBB0_386:
	v_cmp_neq_f32_e64 s[6:7], v228, -v225
	s_cmp_eq_u64 s[6:7], 0
	s_cselect_b64 s[6:7], -1, 0
	v_cndmask_b32_e64 v113, -v225, v113, s[6:7]
	v_cndmask_b32_e64 v112, -v225, v112, s[6:7]
	v_cndmask_b32_e64 v111, -v225, v111, s[6:7]
	v_cndmask_b32_e64 v110, -v225, v110, s[6:7]
	v_cndmask_b32_e64 v109, -v225, v109, s[6:7]
	v_cndmask_b32_e64 v108, -v225, v108, s[6:7]
	v_cndmask_b32_e64 v107, -v225, v107, s[6:7]
	v_cndmask_b32_e64 v106, -v225, v106, s[6:7]
	v_cndmask_b32_e64 v105, -v225, v105, s[6:7]
	v_cndmask_b32_e64 v104, -v225, v104, s[6:7]
	v_cndmask_b32_e64 v103, -v225, v103, s[6:7]
	v_cndmask_b32_e64 v102, -v225, v102, s[6:7]
	v_cndmask_b32_e64 v101, -v225, v101, s[6:7]
	v_cndmask_b32_e64 v100, -v225, v100, s[6:7]
	v_cndmask_b32_e64 v99, -v225, v99, s[6:7]
	v_cndmask_b32_e64 v98, -v225, v98, s[6:7]
	ds_read_b128 v[82:85], v221 offset:0
	ds_read_b128 v[230:233], v221 offset:0x3000
	ds_read_b128 v[234:237], v220 offset:0
	ds_read_b128 v[238:241], v220 offset:0x3000
	s_waitcnt lgkmcnt(2)
	s_nop 1
	v_mfma_f32_32x32x16_bf16 v[114:129], v[82:85], v[158:161], v[98:113]
	v_mfma_f32_32x32x16_bf16 v[82:97], v[230:233], v[158:161], v[98:113]
	ds_read_b128 v[230:233], v219 offset:0
	ds_read_b128 v[242:245], v219 offset:0x3000
	s_waitcnt lgkmcnt(2)
	v_mfma_f32_32x32x16_bf16 v[114:129], v[234:237], v[154:157], v[114:129]
	ds_read_b128 v[234:237], v218 offset:0
	v_mfma_f32_32x32x16_bf16 v[82:97], v[238:241], v[154:157], v[82:97]
	ds_read_b128 v[238:241], v218 offset:0x3000
	s_waitcnt lgkmcnt(2)
	v_mfma_f32_32x32x16_bf16 v[114:129], v[230:233], v[150:153], v[114:129]
	ds_read_b128 v[230:233], v221 offset:0x80
	v_mfma_f32_32x32x16_bf16 v[82:97], v[242:245], v[150:153], v[82:97]
	ds_read_b128 v[242:245], v221 offset:0x3080
	s_waitcnt lgkmcnt(2)
	v_mfma_f32_32x32x16_bf16 v[114:129], v[234:237], v[146:149], v[114:129]
	ds_read_b128 v[234:237], v220 offset:0x80
	v_mfma_f32_32x32x16_bf16 v[82:97], v[238:241], v[146:149], v[82:97]
	ds_read_b128 v[238:241], v220 offset:0x3080
	s_waitcnt lgkmcnt(2)
	v_mfma_f32_32x32x16_bf16 v[114:129], v[230:233], v[142:145], v[114:129]
	ds_read_b128 v[230:233], v219 offset:0x80
	v_mfma_f32_32x32x16_bf16 v[82:97], v[242:245], v[142:145], v[82:97]
	ds_read_b128 v[242:245], v219 offset:0x3080
	s_waitcnt lgkmcnt(2)
	v_mfma_f32_32x32x16_bf16 v[114:129], v[234:237], v[138:141], v[114:129]
	ds_read_b128 v[234:237], v218 offset:0x80
	v_mfma_f32_32x32x16_bf16 v[82:97], v[238:241], v[138:141], v[82:97]
	ds_read_b128 v[238:241], v218 offset:0x3080
	s_waitcnt lgkmcnt(2)
	v_mfma_f32_32x32x16_bf16 v[114:129], v[230:233], v[134:137], v[114:129]
	ds_read_b128 v[230:233], v221 offset:0x100
	v_mfma_f32_32x32x16_bf16 v[82:97], v[242:245], v[134:137], v[82:97]
	ds_read_b128 v[242:245], v221 offset:0x3100
	ds_read_b128 v[246:249], v199 offset:0
	s_waitcnt lgkmcnt(3)
	v_mfma_f32_32x32x16_bf16 v[114:129], v[234:237], v[130:133], v[114:129]
	ds_read_b128 v[234:237], v220 offset:0x100
	v_mfma_f32_32x32x16_bf16 v[82:97], v[238:241], v[130:133], v[82:97]
	ds_read_b128 v[238:241], v220 offset:0x3100
	ds_read_b128 v[250:253], v199 offset:0x400
	s_waitcnt lgkmcnt(3)
	v_mfma_f32_32x32x16_bf16 v[114:129], v[230:233], v[246:249], v[114:129]
	ds_read_b128 v[230:233], v219 offset:0x100
	v_mfma_f32_32x32x16_bf16 v[82:97], v[242:245], v[246:249], v[82:97]
	ds_read_b128 v[242:245], v219 offset:0x3100
	ds_read_b128 v[246:249], v199 offset:0x800
	s_waitcnt lgkmcnt(3)
	v_mfma_f32_32x32x16_bf16 v[114:129], v[234:237], v[250:253], v[114:129]
	ds_read_b128 v[234:237], v218 offset:0x100
	v_mfma_f32_32x32x16_bf16 v[82:97], v[238:241], v[250:253], v[82:97]
	ds_read_b128 v[238:241], v218 offset:0x3100
	ds_read_b128 v[250:253], v199 offset:0xc00
	s_waitcnt lgkmcnt(3)
	v_mfma_f32_32x32x16_bf16 v[114:129], v[230:233], v[246:249], v[114:129]
	s_waitcnt lgkmcnt(0)
	v_mfma_f32_32x32x16_bf16 v[82:97], v[242:245], v[246:249], v[82:97]
	v_mfma_f32_32x32x16_bf16 v[114:129], v[234:237], v[250:253], v[114:129]
	v_mfma_f32_32x32x16_bf16 v[82:97], v[238:241], v[250:253], v[82:97]
	v_exp_f32_e32 v66, v66
	v_exp_f32_e32 v67, v67
	v_exp_f32_e32 v68, v68
	v_exp_f32_e32 v69, v69
	v_exp_f32_e32 v70, v70
	v_exp_f32_e32 v71, v71
	v_exp_f32_e32 v72, v72
	v_exp_f32_e32 v73, v73
	v_add_f32_e32 v166, v168, v176
	v_add_f32_e32 v179, v175, v178
	v_add_f32_e32 v180, v169, v167
	v_add_f32_e32 v181, v174, v177
	v_exp_f32_e32 v74, v74
	v_exp_f32_e32 v75, v75
	v_exp_f32_e32 v76, v76
	v_exp_f32_e32 v77, v77
	v_add_f32_e32 v166, v170, v166
	v_add_f32_e32 v179, v173, v179
	v_add_f32_e32 v180, v165, v180
	v_add_f32_e32 v181, v171, v181
	v_exp_f32_e32 v78, v78
	v_exp_f32_e32 v79, v79
	v_exp_f32_e32 v80, v80
	v_exp_f32_e32 v81, v81
	v_add_f32_e32 v166, v163, v166
	v_add_f32_e32 v179, v172, v179
	v_add_f32_e32 v180, v162, v180
	v_add_f32_e32 v181, v164, v181
	v_add_f32_e32 v166, v66, v166
	v_add_f32_e32 v179, v67, v179
	v_add_f32_e32 v180, v68, v180
	v_add_f32_e32 v181, v69, v181
	v_add_f32_e32 v166, v70, v166
	v_add_f32_e32 v179, v71, v179
	v_add_f32_e32 v180, v72, v180
	v_add_f32_e32 v181, v73, v181
	v_add_f32_e32 v166, v74, v166
	v_add_f32_e32 v179, v75, v179
	v_add_f32_e32 v180, v76, v180
	v_add_f32_e32 v181, v77, v181
	v_add_f32_e32 v166, v78, v166
	v_add_f32_e32 v179, v79, v179
	v_add_f32_e32 v180, v80, v180
	v_add_f32_e32 v181, v81, v181
	v_add_f32_e32 v166, v166, v179
	v_add_f32_e32 v179, v180, v181
	v_add_f32_e32 v223, v166, v179
	v_mov_b32_e32 v224, v223
	v_cvt_pk_bf16_f32 v166, v176, v178
	v_cvt_pk_bf16_f32 v167, v167, v177
	v_cvt_pk_bf16_f32 v168, v168, v175
	s_nop 1
	v_permlane32_swap_b32_e32 v223, v224
	v_cvt_pk_bf16_f32 v169, v169, v174
	v_permlane32_swap_b32_e32 v166, v168
; __device__ __forceinline__ void pv_d0(f32x16* o, int vb, bf16x8 pa0, bf16x8 pa1, bf16x8 pa2, bf16x8 pa3) {
;     ...
;   const s16x4 l0 = tr_read<v_rd_off(0, 0, 0)>(vb), h0 = tr_read<v_rd_off(0, 0, 1)>(vb);
;   const s16x4 l1 = tr_read<v_rd_off(0, 1, 0)>(vb), h1 = tr_read<v_rd_off(0, 1, 1)>(vb);
;   const s16x4 l2 = tr_read<v_rd_off(0, 2, 0)>(vb), h2 = tr_read<v_rd_off(0, 2, 1)>(vb);
;   const s16x4 l3 = tr_read<v_rd_off(0, 3, 0)>(vb), h3 = tr_read<v_rd_off(0, 3, 1)>(vb);
;   const s16x4 l4 = tr_read<v_rd_off(1, 0, 0)>(vb), h4 = tr_read<v_rd_off(1, 0, 1)>(vb);
;   asm volatile("s_waitcnt lgkmcnt(8)" ::: "memory"); SBAR();
;   o[0] = __builtin_amdgcn_mfma_f32_32x32x16_bf16(pa0, PK(l0, h0), o[0], 0, 0, 0);
;   const s16x4 l5 = tr_read<v_rd_off(1, 1, 0)>(vb), h5 = tr_read<v_rd_off(1, 1, 1)>(vb);
;   asm volatile("s_waitcnt lgkmcnt(8)" ::: "memory"); SBAR();
;   o[0] = __builtin_amdgcn_mfma_f32_32x32x16_bf16(pa1, PK(l1, h1), o[0], 0, 0, 0);
;   const s16x4 l6 = tr_read<v_rd_off(1, 2, 0)>(vb), h6 = tr_read<v_rd_off(1, 2, 1)>(vb);
;   asm volatile("s_waitcnt lgkmcnt(8)" ::: "memory"); SBAR();
;   o[0] = __builtin_amdgcn_mfma_f32_32x32x16_bf16(pa2, PK(l2, h2), o[0], 0, 0, 0);
;   const s16x4 l7 = tr_read<v_rd_off(1, 3, 0)>(vb), h7 = tr_read<v_rd_off(1, 3, 1)>(vb);
;   asm volatile("s_waitcnt lgkmcnt(8)" ::: "memory"); SBAR();
;   o[0] = __builtin_amdgcn_mfma_f32_32x32x16_bf16(pa3, PK(l3, h3), o[0], 0, 0, 0);
;   const s16x4 l8 = tr_read<v_rd_off(2, 0, 0)>(vb), h8 = tr_read<v_rd_off(2, 0, 1)>(vb);
;   asm volatile("s_waitcnt lgkmcnt(8)" ::: "memory"); SBAR();
;   o[1] = __builtin_amdgcn_mfma_f32_32x32x16_bf16(pa0, PK(l4, h4), o[1], 0, 0, 0);
;   const s16x4 l9 = tr_read<v_rd_off(2, 1, 0)>(vb), h9 = tr_read<v_rd_off(2, 1, 1)>(vb);
;   asm volatile("s_waitcnt lgkmcnt(8)" ::: "memory"); SBAR();
;   o[1] = __builtin_amdgcn_mfma_f32_32x32x16_bf16(pa1, PK(l5, h5), o[1], 0, 0, 0);
;   const s16x4 l10 = tr_read<v_rd_off(2, 2, 0)>(vb), h10 = tr_read<v_rd_off(2, 2, 1)>(vb);
;   asm volatile("s_waitcnt lgkmcnt(8)" ::: "memory"); SBAR();
;   o[1] = __builtin_amdgcn_mfma_f32_32x32x16_bf16(pa2, PK(l6, h6), o[1], 0, 0, 0);
;   const s16x4 l11 = tr_read<v_rd_off(2, 3, 0)>(vb), h11 = tr_read<v_rd_off(2, 3, 1)>(vb);
;   asm volatile("s_waitcnt lgkmcnt(8)" ::: "memory"); SBAR();
;   o[1] = __builtin_amdgcn_mfma_f32_32x32x16_bf16(pa3, PK(l7, h7), o[1], 0, 0, 0);
	v_cvt_pk_bf16_f32 v170, v170, v173
	v_cvt_pk_bf16_f32 v171, v165, v171
	v_cvt_pk_bf16_f32 v172, v163, v172
	v_cvt_pk_bf16_f32 v173, v162, v164
	v_cvt_pk_bf16_f32 v174, v66, v67
	v_cvt_pk_bf16_f32 v175, v68, v69
	v_cvt_pk_bf16_f32 v176, v70, v71
	v_cvt_pk_bf16_f32 v177, v72, v73
	v_cvt_pk_bf16_f32 v178, v74, v75
	v_cvt_pk_bf16_f32 v179, v76, v77
	v_cvt_pk_bf16_f32 v180, v78, v79
	v_cvt_pk_bf16_f32 v181, v80, v81
	v_permlane32_swap_b32_e32 v167, v169
	v_permlane32_swap_b32_e32 v170, v172
	v_permlane32_swap_b32_e32 v171, v173
	v_permlane32_swap_b32_e32 v174, v176
	v_permlane32_swap_b32_e32 v175, v177
	v_permlane32_swap_b32_e32 v178, v180
	v_permlane32_swap_b32_e32 v179, v181
	v_lshl_add_u64 v[190:191], s[42:43], 0, v[188:189]
	v_add_co_u32_e32 v70, vcc, s49, v190
	v_lshl_add_u64 v[196:197], s[42:43], 0, v[186:187]
	s_nop 0
	v_addc_co_u32_e32 v71, vcc, 0, v191, vcc
	v_add_co_u32_e32 v74, vcc, s28, v190
	s_nop 1
	v_addc_co_u32_e32 v75, vcc, 0, v191, vcc
	global_load_dwordx4 v[66:69], v[70:71], off offset:256
	s_nop 0
	global_load_dwordx4 v[70:73], v[70:71], off
	s_nop 0
	global_load_dwordx4 v[78:81], v[74:75], off offset:256
	s_nop 0
	global_load_dwordx4 v[74:77], v[74:75], off
	v_add_co_u32_e32 v162, vcc, s68, v196
	s_nop 1
	v_addc_co_u32_e32 v163, vcc, 0, v197, vcc
	global_load_dwordx4 v[162:165], v[162:163], off
	ds_read_b64_tr_b16 v[230:231], v201 offset:0
	ds_read_b64_tr_b16 v[232:233], v201 offset:0x800
	ds_read_b64_tr_b16 v[234:235], v201 offset:0x1000
	ds_read_b64_tr_b16 v[236:237], v201 offset:0x1800
	ds_read_b64_tr_b16 v[238:239], v201 offset:0x2000
	ds_read_b64_tr_b16 v[240:241], v201 offset:0x2800
	ds_read_b64_tr_b16 v[242:243], v201 offset:0x3000
	ds_read_b64_tr_b16 v[244:245], v201 offset:0x3800
	ds_read_b64_tr_b16 v[246:247], v201 offset:0x200
	ds_read_b64_tr_b16 v[248:249], v201 offset:0xa00
	s_waitcnt lgkmcnt(8)
	s_nop 0
	v_mfma_f32_32x32x16_bf16 v[2:17], v[166:169], v[230:233], v[2:17]
	ds_read_b64_tr_b16 v[230:231], v201 offset:0x1200
	ds_read_b64_tr_b16 v[232:233], v201 offset:0x1a00
	s_waitcnt lgkmcnt(8)
	v_mfma_f32_32x32x16_bf16 v[2:17], v[170:173], v[234:237], v[2:17]
	ds_read_b64_tr_b16 v[234:235], v201 offset:0x2200
	ds_read_b64_tr_b16 v[236:237], v201 offset:0x2a00
	s_waitcnt lgkmcnt(8)
	v_mfma_f32_32x32x16_bf16 v[2:17], v[174:177], v[238:241], v[2:17]
	ds_read_b64_tr_b16 v[238:239], v201 offset:0x3200
	ds_read_b64_tr_b16 v[240:241], v201 offset:0x3a00
	s_waitcnt lgkmcnt(8)
	v_mfma_f32_32x32x16_bf16 v[2:17], v[178:181], v[242:245], v[2:17]
	ds_read_b64_tr_b16 v[242:243], v201 offset:0x400
	ds_read_b64_tr_b16 v[244:245], v201 offset:0xc00
	s_waitcnt lgkmcnt(8)
	v_mfma_f32_32x32x16_bf16 v[50:65], v[166:169], v[246:249], v[50:65]
	ds_read_b64_tr_b16 v[246:247], v201 offset:0x1400
	ds_read_b64_tr_b16 v[248:249], v201 offset:0x1c00
	s_waitcnt lgkmcnt(8)
	v_mfma_f32_32x32x16_bf16 v[50:65], v[170:173], v[230:233], v[50:65]
	ds_read_b64_tr_b16 v[230:231], v201 offset:0x2400
	ds_read_b64_tr_b16 v[232:233], v201 offset:0x2c00
	s_waitcnt lgkmcnt(8)
	v_mfma_f32_32x32x16_bf16 v[50:65], v[174:177], v[234:237], v[50:65]
	ds_read_b64_tr_b16 v[234:235], v201 offset:0x3400
	ds_read_b64_tr_b16 v[236:237], v201 offset:0x3c00
	s_waitcnt lgkmcnt(8)
	v_mfma_f32_32x32x16_bf16 v[50:65], v[178:181], v[238:241], v[50:65]
	ds_read_b64_tr_b16 v[238:239], v201 offset:0x600
	ds_read_b64_tr_b16 v[240:241], v201 offset:0xe00
	s_waitcnt lgkmcnt(8)
	v_mfma_f32_32x32x16_bf16 v[34:49], v[166:169], v[242:245], v[34:49]
	ds_read_b64_tr_b16 v[242:243], v201 offset:0x1600
	ds_read_b64_tr_b16 v[244:245], v201 offset:0x1e00
	s_waitcnt lgkmcnt(8)
	v_mfma_f32_32x32x16_bf16 v[34:49], v[170:173], v[246:249], v[34:49]
	ds_read_b64_tr_b16 v[246:247], v201 offset:0x2600
	ds_read_b64_tr_b16 v[248:249], v201 offset:0x2e00
	s_waitcnt lgkmcnt(8)
	v_mfma_f32_32x32x16_bf16 v[34:49], v[174:177], v[230:233], v[34:49]
	ds_read_b64_tr_b16 v[230:231], v201 offset:0x3600
	ds_read_b64_tr_b16 v[232:233], v201 offset:0x3e00
	s_waitcnt lgkmcnt(8)
	v_mfma_f32_32x32x16_bf16 v[34:49], v[178:181], v[234:237], v[34:49]
	s_waitcnt lgkmcnt(6)
	v_mfma_f32_32x32x16_bf16 v[18:33], v[166:169], v[238:241], v[18:33]
	s_waitcnt lgkmcnt(4)
	v_mfma_f32_32x32x16_bf16 v[18:33], v[170:173], v[242:245], v[18:33]
	s_waitcnt lgkmcnt(2)
	v_mfma_f32_32x32x16_bf16 v[18:33], v[174:177], v[246:249], v[18:33]
	s_waitcnt lgkmcnt(0)
	v_max_f32_e32 v166, v114, v118
	v_max_f32_e32 v167, v115, v119
	v_max_f32_e32 v168, v117, v121
	v_max3_f32 v169, v116, v120, v124
	v_max3_f32 v168, v168, v125, v129
	v_max3_f32 v166, v166, v122, v126
	v_max3_f32 v167, v167, v123, v127
	v_max3_f32 v169, v169, v128, v84
	v_max3_f32 v168, v168, v85, v89
	v_max3_f32 v166, v166, v82, v86
	v_max3_f32 v167, v167, v83, v87
	v_max3_f32 v169, v169, v88, v92
	v_max3_f32 v168, v168, v93, v97
	v_mfma_f32_32x32x16_bf16 v[18:33], v[178:181], v[230:233], v[18:33]
	v_max3_f32 v166, v166, v90, v94
	v_max3_f32 v167, v167, v91, v95
	v_max3_f32 v168, v169, v96, v168
	v_max3_f32 v166, v166, v167, v168
	v_mov_b32_e32 v167, v166
	s_nop 1
	v_permlane32_swap_b32_e32 v166, v167
	v_max_f32_e32 v166, v166, v167
	v_cmp_ge_f32_e32 vcc, s48, v166
	s_cmp_eq_u64 vcc, exec
	s_cbranch_scc0 .LBB0_400
	v_mov_b32_e32 v227, v225
	v_mov_b32_e32 v226, 1.0
; __device__ __forceinline__ void qkt12_roll(f32x16& p0, f32x16& p1, const f32x16& negm, int kb, int qa, const bf16x8* qr) {
;   const int a0 = kb ^ (0 << 5); const bf16x8 x0 = lds_rd128<0>(a0), y0 = lds_rd128<12288>(a0);
;   const int a1 = kb ^ (1 << 5); const bf16x8 x1 = lds_rd128<0>(a1), y1 = lds_rd128<12288>(a1);
;   asm volatile("s_waitcnt lgkmcnt(2)" ::: "memory"); SBAR();
;   p0 = __builtin_amdgcn_mfma_f32_32x32x16_bf16(x0, qr[0], negm, 0, 0, 0); p1 = __builtin_amdgcn_mfma_f32_32x32x16_bf16(y0, qr[0], negm, 0, 0, 0);
;   const int a2 = kb ^ (2 << 5); const bf16x8 x2 = lds_rd128<0>(a2), y2 = lds_rd128<12288>(a2);
;   asm volatile("s_waitcnt lgkmcnt(2)" ::: "memory"); SBAR();
;   p0 = __builtin_amdgcn_mfma_f32_32x32x16_bf16(x1, qr[1], p0, 0, 0, 0); p1 = __builtin_amdgcn_mfma_f32_32x32x16_bf16(y1, qr[1], p1, 0, 0, 0);
;   const int a3 = kb ^ (3 << 5); const bf16x8 x3 = lds_rd128<0>(a3), y3 = lds_rd128<12288>(a3);
;   asm volatile("s_waitcnt lgkmcnt(2)" ::: "memory"); SBAR();
;   p0 = __builtin_amdgcn_mfma_f32_32x32x16_bf16(x2, qr[2], p0, 0, 0, 0); p1 = __builtin_amdgcn_mfma_f32_32x32x16_bf16(y2, qr[2], p1, 0, 0, 0);
;   const int a4 = kb ^ (0 << 5); const bf16x8 x4 = lds_rd128<128>(a4), y4 = lds_rd128<12416>(a4);
;   asm volatile("s_waitcnt lgkmcnt(2)" ::: "memory"); SBAR();
;   p0 = __builtin_amdgcn_mfma_f32_32x32x16_bf16(x3, qr[3], p0, 0, 0, 0); p1 = __builtin_amdgcn_mfma_f32_32x32x16_bf16(y3, qr[3], p1, 0, 0, 0);
;   const int a5 = kb ^ (1 << 5); const bf16x8 x5 = lds_rd128<128>(a5), y5 = lds_rd128<12416>(a5);
;   asm volatile("s_waitcnt lgkmcnt(2)" ::: "memory"); SBAR();
;   p0 = __builtin_amdgcn_mfma_f32_32x32x16_bf16(x4, qr[4], p0, 0, 0, 0); p1 = __builtin_amdgcn_mfma_f32_32x32x16_bf16(y4, qr[4], p1, 0, 0, 0);
;   const int a6 = kb ^ (2 << 5); const bf16x8 x6 = lds_rd128<128>(a6), y6 = lds_rd128<12416>(a6);
;   asm volatile("s_waitcnt lgkmcnt(2)" ::: "memory"); SBAR();
;   p0 = __builtin_amdgcn_mfma_f32_32x32x16_bf16(x5, qr[5], p0, 0, 0, 0); p1 = __builtin_amdgcn_mfma_f32_32x32x16_bf16(y5, qr[5], p1, 0, 0, 0);
;   const int a7 = kb ^ (3 << 5); const bf16x8 x7 = lds_rd128<128>(a7), y7 = lds_rd128<12416>(a7);
;   asm volatile("s_waitcnt lgkmcnt(2)" ::: "memory"); SBAR();
;   p0 = __builtin_amdgcn_mfma_f32_32x32x16_bf16(x6, qr[6], p0, 0, 0, 0); p1 = __builtin_amdgcn_mfma_f32_32x32x16_bf16(y6, qr[6], p1, 0, 0, 0);
.LBB0_388:
	s_barrier
	s_waitcnt vmcnt(0)
	v_cmp_gt_f32_e32 vcc, 1.0, v226
	ds_write_b128 v210, v[66:69]
	ds_write_b128 v211, v[78:81]
	ds_write_b128 v212, v[70:73] offset:32768
	ds_write_b128 v212, v[74:77] offset:45056
	ds_write_b128 v214, v[162:165] offset:32768
	s_cbranch_vccz .LBB0_392
	s_and_saveexec_b64 s[10:11], s[4:5]
	ds_write_b32 v200, v226 offset:128
	s_or_b64 exec, exec, s[10:11]
	s_waitcnt lgkmcnt(0)
	ds_read_b128 v[66:69], v185 offset:224
	ds_read_b128 v[70:73], v185 offset:192
	ds_read_b128 v[74:77], v185 offset:160
	ds_read_b128 v[78:81], v185 offset:128
	s_waitcnt lgkmcnt(3)
	v_pk_mul_f32 v[16:17], v[16:17], v[68:69]
	s_waitcnt lgkmcnt(2)
	v_pk_mul_f32 v[12:13], v[12:13], v[72:73]
	s_waitcnt lgkmcnt(1)
	v_pk_mul_f32 v[8:9], v[8:9], v[76:77]
	s_waitcnt lgkmcnt(0)
	v_pk_mul_f32 v[4:5], v[4:5], v[80:81]
	v_pk_mul_f32 v[14:15], v[14:15], v[66:67]
	v_pk_mul_f32 v[10:11], v[10:11], v[70:71]
	v_pk_mul_f32 v[6:7], v[6:7], v[74:75]
	v_pk_mul_f32 v[2:3], v[2:3], v[78:79]
	v_pk_mul_f32 v[64:65], v[64:65], v[68:69]
	v_pk_mul_f32 v[60:61], v[60:61], v[72:73]
	v_pk_mul_f32 v[56:57], v[56:57], v[76:77]
	v_pk_mul_f32 v[52:53], v[52:53], v[80:81]
	v_pk_mul_f32 v[62:63], v[62:63], v[66:67]
	v_pk_mul_f32 v[58:59], v[58:59], v[70:71]
	v_pk_mul_f32 v[54:55], v[54:55], v[74:75]
	v_pk_mul_f32 v[50:51], v[50:51], v[78:79]
	v_pk_mul_f32 v[48:49], v[48:49], v[68:69]
	v_pk_mul_f32 v[44:45], v[44:45], v[72:73]
	v_pk_mul_f32 v[40:41], v[40:41], v[76:77]
	v_pk_mul_f32 v[36:37], v[36:37], v[80:81]
	v_pk_mul_f32 v[46:47], v[46:47], v[66:67]
	v_pk_mul_f32 v[42:43], v[42:43], v[70:71]
	v_pk_mul_f32 v[38:39], v[38:39], v[74:75]
	v_pk_mul_f32 v[34:35], v[34:35], v[78:79]
	v_pk_mul_f32 v[32:33], v[32:33], v[68:69]
	v_pk_mul_f32 v[28:29], v[28:29], v[72:73]
	v_pk_mul_f32 v[24:25], v[24:25], v[76:77]
	v_pk_mul_f32 v[20:21], v[20:21], v[80:81]
	v_pk_mul_f32 v[30:31], v[30:31], v[66:67]
	v_pk_mul_f32 v[26:27], v[26:27], v[70:71]
	v_pk_mul_f32 v[22:23], v[22:23], v[74:75]
	v_pk_mul_f32 v[18:19], v[18:19], v[78:79]
.LBB0_392:
	v_xor_b32_e32 v66, 0x80000000, v225
	v_cndmask_b32_e64 v228, v66, v228, s[6:7]
	v_exp_f32_e32 v166, v114
	v_exp_f32_e32 v167, v116
	v_exp_f32_e32 v165, v124
	v_exp_f32_e32 v163, v126
	v_exp_f32_e32 v162, v128
	v_exp_f32_e32 v164, v129
	v_cmp_neq_f32_e64 s[6:7], v228, -v227
	s_cmp_eq_u64 s[6:7], 0
	s_cselect_b64 s[6:7], -1, 0
	v_cndmask_b32_e64 v113, -v227, v113, s[6:7]
	v_cndmask_b32_e64 v112, -v227, v112, s[6:7]
	v_cndmask_b32_e64 v111, -v227, v111, s[6:7]
	v_cndmask_b32_e64 v110, -v227, v110, s[6:7]
	v_cndmask_b32_e64 v109, -v227, v109, s[6:7]
	v_cndmask_b32_e64 v108, -v227, v108, s[6:7]
	v_cndmask_b32_e64 v107, -v227, v107, s[6:7]
	v_cndmask_b32_e64 v106, -v227, v106, s[6:7]
	v_cndmask_b32_e64 v105, -v227, v105, s[6:7]
	v_cndmask_b32_e64 v104, -v227, v104, s[6:7]
	v_cndmask_b32_e64 v103, -v227, v103, s[6:7]
	v_cndmask_b32_e64 v102, -v227, v102, s[6:7]
	v_cndmask_b32_e64 v101, -v227, v101, s[6:7]
	v_cndmask_b32_e64 v100, -v227, v100, s[6:7]
	v_cndmask_b32_e64 v99, -v227, v99, s[6:7]
	v_cndmask_b32_e64 v98, -v227, v98, s[6:7]
	v_exp_f32_e32 v177, v115
	v_exp_f32_e32 v176, v117
	v_exp_f32_e32 v168, v118
	v_exp_f32_e32 v175, v119
	v_exp_f32_e32 v169, v120
	v_exp_f32_e32 v174, v121
	v_exp_f32_e32 v170, v122
	v_exp_f32_e32 v173, v123
	v_exp_f32_e32 v171, v125
	v_exp_f32_e32 v172, v127
	s_waitcnt lgkmcnt(0)
	s_barrier
	ds_read_b128 v[66:69], v209 offset:0
	ds_read_b128 v[178:181], v209 offset:0x3000
	ds_read_b128 v[230:233], v215 offset:0
	ds_read_b128 v[234:237], v215 offset:0x3000
	s_waitcnt lgkmcnt(2)
	s_nop 0
	v_mfma_f32_32x32x16_bf16 v[114:129], v[66:69], v[158:161], v[98:113]
	v_mfma_f32_32x32x16_bf16 v[66:81], v[178:181], v[158:161], v[98:113]
	ds_read_b128 v[178:181], v216 offset:0
	ds_read_b128 v[238:241], v216 offset:0x3000
	s_waitcnt lgkmcnt(2)
	v_mfma_f32_32x32x16_bf16 v[114:129], v[230:233], v[154:157], v[114:129]
	ds_read_b128 v[230:233], v217 offset:0
	v_mfma_f32_32x32x16_bf16 v[66:81], v[234:237], v[154:157], v[66:81]
	ds_read_b128 v[234:237], v217 offset:0x3000
	s_waitcnt lgkmcnt(2)
	v_mfma_f32_32x32x16_bf16 v[114:129], v[178:181], v[150:153], v[114:129]
	ds_read_b128 v[178:181], v209 offset:0x80
	v_mfma_f32_32x32x16_bf16 v[66:81], v[238:241], v[150:153], v[66:81]
	ds_read_b128 v[238:241], v209 offset:0x3080
	s_waitcnt lgkmcnt(2)
	v_mfma_f32_32x32x16_bf16 v[114:129], v[230:233], v[146:149], v[114:129]
	ds_read_b128 v[230:233], v215 offset:0x80
	v_mfma_f32_32x32x16_bf16 v[66:81], v[234:237], v[146:149], v[66:81]
	ds_read_b128 v[234:237], v215 offset:0x3080
	s_waitcnt lgkmcnt(2)
	v_mfma_f32_32x32x16_bf16 v[114:129], v[178:181], v[142:145], v[114:129]
	ds_read_b128 v[178:181], v216 offset:0x80
	v_mfma_f32_32x32x16_bf16 v[66:81], v[238:241], v[142:145], v[66:81]
	ds_read_b128 v[238:241], v216 offset:0x3080
	s_waitcnt lgkmcnt(2)
	v_mfma_f32_32x32x16_bf16 v[114:129], v[230:233], v[138:141], v[114:129]
	ds_read_b128 v[230:233], v217 offset:0x80
	v_mfma_f32_32x32x16_bf16 v[66:81], v[234:237], v[138:141], v[66:81]
	ds_read_b128 v[234:237], v217 offset:0x3080
	s_waitcnt lgkmcnt(2)
	v_mfma_f32_32x32x16_bf16 v[114:129], v[178:181], v[134:137], v[114:129]
	ds_read_b128 v[178:181], v209 offset:0x100
	v_mfma_f32_32x32x16_bf16 v[66:81], v[238:241], v[134:137], v[66:81]
	ds_read_b128 v[238:241], v209 offset:0x3100
	ds_read_b128 v[242:245], v199 offset:0
	s_waitcnt lgkmcnt(3)
	v_mfma_f32_32x32x16_bf16 v[114:129], v[230:233], v[130:133], v[114:129]
	ds_read_b128 v[230:233], v215 offset:0x100
	v_mfma_f32_32x32x16_bf16 v[66:81], v[234:237], v[130:133], v[66:81]
	ds_read_b128 v[234:237], v215 offset:0x3100
	ds_read_b128 v[246:249], v199 offset:0x400
	s_waitcnt lgkmcnt(3)
; __device__ __forceinline__ void qkt12_roll(f32x16& p0, f32x16& p1, const f32x16& negm, int kb, int qa, const bf16x8* qr) {
;   const int a0 = kb ^ (0 << 5); const bf16x8 x0 = lds_rd128<0>(a0), y0 = lds_rd128<12288>(a0);
;   const int a1 = kb ^ (1 << 5); const bf16x8 x1 = lds_rd128<0>(a1), y1 = lds_rd128<12288>(a1);
;   asm volatile("s_waitcnt lgkmcnt(2)" ::: "memory"); SBAR();
;   p0 = __builtin_amdgcn_mfma_f32_32x32x16_bf16(x0, qr[0], negm, 0, 0, 0); p1 = __builtin_amdgcn_mfma_f32_32x32x16_bf16(y0, qr[0], negm, 0, 0, 0);
;   const int a2 = kb ^ (2 << 5); const bf16x8 x2 = lds_rd128<0>(a2), y2 = lds_rd128<12288>(a2);
;   asm volatile("s_waitcnt lgkmcnt(2)" ::: "memory"); SBAR();
;   p0 = __builtin_amdgcn_mfma_f32_32x32x16_bf16(x1, qr[1], p0, 0, 0, 0); p1 = __builtin_amdgcn_mfma_f32_32x32x16_bf16(y1, qr[1], p1, 0, 0, 0);
;   const int a3 = kb ^ (3 << 5); const bf16x8 x3 = lds_rd128<0>(a3), y3 = lds_rd128<12288>(a3);
;   asm volatile("s_waitcnt lgkmcnt(2)" ::: "memory"); SBAR();
;   p0 = __builtin_amdgcn_mfma_f32_32x32x16_bf16(x2, qr[2], p0, 0, 0, 0); p1 = __builtin_amdgcn_mfma_f32_32x32x16_bf16(y2, qr[2], p1, 0, 0, 0);
;   const int a4 = kb ^ (0 << 5); const bf16x8 x4 = lds_rd128<128>(a4), y4 = lds_rd128<12416>(a4);
;   asm volatile("s_waitcnt lgkmcnt(2)" ::: "memory"); SBAR();
;   p0 = __builtin_amdgcn_mfma_f32_32x32x16_bf16(x3, qr[3], p0, 0, 0, 0); p1 = __builtin_amdgcn_mfma_f32_32x32x16_bf16(y3, qr[3], p1, 0, 0, 0);
;   const int a5 = kb ^ (1 << 5); const bf16x8 x5 = lds_rd128<128>(a5), y5 = lds_rd128<12416>(a5);
;   asm volatile("s_waitcnt lgkmcnt(2)" ::: "memory"); SBAR();
;   p0 = __builtin_amdgcn_mfma_f32_32x32x16_bf16(x4, qr[4], p0, 0, 0, 0); p1 = __builtin_amdgcn_mfma_f32_32x32x16_bf16(y4, qr[4], p1, 0, 0, 0);
;   const int a6 = kb ^ (2 << 5); const bf16x8 x6 = lds_rd128<128>(a6), y6 = lds_rd128<12416>(a6);
;   asm volatile("s_waitcnt lgkmcnt(2)" ::: "memory"); SBAR();
;   p0 = __builtin_amdgcn_mfma_f32_32x32x16_bf16(x5, qr[5], p0, 0, 0, 0); p1 = __builtin_amdgcn_mfma_f32_32x32x16_bf16(y5, qr[5], p1, 0, 0, 0);
;   const int a7 = kb ^ (3 << 5); const bf16x8 x7 = lds_rd128<128>(a7), y7 = lds_rd128<12416>(a7);
;   asm volatile("s_waitcnt lgkmcnt(2)" ::: "memory"); SBAR();
;   p0 = __builtin_amdgcn_mfma_f32_32x32x16_bf16(x6, qr[6], p0, 0, 0, 0); p1 = __builtin_amdgcn_mfma_f32_32x32x16_bf16(y6, qr[6], p1, 0, 0, 0);
	v_mfma_f32_32x32x16_bf16 v[114:129], v[178:181], v[242:245], v[114:129]
	ds_read_b128 v[178:181], v216 offset:0x100
	v_mfma_f32_32x32x16_bf16 v[66:81], v[238:241], v[242:245], v[66:81]
	ds_read_b128 v[238:241], v216 offset:0x3100
	ds_read_b128 v[242:245], v199 offset:0x800
	s_waitcnt lgkmcnt(3)
	v_mfma_f32_32x32x16_bf16 v[114:129], v[230:233], v[246:249], v[114:129]
	ds_read_b128 v[230:233], v217 offset:0x100
	v_mfma_f32_32x32x16_bf16 v[66:81], v[234:237], v[246:249], v[66:81]
	ds_read_b128 v[234:237], v217 offset:0x3100
	ds_read_b128 v[246:249], v199 offset:0xc00
	s_waitcnt lgkmcnt(3)
	v_mfma_f32_32x32x16_bf16 v[114:129], v[178:181], v[242:245], v[114:129]
	s_waitcnt lgkmcnt(0)
	v_mfma_f32_32x32x16_bf16 v[66:81], v[238:241], v[242:245], v[66:81]
	v_mfma_f32_32x32x16_bf16 v[114:129], v[230:233], v[246:249], v[114:129]
	v_mfma_f32_32x32x16_bf16 v[66:81], v[234:237], v[246:249], v[66:81]
	v_exp_f32_e32 v82, v82
	v_exp_f32_e32 v83, v83
	v_exp_f32_e32 v84, v84
	v_exp_f32_e32 v85, v85
	v_exp_f32_e32 v86, v86
	v_exp_f32_e32 v87, v87
	v_exp_f32_e32 v88, v88
	v_exp_f32_e32 v89, v89
	v_add_f32_e32 v178, v168, v166
	v_add_f32_e32 v179, v175, v177
	v_add_f32_e32 v180, v169, v167
	v_add_f32_e32 v181, v174, v176
	v_exp_f32_e32 v90, v90
	v_exp_f32_e32 v91, v91
	v_exp_f32_e32 v92, v92
	v_exp_f32_e32 v93, v93
	v_add_f32_e32 v178, v170, v178
	v_add_f32_e32 v179, v173, v179
	v_add_f32_e32 v180, v165, v180
	v_add_f32_e32 v181, v171, v181
	v_exp_f32_e32 v94, v94
	v_exp_f32_e32 v95, v95
	v_exp_f32_e32 v96, v96
	v_exp_f32_e32 v97, v97
	v_add_f32_e32 v178, v163, v178
	v_add_f32_e32 v179, v172, v179
	v_add_f32_e32 v180, v162, v180
	v_add_f32_e32 v181, v164, v181
	v_add_f32_e32 v178, v82, v178
	v_add_f32_e32 v179, v179, v83
	v_add_f32_e32 v180, v180, v84
	v_add_f32_e32 v181, v181, v85
	v_add_f32_e32 v178, v86, v178
	v_add_f32_e32 v179, v87, v179
	v_add_f32_e32 v180, v88, v180
	v_add_f32_e32 v181, v89, v181
	v_add_f32_e32 v178, v90, v178
	v_add_f32_e32 v179, v91, v179
	v_add_f32_e32 v180, v92, v180
	v_add_f32_e32 v181, v93, v181
	v_add_f32_e32 v178, v94, v178
	v_add_f32_e32 v179, v95, v179
	v_add_f32_e32 v180, v96, v180
	v_add_f32_e32 v181, v97, v181
	v_add_f32_e32 v178, v178, v179
	v_add_f32_e32 v179, v180, v181
	v_add_f32_e32 v229, v178, v179
	v_mov_b32_e32 v230, v229
	v_cvt_pk_bf16_f32 v166, v166, v177
	v_cvt_pk_bf16_f32 v167, v167, v176
	v_cvt_pk_bf16_f32 v168, v168, v175
	v_cvt_pk_bf16_f32 v169, v169, v174
	s_nop 1
	v_permlane32_swap_b32_e32 v229, v230
	v_permlane32_swap_b32_e32 v166, v168
	v_permlane32_swap_b32_e32 v167, v169
	v_cvt_pk_bf16_f32 v170, v170, v173
	v_cvt_pk_bf16_f32 v171, v165, v171
	v_cvt_pk_bf16_f32 v172, v163, v172
	v_cvt_pk_bf16_f32 v173, v162, v164
	v_cvt_pk_bf16_f32 v174, v82, v83
	v_cvt_pk_bf16_f32 v175, v84, v85
	v_cvt_pk_bf16_f32 v176, v86, v87
	v_cvt_pk_bf16_f32 v177, v88, v89
	v_cvt_pk_bf16_f32 v178, v90, v91
	v_cvt_pk_bf16_f32 v179, v92, v93
	v_cvt_pk_bf16_f32 v180, v94, v95
	v_cvt_pk_bf16_f32 v181, v96, v97
	s_nop 0
	v_permlane32_swap_b32_e32 v170, v172
	v_permlane32_swap_b32_e32 v171, v173
	v_permlane32_swap_b32_e32 v174, v176
	v_permlane32_swap_b32_e32 v175, v177
	v_permlane32_swap_b32_e32 v178, v180
	v_permlane32_swap_b32_e32 v179, v181
	v_add_co_u32_e32 v86, vcc, s69, v190
	s_nop 1
	v_addc_co_u32_e32 v87, vcc, 0, v191, vcc
	v_add_co_u32_e32 v90, vcc, s74, v190
	s_nop 1
	v_addc_co_u32_e32 v91, vcc, 0, v191, vcc
	global_load_dwordx4 v[82:85], v[86:87], off offset:256
	s_nop 0
	global_load_dwordx4 v[86:89], v[86:87], off
	s_nop 0
	global_load_dwordx4 v[94:97], v[90:91], off offset:256
	s_nop 0
	global_load_dwordx4 v[90:93], v[90:91], off
	v_add_co_u32_e32 v162, vcc, s75, v196
	s_nop 1
	v_addc_co_u32_e32 v163, vcc, 0, v197, vcc
	global_load_dwordx4 v[162:165], v[162:163], off
	ds_read_b64_tr_b16 v[232:233], v208 offset:0
	ds_read_b64_tr_b16 v[234:235], v208 offset:0x800
	ds_read_b64_tr_b16 v[236:237], v208 offset:0x1000
	ds_read_b64_tr_b16 v[238:239], v208 offset:0x1800
	ds_read_b64_tr_b16 v[240:241], v208 offset:0x2000
	ds_read_b64_tr_b16 v[242:243], v208 offset:0x2800
	ds_read_b64_tr_b16 v[244:245], v208 offset:0x3000
	ds_read_b64_tr_b16 v[246:247], v208 offset:0x3800
	ds_read_b64_tr_b16 v[248:249], v208 offset:0x200
	ds_read_b64_tr_b16 v[250:251], v208 offset:0xa00
	s_waitcnt lgkmcnt(8)
	s_nop 0
	v_mfma_f32_32x32x16_bf16 v[2:17], v[166:169], v[232:235], v[2:17]
	ds_read_b64_tr_b16 v[232:233], v208 offset:0x1200
	ds_read_b64_tr_b16 v[234:235], v208 offset:0x1a00
	s_waitcnt lgkmcnt(8)
	v_mfma_f32_32x32x16_bf16 v[2:17], v[170:173], v[236:239], v[2:17]
	ds_read_b64_tr_b16 v[236:237], v208 offset:0x2200
	ds_read_b64_tr_b16 v[238:239], v208 offset:0x2a00
	s_waitcnt lgkmcnt(8)
	v_mfma_f32_32x32x16_bf16 v[2:17], v[174:177], v[240:243], v[2:17]
	ds_read_b64_tr_b16 v[240:241], v208 offset:0x3200
	ds_read_b64_tr_b16 v[242:243], v208 offset:0x3a00
	s_waitcnt lgkmcnt(8)
; __device__ __forceinline__ void pv_d0(f32x16* o, int vb, bf16x8 pa0, bf16x8 pa1, bf16x8 pa2, bf16x8 pa3) {
;     ...
;   const s16x4 l0 = tr_read<v_rd_off(0, 0, 0)>(vb), h0 = tr_read<v_rd_off(0, 0, 1)>(vb);
;   const s16x4 l1 = tr_read<v_rd_off(0, 1, 0)>(vb), h1 = tr_read<v_rd_off(0, 1, 1)>(vb);
;   const s16x4 l2 = tr_read<v_rd_off(0, 2, 0)>(vb), h2 = tr_read<v_rd_off(0, 2, 1)>(vb);
;   const s16x4 l3 = tr_read<v_rd_off(0, 3, 0)>(vb), h3 = tr_read<v_rd_off(0, 3, 1)>(vb);
;   const s16x4 l4 = tr_read<v_rd_off(1, 0, 0)>(vb), h4 = tr_read<v_rd_off(1, 0, 1)>(vb);
;   asm volatile("s_waitcnt lgkmcnt(8)" ::: "memory"); SBAR();
;   o[0] = __builtin_amdgcn_mfma_f32_32x32x16_bf16(pa0, PK(l0, h0), o[0], 0, 0, 0);
;   const s16x4 l5 = tr_read<v_rd_off(1, 1, 0)>(vb), h5 = tr_read<v_rd_off(1, 1, 1)>(vb);
;   asm volatile("s_waitcnt lgkmcnt(8)" ::: "memory"); SBAR();
;   o[0] = __builtin_amdgcn_mfma_f32_32x32x16_bf16(pa1, PK(l1, h1), o[0], 0, 0, 0);
;   const s16x4 l6 = tr_read<v_rd_off(1, 2, 0)>(vb), h6 = tr_read<v_rd_off(1, 2, 1)>(vb);
;   asm volatile("s_waitcnt lgkmcnt(8)" ::: "memory"); SBAR();
;   o[0] = __builtin_amdgcn_mfma_f32_32x32x16_bf16(pa2, PK(l2, h2), o[0], 0, 0, 0);
;   const s16x4 l7 = tr_read<v_rd_off(1, 3, 0)>(vb), h7 = tr_read<v_rd_off(1, 3, 1)>(vb);
;   asm volatile("s_waitcnt lgkmcnt(8)" ::: "memory"); SBAR();
;   o[0] = __builtin_amdgcn_mfma_f32_32x32x16_bf16(pa3, PK(l3, h3), o[0], 0, 0, 0);
;   const s16x4 l8 = tr_read<v_rd_off(2, 0, 0)>(vb), h8 = tr_read<v_rd_off(2, 0, 1)>(vb);
;   asm volatile("s_waitcnt lgkmcnt(8)" ::: "memory"); SBAR();
;   o[1] = __builtin_amdgcn_mfma_f32_32x32x16_bf16(pa0, PK(l4, h4), o[1], 0, 0, 0);
;   const s16x4 l9 = tr_read<v_rd_off(2, 1, 0)>(vb), h9 = tr_read<v_rd_off(2, 1, 1)>(vb);
;   asm volatile("s_waitcnt lgkmcnt(8)" ::: "memory"); SBAR();
;   o[1] = __builtin_amdgcn_mfma_f32_32x32x16_bf16(pa1, PK(l5, h5), o[1], 0, 0, 0);
;   const s16x4 l10 = tr_read<v_rd_off(2, 2, 0)>(vb), h10 = tr_read<v_rd_off(2, 2, 1)>(vb);
;   asm volatile("s_waitcnt lgkmcnt(8)" ::: "memory"); SBAR();
;   o[1] = __builtin_amdgcn_mfma_f32_32x32x16_bf16(pa2, PK(l6, h6), o[1], 0, 0, 0);
;   const s16x4 l11 = tr_read<v_rd_off(2, 3, 0)>(vb), h11 = tr_read<v_rd_off(2, 3, 1)>(vb);
;   asm volatile("s_waitcnt lgkmcnt(8)" ::: "memory"); SBAR();
;   o[1] = __builtin_amdgcn_mfma_f32_32x32x16_bf16(pa3, PK(l7, h7), o[1], 0, 0, 0);
	v_mfma_f32_32x32x16_bf16 v[2:17], v[178:181], v[244:247], v[2:17]
	ds_read_b64_tr_b16 v[244:245], v208 offset:0x400
	ds_read_b64_tr_b16 v[246:247], v208 offset:0xc00
	s_waitcnt lgkmcnt(8)
	v_mfma_f32_32x32x16_bf16 v[50:65], v[166:169], v[248:251], v[50:65]
	ds_read_b64_tr_b16 v[248:249], v208 offset:0x1400
	ds_read_b64_tr_b16 v[250:251], v208 offset:0x1c00
	s_waitcnt lgkmcnt(8)
	v_mfma_f32_32x32x16_bf16 v[50:65], v[170:173], v[232:235], v[50:65]
	ds_read_b64_tr_b16 v[232:233], v208 offset:0x2400
	ds_read_b64_tr_b16 v[234:235], v208 offset:0x2c00
	s_waitcnt lgkmcnt(8)
	v_mfma_f32_32x32x16_bf16 v[50:65], v[174:177], v[236:239], v[50:65]
	ds_read_b64_tr_b16 v[236:237], v208 offset:0x3400
	ds_read_b64_tr_b16 v[238:239], v208 offset:0x3c00
	s_waitcnt lgkmcnt(8)
	v_mfma_f32_32x32x16_bf16 v[50:65], v[178:181], v[240:243], v[50:65]
	ds_read_b64_tr_b16 v[240:241], v208 offset:0x600
	ds_read_b64_tr_b16 v[242:243], v208 offset:0xe00
	s_waitcnt lgkmcnt(8)
	v_mfma_f32_32x32x16_bf16 v[34:49], v[166:169], v[244:247], v[34:49]
	ds_read_b64_tr_b16 v[244:245], v208 offset:0x1600
	ds_read_b64_tr_b16 v[246:247], v208 offset:0x1e00
	s_waitcnt lgkmcnt(8)
	v_mfma_f32_32x32x16_bf16 v[34:49], v[170:173], v[248:251], v[34:49]
	ds_read_b64_tr_b16 v[248:249], v208 offset:0x2600
	ds_read_b64_tr_b16 v[250:251], v208 offset:0x2e00
	s_waitcnt lgkmcnt(8)
	v_mfma_f32_32x32x16_bf16 v[34:49], v[174:177], v[232:235], v[34:49]
	ds_read_b64_tr_b16 v[232:233], v208 offset:0x3600
	ds_read_b64_tr_b16 v[234:235], v208 offset:0x3e00
	s_waitcnt lgkmcnt(8)
	v_mfma_f32_32x32x16_bf16 v[34:49], v[178:181], v[236:239], v[34:49]
	s_waitcnt lgkmcnt(6)
	v_mfma_f32_32x32x16_bf16 v[18:33], v[166:169], v[240:243], v[18:33]
	s_waitcnt lgkmcnt(4)
	v_mfma_f32_32x32x16_bf16 v[18:33], v[170:173], v[244:247], v[18:33]
	s_waitcnt lgkmcnt(2)
	v_mfma_f32_32x32x16_bf16 v[18:33], v[174:177], v[248:251], v[18:33]
	s_waitcnt lgkmcnt(0)
	v_max_f32_e32 v166, v114, v118
	v_max_f32_e32 v167, v115, v119
	v_max_f32_e32 v168, v117, v121
	v_max3_f32 v169, v116, v120, v124
	v_max3_f32 v168, v168, v125, v129
	v_max3_f32 v166, v166, v122, v126
	v_max3_f32 v167, v167, v123, v127
	v_max3_f32 v169, v169, v128, v68
	v_max3_f32 v168, v168, v69, v73
	v_max3_f32 v166, v166, v66, v70
	v_max3_f32 v167, v167, v67, v71
	v_max3_f32 v169, v169, v72, v76
	v_max3_f32 v168, v168, v77, v81
	v_mfma_f32_32x32x16_bf16 v[18:33], v[178:181], v[232:235], v[18:33]
	v_max3_f32 v166, v166, v74, v78
	v_max3_f32 v167, v167, v75, v79
	v_max3_f32 v168, v169, v80, v168
	v_max3_f32 v166, v166, v167, v168
	v_mov_b32_e32 v167, v166
	s_nop 1
	v_permlane32_swap_b32_e32 v166, v167
	v_max_f32_e32 v167, v166, v167
	v_cmp_ge_f32_e32 vcc, s48, v167
	s_cmp_eq_u64 vcc, exec
	v_mov_b32_e32 v166, 1.0
	s_cbranch_scc0 .LBB0_401
	v_mov_b32_e32 v225, v227
.LBB0_394:
	s_barrier
	s_waitcnt vmcnt(0)
	v_cmp_gt_f32_e32 vcc, 1.0, v166
	ds_write_b128 v210, v[82:85] offset:16384
	ds_write_b128 v211, v[94:97] offset:16384
	ds_write_b128 v212, v[86:89] offset:57344
	ds_write_b128 v213, v[90:93] offset:57344
	ds_write_b128 v214, v[162:165] offset:57344
	s_cbranch_vccz .LBB0_398
	s_and_saveexec_b64 s[10:11], s[4:5]
	ds_write_b32 v200, v166 offset:128
	s_or_b64 exec, exec, s[10:11]
	s_waitcnt lgkmcnt(0)
	ds_read_b128 v[82:85], v185 offset:224
	ds_read_b128 v[86:89], v185 offset:192
	ds_read_b128 v[90:93], v185 offset:160
	ds_read_b128 v[94:97], v185 offset:128
	s_waitcnt lgkmcnt(3)
	v_pk_mul_f32 v[16:17], v[16:17], v[84:85]
	s_waitcnt lgkmcnt(2)
	v_pk_mul_f32 v[12:13], v[12:13], v[88:89]
	s_waitcnt lgkmcnt(1)
	v_pk_mul_f32 v[8:9], v[8:9], v[92:93]
	s_waitcnt lgkmcnt(0)
	v_pk_mul_f32 v[4:5], v[4:5], v[96:97]
	v_pk_mul_f32 v[14:15], v[14:15], v[82:83]
	v_pk_mul_f32 v[10:11], v[10:11], v[86:87]
	v_pk_mul_f32 v[6:7], v[6:7], v[90:91]
	v_pk_mul_f32 v[2:3], v[2:3], v[94:95]
	v_pk_mul_f32 v[64:65], v[64:65], v[84:85]
	v_pk_mul_f32 v[60:61], v[60:61], v[88:89]
	v_pk_mul_f32 v[56:57], v[56:57], v[92:93]
	v_pk_mul_f32 v[52:53], v[52:53], v[96:97]
	v_pk_mul_f32 v[62:63], v[62:63], v[82:83]
	v_pk_mul_f32 v[58:59], v[58:59], v[86:87]
	v_pk_mul_f32 v[54:55], v[54:55], v[90:91]
	v_pk_mul_f32 v[50:51], v[50:51], v[94:95]
	v_pk_mul_f32 v[48:49], v[48:49], v[84:85]
	v_pk_mul_f32 v[44:45], v[44:45], v[88:89]
	v_pk_mul_f32 v[40:41], v[40:41], v[92:93]
	v_pk_mul_f32 v[36:37], v[36:37], v[96:97]
	v_pk_mul_f32 v[46:47], v[46:47], v[82:83]
	v_pk_mul_f32 v[42:43], v[42:43], v[86:87]
	v_pk_mul_f32 v[38:39], v[38:39], v[90:91]
	v_pk_mul_f32 v[34:35], v[34:35], v[94:95]
	v_pk_mul_f32 v[32:33], v[32:33], v[84:85]
	v_pk_mul_f32 v[28:29], v[28:29], v[88:89]
	v_pk_mul_f32 v[24:25], v[24:25], v[92:93]
	v_pk_mul_f32 v[20:21], v[20:21], v[96:97]
	v_pk_mul_f32 v[30:31], v[30:31], v[82:83]
	v_pk_mul_f32 v[26:27], v[26:27], v[86:87]
	v_pk_mul_f32 v[22:23], v[22:23], v[90:91]
	v_pk_mul_f32 v[18:19], v[18:19], v[94:95]

; __device__ __forceinline__ void qkt8_roll(f32x16& p0, f32x16& p1, const f32x16& negm, int kb, const bf16x8* qr) {
;   const int a0 = kb ^ (0 << 5); const bf16x8 x0 = lds_rd128<0>(a0), y0 = lds_rd128<8192>(a0);
;   const int a1 = kb ^ (1 << 5); const bf16x8 x1 = lds_rd128<0>(a1), y1 = lds_rd128<8192>(a1);
;   const int a2 = kb ^ (2 << 5); const bf16x8 x2 = lds_rd128<0>(a2), y2 = lds_rd128<8192>(a2);
;   asm volatile("s_waitcnt lgkmcnt(4)" ::: "memory"); SBAR_M();
;   p0 = __builtin_amdgcn_mfma_f32_32x32x16_bf16(x0, qr[0], negm, 0, 0, 0); p1 = __builtin_amdgcn_mfma_f32_32x32x16_bf16(y0, qr[0], negm, 0, 0, 0);
;   const int a3 = kb ^ (3 << 5); const bf16x8 x3 = lds_rd128<0>(a3), y3 = lds_rd128<8192>(a3);
;   asm volatile("s_waitcnt lgkmcnt(4)" ::: "memory"); SBAR_M();
;   p0 = __builtin_amdgcn_mfma_f32_32x32x16_bf16(x1, qr[1], p0, 0, 0, 0); p1 = __builtin_amdgcn_mfma_f32_32x32x16_bf16(y1, qr[1], p1, 0, 0, 0);
;   const int a4 = kb ^ (4 << 5); const bf16x8 x4 = lds_rd128<0>(a4), y4 = lds_rd128<8192>(a4);
;   asm volatile("s_waitcnt lgkmcnt(4)" ::: "memory"); SBAR_M();
;   p0 = __builtin_amdgcn_mfma_f32_32x32x16_bf16(x2, qr[2], p0, 0, 0, 0); p1 = __builtin_amdgcn_mfma_f32_32x32x16_bf16(y2, qr[2], p1, 0, 0, 0);
;   const int a5 = kb ^ (5 << 5); const bf16x8 x5 = lds_rd128<0>(a5), y5 = lds_rd128<8192>(a5);
;   asm volatile("s_waitcnt lgkmcnt(4)" ::: "memory"); SBAR_M();
;   p0 = __builtin_amdgcn_mfma_f32_32x32x16_bf16(x3, qr[3], p0, 0, 0, 0); p1 = __builtin_amdgcn_mfma_f32_32x32x16_bf16(y3, qr[3], p1, 0, 0, 0);
;   const int a6 = kb ^ (6 << 5); const bf16x8 x6 = lds_rd128<0>(a6), y6 = lds_rd128<8192>(a6);
;   asm volatile("s_waitcnt lgkmcnt(4)" ::: "memory"); SBAR_M();
;   p0 = __builtin_amdgcn_mfma_f32_32x32x16_bf16(x4, qr[4], p0, 0, 0, 0); p1 = __builtin_amdgcn_mfma_f32_32x32x16_bf16(y4, qr[4], p1, 0, 0, 0);
;   const int a7 = kb ^ (7 << 5); const bf16x8 x7 = lds_rd128<0>(a7), y7 = lds_rd128<8192>(a7);
;   asm volatile("s_waitcnt lgkmcnt(4)" ::: "memory"); SBAR_M();
;   p0 = __builtin_amdgcn_mfma_f32_32x32x16_bf16(x5, qr[5], p0, 0, 0, 0); p1 = __builtin_amdgcn_mfma_f32_32x32x16_bf16(y5, qr[5], p1, 0, 0, 0);
;   asm volatile("s_waitcnt lgkmcnt(2)" ::: "memory"); SBAR_M();
;   p0 = __builtin_amdgcn_mfma_f32_32x32x16_bf16(x6, qr[6], p0, 0, 0, 0); p1 = __builtin_amdgcn_mfma_f32_32x32x16_bf16(y6, qr[6], p1, 0, 0, 0);
.LBB0_421:
	v_exp_f32_e32 v66, v66
	v_exp_f32_e32 v67, v67
	v_exp_f32_e32 v68, v68
	v_exp_f32_e32 v69, v69
	v_exp_f32_e32 v70, v70
	v_exp_f32_e32 v71, v71
	v_exp_f32_e32 v72, v72
	v_exp_f32_e32 v73, v73
	v_add_f32_e32 v98, v148, v146
	v_add_f32_e32 v99, v159, v161
	v_add_f32_e32 v100, v149, v147
	v_add_f32_e32 v101, v158, v160
	v_exp_f32_e32 v74, v74
	v_exp_f32_e32 v75, v75
	v_exp_f32_e32 v76, v76
	v_exp_f32_e32 v77, v77
	v_add_f32_e32 v98, v150, v98
	v_add_f32_e32 v99, v157, v99
	v_add_f32_e32 v100, v151, v100
	v_add_f32_e32 v101, v156, v101
	v_exp_f32_e32 v78, v78
	v_exp_f32_e32 v79, v79
	v_exp_f32_e32 v80, v80
	v_exp_f32_e32 v81, v81
	v_add_f32_e32 v98, v152, v98
	v_add_f32_e32 v99, v155, v99
	v_add_f32_e32 v100, v153, v100
	v_add_f32_e32 v101, v154, v101
	v_add_f32_e32 v98, v66, v98
	v_add_f32_e32 v99, v67, v99
	v_add_f32_e32 v100, v68, v100
	v_add_f32_e32 v101, v69, v101
	v_add_f32_e32 v98, v70, v98
	v_add_f32_e32 v99, v71, v99
	v_add_f32_e32 v100, v72, v100
	v_add_f32_e32 v101, v73, v101
	v_add_f32_e32 v98, v74, v98
	v_add_f32_e32 v99, v75, v99
	v_add_f32_e32 v100, v76, v100
	v_add_f32_e32 v101, v77, v101
	v_add_f32_e32 v98, v78, v98
	v_add_f32_e32 v99, v79, v99
	v_add_f32_e32 v100, v80, v100
	v_add_f32_e32 v101, v81, v101
	v_add_f32_e32 v98, v98, v99
	v_add_f32_e32 v99, v100, v101
	v_add_f32_e32 v228, v98, v99
	v_mov_b32_e32 v229, v228
	v_cvt_pk_bf16_f32 v146, v146, v161
	v_cvt_pk_bf16_f32 v147, v147, v160
	v_cvt_pk_bf16_f32 v148, v148, v159
	v_cvt_pk_bf16_f32 v149, v149, v158
	v_cvt_pk_bf16_f32 v150, v150, v157
	v_cvt_pk_bf16_f32 v151, v151, v156
	v_cvt_pk_bf16_f32 v152, v152, v155
	v_cvt_pk_bf16_f32 v153, v153, v154
	v_cvt_pk_bf16_f32 v158, v66, v67
	v_cvt_pk_bf16_f32 v159, v68, v69
	v_cvt_pk_bf16_f32 v160, v70, v71
	v_cvt_pk_bf16_f32 v161, v72, v73
	v_cvt_pk_bf16_f32 v154, v74, v75
	v_cvt_pk_bf16_f32 v155, v76, v77
	v_cvt_pk_bf16_f32 v156, v78, v79
	v_cvt_pk_bf16_f32 v157, v80, v81
	s_nop 1
	v_permlane32_swap_b32_e32 v228, v229
	v_permlane32_swap_b32_e32 v146, v148
	v_permlane32_swap_b32_e32 v147, v149
	v_permlane32_swap_b32_e32 v150, v152
	v_permlane32_swap_b32_e32 v151, v153
	v_permlane32_swap_b32_e32 v158, v160
	v_permlane32_swap_b32_e32 v159, v161
	v_permlane32_swap_b32_e32 v154, v156
	v_permlane32_swap_b32_e32 v155, v157
	v_cmp_neq_f32_e64 s[6:7], v232, -v227
	s_cmp_eq_u64 s[6:7], 0
	s_cselect_b64 s[6:7], -1, 0
	v_cndmask_b32_e64 v81, -v227, v97, s[6:7]
	v_cndmask_b32_e64 v80, -v227, v96, s[6:7]
	v_cndmask_b32_e64 v79, -v227, v95, s[6:7]
	v_cndmask_b32_e64 v78, -v227, v94, s[6:7]
	v_cndmask_b32_e64 v77, -v227, v93, s[6:7]
	v_cndmask_b32_e64 v76, -v227, v92, s[6:7]
	v_cndmask_b32_e64 v75, -v227, v91, s[6:7]
	v_cndmask_b32_e64 v74, -v227, v90, s[6:7]
	v_cndmask_b32_e64 v73, -v227, v89, s[6:7]
	v_cndmask_b32_e64 v72, -v227, v88, s[6:7]
	v_cndmask_b32_e64 v71, -v227, v87, s[6:7]
	v_cndmask_b32_e64 v70, -v227, v86, s[6:7]
	v_cndmask_b32_e64 v69, -v227, v85, s[6:7]
	v_cndmask_b32_e64 v68, -v227, v84, s[6:7]
	v_cndmask_b32_e64 v67, -v227, v83, s[6:7]
	v_cndmask_b32_e64 v66, -v227, v82, s[6:7]
	ds_read_b128 v[82:85], v224 offset:0
	ds_read_b128 v[162:165], v224 offset:0x2000
	ds_read_b128 v[166:169], v223 offset:0
	ds_read_b128 v[170:173], v223 offset:0x2000
	ds_read_b128 v[174:177], v222 offset:0
	ds_read_b128 v[188:191], v222 offset:0x2000
	s_waitcnt lgkmcnt(4)
	s_nop 1
	v_mfma_f32_32x32x16_bf16 v[98:113], v[82:85], v[142:145], v[66:81]
	v_mfma_f32_32x32x16_bf16 v[82:97], v[162:165], v[142:145], v[66:81]
	ds_read_b128 v[162:165], v221 offset:0
	ds_read_b128 v[192:195], v221 offset:0x2000
	s_waitcnt lgkmcnt(4)
	v_mfma_f32_32x32x16_bf16 v[98:113], v[166:169], v[138:141], v[98:113]
	ds_read_b128 v[166:169], v220 offset:0
	v_mfma_f32_32x32x16_bf16 v[82:97], v[170:173], v[138:141], v[82:97]
	ds_read_b128 v[170:173], v220 offset:0x2000
	s_waitcnt lgkmcnt(4)
	v_mfma_f32_32x32x16_bf16 v[98:113], v[174:177], v[134:137], v[98:113]
	ds_read_b128 v[174:177], v219 offset:0
	v_mfma_f32_32x32x16_bf16 v[82:97], v[188:191], v[134:137], v[82:97]
	ds_read_b128 v[188:191], v219 offset:0x2000
	s_waitcnt lgkmcnt(4)
	v_mfma_f32_32x32x16_bf16 v[98:113], v[162:165], v[130:133], v[98:113]
	ds_read_b128 v[162:165], v218 offset:0
	v_mfma_f32_32x32x16_bf16 v[82:97], v[192:195], v[130:133], v[82:97]
	ds_read_b128 v[192:195], v218 offset:0x2000
	s_waitcnt lgkmcnt(4)
	v_mfma_f32_32x32x16_bf16 v[98:113], v[166:169], v[126:129], v[98:113]
	ds_read_b128 v[166:169], v217 offset:0
	v_mfma_f32_32x32x16_bf16 v[82:97], v[170:173], v[126:129], v[82:97]
	ds_read_b128 v[170:173], v217 offset:0x2000
	s_waitcnt lgkmcnt(4)
	v_mfma_f32_32x32x16_bf16 v[98:113], v[174:177], v[122:125], v[98:113]
	s_waitcnt lgkmcnt(2)
	v_mfma_f32_32x32x16_bf16 v[82:97], v[188:191], v[122:125], v[82:97]
	v_mfma_f32_32x32x16_bf16 v[98:113], v[162:165], v[118:121], v[98:113]
	s_waitcnt lgkmcnt(0)
	v_mfma_f32_32x32x16_bf16 v[82:97], v[192:195], v[118:121], v[82:97]
	v_mfma_f32_32x32x16_bf16 v[98:113], v[166:169], v[114:117], v[98:113]
	v_mfma_f32_32x32x16_bf16 v[82:97], v[170:173], v[114:117], v[82:97]
	s_nop 10
	v_max_f32_e32 v162, v98, v102
	v_max_f32_e32 v163, v99, v103
	v_max_f32_e32 v164, v101, v105
	v_max3_f32 v165, v100, v104, v108
	v_max3_f32 v164, v164, v109, v113
	v_max3_f32 v162, v162, v106, v110
	v_max3_f32 v163, v163, v107, v111
	v_max3_f32 v165, v165, v112, v84
	v_max3_f32 v164, v164, v85, v89
	v_max3_f32 v162, v162, v82, v86
	v_max3_f32 v163, v163, v83, v87
	v_max3_f32 v165, v165, v88, v92
	v_max3_f32 v164, v164, v93, v97
	v_max3_f32 v162, v162, v90, v94
	v_max3_f32 v163, v163, v91, v95
	v_max3_f32 v164, v165, v96, v164
	v_max3_f32 v162, v162, v163, v164
	v_mov_b32_e32 v163, v162
	s_nop 1
	v_permlane32_swap_b32_e32 v162, v163
	v_max_f32_e32 v162, v162, v163
	v_cmp_ge_f32_e32 vcc, s48, v162
	s_cmp_eq_u64 vcc, exec
	s_cbranch_scc0 .LBB0_435
	v_mov_b32_e32 v231, v227
	v_mov_b32_e32 v230, 1.0
; __device__ __forceinline__ void pv_d0(f32x16* o, int vb, bf16x8 pa0, bf16x8 pa1, bf16x8 pa2, bf16x8 pa3) {
;     ...
;   const s16x4 l0 = tr_read<v_rd_off(0, 0, 0)>(vb), h0 = tr_read<v_rd_off(0, 0, 1)>(vb);
;   const s16x4 l1 = tr_read<v_rd_off(0, 1, 0)>(vb), h1 = tr_read<v_rd_off(0, 1, 1)>(vb);
;   const s16x4 l2 = tr_read<v_rd_off(0, 2, 0)>(vb), h2 = tr_read<v_rd_off(0, 2, 1)>(vb);
;   const s16x4 l3 = tr_read<v_rd_off(0, 3, 0)>(vb), h3 = tr_read<v_rd_off(0, 3, 1)>(vb);
;   const s16x4 l4 = tr_read<v_rd_off(1, 0, 0)>(vb), h4 = tr_read<v_rd_off(1, 0, 1)>(vb);
;   asm volatile("s_waitcnt lgkmcnt(8)" ::: "memory"); SBAR();
;   o[0] = __builtin_amdgcn_mfma_f32_32x32x16_bf16(pa0, PK(l0, h0), o[0], 0, 0, 0);
;   const s16x4 l5 = tr_read<v_rd_off(1, 1, 0)>(vb), h5 = tr_read<v_rd_off(1, 1, 1)>(vb);
;   asm volatile("s_waitcnt lgkmcnt(8)" ::: "memory"); SBAR();
;   o[0] = __builtin_amdgcn_mfma_f32_32x32x16_bf16(pa1, PK(l1, h1), o[0], 0, 0, 0);
;   const s16x4 l6 = tr_read<v_rd_off(1, 2, 0)>(vb), h6 = tr_read<v_rd_off(1, 2, 1)>(vb);
;   asm volatile("s_waitcnt lgkmcnt(8)" ::: "memory"); SBAR();
;   o[0] = __builtin_amdgcn_mfma_f32_32x32x16_bf16(pa2, PK(l2, h2), o[0], 0, 0, 0);
;   const s16x4 l7 = tr_read<v_rd_off(1, 3, 0)>(vb), h7 = tr_read<v_rd_off(1, 3, 1)>(vb);
;   asm volatile("s_waitcnt lgkmcnt(8)" ::: "memory"); SBAR();
;   o[0] = __builtin_amdgcn_mfma_f32_32x32x16_bf16(pa3, PK(l3, h3), o[0], 0, 0, 0);
;   const s16x4 l8 = tr_read<v_rd_off(2, 0, 0)>(vb), h8 = tr_read<v_rd_off(2, 0, 1)>(vb);
;   asm volatile("s_waitcnt lgkmcnt(8)" ::: "memory"); SBAR();
;   o[1] = __builtin_amdgcn_mfma_f32_32x32x16_bf16(pa0, PK(l4, h4), o[1], 0, 0, 0);
;   const s16x4 l9 = tr_read<v_rd_off(2, 1, 0)>(vb), h9 = tr_read<v_rd_off(2, 1, 1)>(vb);
;   asm volatile("s_waitcnt lgkmcnt(8)" ::: "memory"); SBAR();
;   o[1] = __builtin_amdgcn_mfma_f32_32x32x16_bf16(pa1, PK(l5, h5), o[1], 0, 0, 0);
;   const s16x4 l10 = tr_read<v_rd_off(2, 2, 0)>(vb), h10 = tr_read<v_rd_off(2, 2, 1)>(vb);
;   asm volatile("s_waitcnt lgkmcnt(8)" ::: "memory"); SBAR();
;   o[1] = __builtin_amdgcn_mfma_f32_32x32x16_bf16(pa2, PK(l6, h6), o[1], 0, 0, 0);
;   const s16x4 l11 = tr_read<v_rd_off(2, 3, 0)>(vb), h11 = tr_read<v_rd_off(2, 3, 1)>(vb);
;   asm volatile("s_waitcnt lgkmcnt(8)" ::: "memory"); SBAR();
;   o[1] = __builtin_amdgcn_mfma_f32_32x32x16_bf16(pa3, PK(l7, h7), o[1], 0, 0, 0);
.LBB0_423:
	v_lshl_add_u64 v[188:189], v[186:187], 0, v[0:1]
	v_add_co_u32_e32 v162, vcc, s78, v188
	v_lshl_add_u64 v[190:191], v[184:185], 0, v[0:1]
	s_nop 0
	v_addc_co_u32_e32 v163, vcc, 0, v189, vcc
	v_add_co_u32_e32 v166, vcc, s79, v188
	s_nop 1
	v_addc_co_u32_e32 v167, vcc, 0, v189, vcc
	v_add_co_u32_e32 v170, vcc, s70, v190
	global_load_dwordx4 v[162:165], v[162:163], off offset:2176
	s_nop 0
	global_load_dwordx4 v[166:169], v[166:167], off offset:2176
	v_addc_co_u32_e32 v171, vcc, 0, v191, vcc
	v_add_co_u32_e32 v174, vcc, s71, v190
	s_nop 1
	v_addc_co_u32_e32 v175, vcc, 0, v191, vcc
	global_load_dwordx4 v[170:173], v[170:171], off
	s_nop 0
	global_load_dwordx4 v[174:177], v[174:175], off
	ds_read_b64_tr_b16 v[192:193], v199 offset:0
	ds_read_b64_tr_b16 v[194:195], v199 offset:0x800
	ds_read_b64_tr_b16 v[234:235], v199 offset:0x1000
	ds_read_b64_tr_b16 v[236:237], v199 offset:0x1800
	ds_read_b64_tr_b16 v[238:239], v199 offset:0x2000
	ds_read_b64_tr_b16 v[240:241], v199 offset:0x2800
	ds_read_b64_tr_b16 v[242:243], v199 offset:0x3000
	ds_read_b64_tr_b16 v[244:245], v199 offset:0x3800
	ds_read_b64_tr_b16 v[246:247], v199 offset:0x200
	ds_read_b64_tr_b16 v[248:249], v199 offset:0xa00
	s_waitcnt lgkmcnt(8)
	s_nop 0
	v_mfma_f32_32x32x16_bf16 v[2:17], v[146:149], v[192:195], v[2:17]
	ds_read_b64_tr_b16 v[192:193], v199 offset:0x1200
	ds_read_b64_tr_b16 v[194:195], v199 offset:0x1a00
	s_waitcnt lgkmcnt(8)
	v_mfma_f32_32x32x16_bf16 v[2:17], v[150:153], v[234:237], v[2:17]
	ds_read_b64_tr_b16 v[234:235], v199 offset:0x2200
	ds_read_b64_tr_b16 v[236:237], v199 offset:0x2a00
	s_waitcnt lgkmcnt(8)
	v_mfma_f32_32x32x16_bf16 v[2:17], v[158:161], v[238:241], v[2:17]
	ds_read_b64_tr_b16 v[238:239], v199 offset:0x3200
	ds_read_b64_tr_b16 v[240:241], v199 offset:0x3a00
	s_waitcnt lgkmcnt(8)
	v_mfma_f32_32x32x16_bf16 v[2:17], v[154:157], v[242:245], v[2:17]
	ds_read_b64_tr_b16 v[242:243], v199 offset:0x400
	ds_read_b64_tr_b16 v[244:245], v199 offset:0xc00
	s_waitcnt lgkmcnt(8)
	v_mfma_f32_32x32x16_bf16 v[50:65], v[146:149], v[246:249], v[50:65]
	ds_read_b64_tr_b16 v[246:247], v199 offset:0x1400
	ds_read_b64_tr_b16 v[248:249], v199 offset:0x1c00
	s_waitcnt lgkmcnt(8)
	v_mfma_f32_32x32x16_bf16 v[50:65], v[150:153], v[192:195], v[50:65]
	ds_read_b64_tr_b16 v[192:193], v199 offset:0x2400
	ds_read_b64_tr_b16 v[194:195], v199 offset:0x2c00
	s_waitcnt lgkmcnt(8)
	v_mfma_f32_32x32x16_bf16 v[50:65], v[158:161], v[234:237], v[50:65]
	ds_read_b64_tr_b16 v[234:235], v199 offset:0x3400
	ds_read_b64_tr_b16 v[236:237], v199 offset:0x3c00
	s_waitcnt lgkmcnt(8)
	v_mfma_f32_32x32x16_bf16 v[50:65], v[154:157], v[238:241], v[50:65]
	ds_read_b64_tr_b16 v[238:239], v199 offset:0x600
	ds_read_b64_tr_b16 v[240:241], v199 offset:0xe00
	s_waitcnt lgkmcnt(8)
	v_mfma_f32_32x32x16_bf16 v[34:49], v[146:149], v[242:245], v[34:49]
	ds_read_b64_tr_b16 v[242:243], v199 offset:0x1600
	ds_read_b64_tr_b16 v[244:245], v199 offset:0x1e00
	s_waitcnt lgkmcnt(8)
	v_mfma_f32_32x32x16_bf16 v[34:49], v[150:153], v[246:249], v[34:49]
	ds_read_b64_tr_b16 v[246:247], v199 offset:0x2600
	ds_read_b64_tr_b16 v[248:249], v199 offset:0x2e00
	s_waitcnt lgkmcnt(8)
	v_mfma_f32_32x32x16_bf16 v[34:49], v[158:161], v[192:195], v[34:49]
	ds_read_b64_tr_b16 v[192:193], v199 offset:0x3600
	ds_read_b64_tr_b16 v[194:195], v199 offset:0x3e00
	s_waitcnt lgkmcnt(8)
	v_mfma_f32_32x32x16_bf16 v[34:49], v[154:157], v[234:237], v[34:49]
	s_waitcnt lgkmcnt(6)
	v_mfma_f32_32x32x16_bf16 v[18:33], v[146:149], v[238:241], v[18:33]
	s_waitcnt lgkmcnt(4)
	v_mfma_f32_32x32x16_bf16 v[18:33], v[150:153], v[242:245], v[18:33]
	s_waitcnt lgkmcnt(2)
	v_mfma_f32_32x32x16_bf16 v[18:33], v[158:161], v[246:249], v[18:33]
	s_waitcnt lgkmcnt(0)
	v_mfma_f32_32x32x16_bf16 v[18:33], v[154:157], v[192:195], v[18:33]
	s_barrier
	s_waitcnt vmcnt(0)
	v_cmp_gt_f32_e32 vcc, 1.0, v230
	ds_write_b128 v201, v[162:165]
	ds_write_b128 v207, v[166:169]
	ds_write_b128 v208, v[170:173] offset:32768
	ds_write_b128 v209, v[174:177] offset:32768
	s_cbranch_vccz .LBB0_427
	s_and_saveexec_b64 s[10:11], s[4:5]
	ds_write_b32 v183, v230 offset:128
	s_or_b64 exec, exec, s[10:11]
	s_waitcnt lgkmcnt(0)
	ds_read_b128 v[146:149], v181 offset:224
	ds_read_b128 v[150:153], v181 offset:192
	ds_read_b128 v[154:157], v181 offset:160
	ds_read_b128 v[158:161], v181 offset:128
	s_waitcnt lgkmcnt(3)
	v_pk_mul_f32 v[16:17], v[16:17], v[148:149]
	s_waitcnt lgkmcnt(2)
	v_pk_mul_f32 v[12:13], v[12:13], v[152:153]
	s_waitcnt lgkmcnt(1)
	v_pk_mul_f32 v[8:9], v[8:9], v[156:157]
	s_waitcnt lgkmcnt(0)
	v_pk_mul_f32 v[4:5], v[4:5], v[160:161]
	v_pk_mul_f32 v[14:15], v[14:15], v[146:147]
	v_pk_mul_f32 v[10:11], v[10:11], v[150:151]
	v_pk_mul_f32 v[6:7], v[6:7], v[154:155]
	v_pk_mul_f32 v[2:3], v[2:3], v[158:159]
	v_pk_mul_f32 v[64:65], v[64:65], v[148:149]
	v_pk_mul_f32 v[60:61], v[60:61], v[152:153]
	v_pk_mul_f32 v[56:57], v[56:57], v[156:157]
	v_pk_mul_f32 v[52:53], v[52:53], v[160:161]
	v_pk_mul_f32 v[62:63], v[62:63], v[146:147]
	v_pk_mul_f32 v[58:59], v[58:59], v[150:151]
	v_pk_mul_f32 v[54:55], v[54:55], v[154:155]
	v_pk_mul_f32 v[50:51], v[50:51], v[158:159]
	v_pk_mul_f32 v[48:49], v[48:49], v[148:149]
	v_pk_mul_f32 v[44:45], v[44:45], v[152:153]
	v_pk_mul_f32 v[40:41], v[40:41], v[156:157]
	v_pk_mul_f32 v[36:37], v[36:37], v[160:161]
	v_pk_mul_f32 v[46:47], v[46:47], v[146:147]
	v_pk_mul_f32 v[42:43], v[42:43], v[150:151]
	v_pk_mul_f32 v[38:39], v[38:39], v[154:155]
	v_pk_mul_f32 v[34:35], v[34:35], v[158:159]
	v_pk_mul_f32 v[32:33], v[32:33], v[148:149]
	v_pk_mul_f32 v[28:29], v[28:29], v[152:153]
	v_pk_mul_f32 v[24:25], v[24:25], v[156:157]
	v_pk_mul_f32 v[20:21], v[20:21], v[160:161]
	v_pk_mul_f32 v[30:31], v[30:31], v[146:147]
	v_pk_mul_f32 v[26:27], v[26:27], v[150:151]
	v_pk_mul_f32 v[22:23], v[22:23], v[154:155]
	v_pk_mul_f32 v[18:19], v[18:19], v[158:159]
; template <bool EXP1 = true>
; __device__ __forceinline__ void finishSM(f32x16& p0, f32x16& p1, float alpha, float& l_reg, bf16x8& pa0, bf16x8& pa1, bf16x8& pa2, bf16x8& pa3) {
;   if constexpr (EXP1) {
; #pragma unroll
;   for (int r = 0; r < 16; ++r) p1[r] = __builtin_amdgcn_exp2f(p1[r]);
;   }
;   float sm_[4] = {p0[0], p0[1], p0[2], p0[3]};
; #pragma unroll
;   for (int r = 4; r < 16; ++r) sm_[r & 3] += p0[r];
; #pragma unroll
;   for (int r = 0; r < 16; ++r) sm_[r & 3] += p1[r];
;   float ps = (sm_[0] + sm_[1]) + (sm_[2] + sm_[3]);
;   { auto rr = __builtin_amdgcn_permlane32_swap(__float_as_uint(ps), __float_as_uint(ps), false, false);
;     ps = __uint_as_float(rr[0]) + __uint_as_float(rr[1]); }
;   l_reg = l_reg * alpha + ps;
;     ...
;   PK4(p0, 0, pa0); PK4(p0, 8, pa1); PK4(p1, 0, pa2); PK4(p1, 8, pa3);
; __device__ __forceinline__ void qkt8_roll(f32x16& p0, f32x16& p1, const f32x16& negm, int kb, const bf16x8* qr) {
;   const int a0 = kb ^ (0 << 5); const bf16x8 x0 = lds_rd128<0>(a0), y0 = lds_rd128<8192>(a0);
;   const int a1 = kb ^ (1 << 5); const bf16x8 x1 = lds_rd128<0>(a1), y1 = lds_rd128<8192>(a1);
;   const int a2 = kb ^ (2 << 5); const bf16x8 x2 = lds_rd128<0>(a2), y2 = lds_rd128<8192>(a2);
;   asm volatile("s_waitcnt lgkmcnt(4)" ::: "memory"); SBAR_M();
;   p0 = __builtin_amdgcn_mfma_f32_32x32x16_bf16(x0, qr[0], negm, 0, 0, 0); p1 = __builtin_amdgcn_mfma_f32_32x32x16_bf16(y0, qr[0], negm, 0, 0, 0);
;   const int a3 = kb ^ (3 << 5); const bf16x8 x3 = lds_rd128<0>(a3), y3 = lds_rd128<8192>(a3);
;   asm volatile("s_waitcnt lgkmcnt(4)" ::: "memory"); SBAR_M();
;   p0 = __builtin_amdgcn_mfma_f32_32x32x16_bf16(x1, qr[1], p0, 0, 0, 0); p1 = __builtin_amdgcn_mfma_f32_32x32x16_bf16(y1, qr[1], p1, 0, 0, 0);
;   const int a4 = kb ^ (4 << 5); const bf16x8 x4 = lds_rd128<0>(a4), y4 = lds_rd128<8192>(a4);
;   asm volatile("s_waitcnt lgkmcnt(4)" ::: "memory"); SBAR_M();
;   p0 = __builtin_amdgcn_mfma_f32_32x32x16_bf16(x2, qr[2], p0, 0, 0, 0); p1 = __builtin_amdgcn_mfma_f32_32x32x16_bf16(y2, qr[2], p1, 0, 0, 0);
;   const int a5 = kb ^ (5 << 5); const bf16x8 x5 = lds_rd128<0>(a5), y5 = lds_rd128<8192>(a5);
;   asm volatile("s_waitcnt lgkmcnt(4)" ::: "memory"); SBAR_M();
;   p0 = __builtin_amdgcn_mfma_f32_32x32x16_bf16(x3, qr[3], p0, 0, 0, 0); p1 = __builtin_amdgcn_mfma_f32_32x32x16_bf16(y3, qr[3], p1, 0, 0, 0);
.LBB0_427:
	v_exp_f32_e32 v146, v98
	v_exp_f32_e32 v153, v99
	v_exp_f32_e32 v147, v100
	v_exp_f32_e32 v152, v101
	v_exp_f32_e32 v148, v102
	v_exp_f32_e32 v151, v103
	v_exp_f32_e32 v149, v104
	v_exp_f32_e32 v150, v105
	v_exp_f32_e32 v103, v106
	v_exp_f32_e32 v105, v107
	v_exp_f32_e32 v101, v108
	v_exp_f32_e32 v104, v109
	v_exp_f32_e32 v99, v110
	v_exp_f32_e32 v102, v111
	v_exp_f32_e32 v98, v112
	v_exp_f32_e32 v100, v113
	v_xor_b32_e32 v106, 0x80000000, v227
	v_exp_f32_e32 v82, v82
	v_exp_f32_e32 v83, v83
	v_exp_f32_e32 v84, v84
	v_exp_f32_e32 v85, v85
	v_cndmask_b32_e64 v232, v106, v232, s[6:7]
	v_exp_f32_e32 v86, v86
	v_exp_f32_e32 v87, v87
	v_exp_f32_e32 v88, v88
	v_exp_f32_e32 v89, v89
	v_add_f32_e32 v106, v148, v146
	v_add_f32_e32 v107, v151, v153
	v_add_f32_e32 v108, v149, v147
	v_add_f32_e32 v109, v150, v152
	v_exp_f32_e32 v90, v90
	v_exp_f32_e32 v91, v91
	v_exp_f32_e32 v92, v92
	v_exp_f32_e32 v93, v93
	v_add_f32_e32 v106, v103, v106
	v_add_f32_e32 v107, v105, v107
	v_add_f32_e32 v108, v101, v108
	v_add_f32_e32 v109, v104, v109
	v_exp_f32_e32 v94, v94
	v_exp_f32_e32 v95, v95
	v_exp_f32_e32 v96, v96
	v_exp_f32_e32 v97, v97
	v_add_f32_e32 v106, v99, v106
	v_add_f32_e32 v107, v102, v107
	v_add_f32_e32 v108, v98, v108
	v_add_f32_e32 v109, v100, v109
	v_add_f32_e32 v106, v82, v106
	v_add_f32_e32 v107, v107, v83
	v_add_f32_e32 v108, v108, v84
	v_add_f32_e32 v109, v109, v85
	v_add_f32_e32 v106, v86, v106
	v_add_f32_e32 v107, v87, v107
	v_add_f32_e32 v108, v88, v108
	v_add_f32_e32 v109, v89, v109
	v_add_f32_e32 v106, v90, v106
	v_add_f32_e32 v107, v91, v107
	v_add_f32_e32 v108, v92, v108
	v_add_f32_e32 v109, v93, v109
	v_add_f32_e32 v106, v94, v106
	v_add_f32_e32 v107, v95, v107
	v_add_f32_e32 v108, v96, v108
	v_add_f32_e32 v109, v97, v109
	v_add_f32_e32 v106, v106, v107
	v_add_f32_e32 v107, v108, v109
	v_add_f32_e32 v233, v106, v107
	s_waitcnt lgkmcnt(0)
	s_barrier
	v_mov_b32_e32 v234, v233
	v_cvt_pk_bf16_f32 v146, v146, v153
	v_cvt_pk_bf16_f32 v147, v147, v152
	v_cvt_pk_bf16_f32 v148, v148, v151
	v_cvt_pk_bf16_f32 v149, v149, v150
	v_cvt_pk_bf16_f32 v150, v103, v105
	v_cvt_pk_bf16_f32 v151, v101, v104
	v_cvt_pk_bf16_f32 v152, v99, v102
	v_cvt_pk_bf16_f32 v153, v98, v100
	v_cvt_pk_bf16_f32 v158, v82, v83
	v_cvt_pk_bf16_f32 v159, v84, v85
	v_cvt_pk_bf16_f32 v160, v86, v87
	v_cvt_pk_bf16_f32 v161, v88, v89
	v_cvt_pk_bf16_f32 v154, v90, v91
	v_cvt_pk_bf16_f32 v155, v92, v93
	v_cvt_pk_bf16_f32 v156, v94, v95
	v_cvt_pk_bf16_f32 v157, v96, v97
	s_nop 1
	v_permlane32_swap_b32_e32 v233, v234
	v_permlane32_swap_b32_e32 v146, v148
	v_permlane32_swap_b32_e32 v147, v149
	v_permlane32_swap_b32_e32 v150, v152
	v_permlane32_swap_b32_e32 v151, v153
	v_permlane32_swap_b32_e32 v158, v160
	v_permlane32_swap_b32_e32 v159, v161
	v_permlane32_swap_b32_e32 v154, v156
	v_permlane32_swap_b32_e32 v155, v157
	v_cmp_neq_f32_e64 s[6:7], v232, -v231
	s_cmp_eq_u64 s[6:7], 0
	s_cselect_b64 s[6:7], -1, 0
	v_cndmask_b32_e64 v97, -v231, v81, s[6:7]
	v_cndmask_b32_e64 v96, -v231, v80, s[6:7]
	v_cndmask_b32_e64 v95, -v231, v79, s[6:7]
	v_cndmask_b32_e64 v94, -v231, v78, s[6:7]
	v_cndmask_b32_e64 v93, -v231, v77, s[6:7]
	v_cndmask_b32_e64 v92, -v231, v76, s[6:7]
	v_cndmask_b32_e64 v91, -v231, v75, s[6:7]
	v_cndmask_b32_e64 v90, -v231, v74, s[6:7]
	v_cndmask_b32_e64 v89, -v231, v73, s[6:7]
	v_cndmask_b32_e64 v88, -v231, v72, s[6:7]
	v_cndmask_b32_e64 v87, -v231, v71, s[6:7]
	v_cndmask_b32_e64 v86, -v231, v70, s[6:7]
	v_cndmask_b32_e64 v85, -v231, v69, s[6:7]
	v_cndmask_b32_e64 v84, -v231, v68, s[6:7]
	v_cndmask_b32_e64 v83, -v231, v67, s[6:7]
	v_cndmask_b32_e64 v82, -v231, v66, s[6:7]
	ds_read_b128 v[66:69], v200 offset:0
	ds_read_b128 v[162:165], v200 offset:0x2000
	ds_read_b128 v[166:169], v210 offset:0
	ds_read_b128 v[170:173], v210 offset:0x2000
	ds_read_b128 v[174:177], v211 offset:0
	ds_read_b128 v[192:195], v211 offset:0x2000
	s_waitcnt lgkmcnt(4)
	s_nop 1
	v_mfma_f32_32x32x16_bf16 v[98:113], v[66:69], v[142:145], v[82:97]
	v_mfma_f32_32x32x16_bf16 v[66:81], v[162:165], v[142:145], v[82:97]
	ds_read_b128 v[162:165], v212 offset:0
	ds_read_b128 v[236:239], v212 offset:0x2000
	s_waitcnt lgkmcnt(4)
	v_mfma_f32_32x32x16_bf16 v[98:113], v[166:169], v[138:141], v[98:113]
	ds_read_b128 v[166:169], v213 offset:0
	v_mfma_f32_32x32x16_bf16 v[66:81], v[170:173], v[138:141], v[66:81]
	ds_read_b128 v[170:173], v213 offset:0x2000
	s_waitcnt lgkmcnt(4)
	v_mfma_f32_32x32x16_bf16 v[98:113], v[174:177], v[134:137], v[98:113]
	ds_read_b128 v[174:177], v214 offset:0
	v_mfma_f32_32x32x16_bf16 v[66:81], v[192:195], v[134:137], v[66:81]
	ds_read_b128 v[192:195], v214 offset:0x2000
	s_waitcnt lgkmcnt(4)
	v_mfma_f32_32x32x16_bf16 v[98:113], v[162:165], v[130:133], v[98:113]
	ds_read_b128 v[162:165], v215 offset:0
	v_mfma_f32_32x32x16_bf16 v[66:81], v[236:239], v[130:133], v[66:81]
	ds_read_b128 v[236:239], v215 offset:0x2000
	s_waitcnt lgkmcnt(4)
	v_mfma_f32_32x32x16_bf16 v[98:113], v[166:169], v[126:129], v[98:113]
	ds_read_b128 v[166:169], v216 offset:0
	v_mfma_f32_32x32x16_bf16 v[66:81], v[170:173], v[126:129], v[66:81]
	ds_read_b128 v[170:173], v216 offset:0x2000
	s_waitcnt lgkmcnt(4)
	v_mfma_f32_32x32x16_bf16 v[98:113], v[174:177], v[122:125], v[98:113]
	s_waitcnt lgkmcnt(2)
	v_mfma_f32_32x32x16_bf16 v[66:81], v[192:195], v[122:125], v[66:81]
	v_mfma_f32_32x32x16_bf16 v[98:113], v[162:165], v[118:121], v[98:113]
	s_waitcnt lgkmcnt(0)
	v_mfma_f32_32x32x16_bf16 v[66:81], v[236:239], v[118:121], v[66:81]
	v_mfma_f32_32x32x16_bf16 v[98:113], v[166:169], v[114:117], v[98:113]
	v_mfma_f32_32x32x16_bf16 v[66:81], v[170:173], v[114:117], v[66:81]
	s_nop 10
	v_max_f32_e32 v162, v98, v102
	v_max_f32_e32 v163, v99, v103
	v_max_f32_e32 v164, v101, v105
	v_max3_f32 v165, v100, v104, v108
	v_max3_f32 v164, v164, v109, v113
	v_max3_f32 v162, v162, v106, v110
	v_max3_f32 v163, v163, v107, v111
	v_max3_f32 v165, v165, v112, v68
	v_max3_f32 v164, v164, v69, v73
	v_max3_f32 v162, v162, v66, v70
	v_max3_f32 v163, v163, v67, v71
	v_max3_f32 v165, v165, v72, v76
	v_max3_f32 v164, v164, v77, v81
	v_max3_f32 v162, v162, v74, v78
	v_max3_f32 v163, v163, v75, v79
	v_max3_f32 v164, v165, v80, v164
	v_max3_f32 v162, v162, v163, v164
	v_mov_b32_e32 v163, v162
	s_nop 1
	v_permlane32_swap_b32_e32 v162, v163
	v_max_f32_e32 v162, v162, v163
	v_cmp_ge_f32_e32 vcc, s48, v162
	s_cmp_eq_u64 vcc, exec
	v_mov_b32_e32 v226, 1.0
	s_cbranch_scc0 .LBB0_436
	v_mov_b32_e32 v227, v231
; __device__ __forceinline__ void pv_d0(f32x16* o, int vb, bf16x8 pa0, bf16x8 pa1, bf16x8 pa2, bf16x8 pa3) {
;     ...
;   const s16x4 l0 = tr_read<v_rd_off(0, 0, 0)>(vb), h0 = tr_read<v_rd_off(0, 0, 1)>(vb);
;   const s16x4 l1 = tr_read<v_rd_off(0, 1, 0)>(vb), h1 = tr_read<v_rd_off(0, 1, 1)>(vb);
;   const s16x4 l2 = tr_read<v_rd_off(0, 2, 0)>(vb), h2 = tr_read<v_rd_off(0, 2, 1)>(vb);
;   const s16x4 l3 = tr_read<v_rd_off(0, 3, 0)>(vb), h3 = tr_read<v_rd_off(0, 3, 1)>(vb);
;   const s16x4 l4 = tr_read<v_rd_off(1, 0, 0)>(vb), h4 = tr_read<v_rd_off(1, 0, 1)>(vb);
;   asm volatile("s_waitcnt lgkmcnt(8)" ::: "memory"); SBAR();
;   o[0] = __builtin_amdgcn_mfma_f32_32x32x16_bf16(pa0, PK(l0, h0), o[0], 0, 0, 0);
;   const s16x4 l5 = tr_read<v_rd_off(1, 1, 0)>(vb), h5 = tr_read<v_rd_off(1, 1, 1)>(vb);
;   asm volatile("s_waitcnt lgkmcnt(8)" ::: "memory"); SBAR();
;   o[0] = __builtin_amdgcn_mfma_f32_32x32x16_bf16(pa1, PK(l1, h1), o[0], 0, 0, 0);
;   const s16x4 l6 = tr_read<v_rd_off(1, 2, 0)>(vb), h6 = tr_read<v_rd_off(1, 2, 1)>(vb);
;   asm volatile("s_waitcnt lgkmcnt(8)" ::: "memory"); SBAR();
;   o[0] = __builtin_amdgcn_mfma_f32_32x32x16_bf16(pa2, PK(l2, h2), o[0], 0, 0, 0);
;   const s16x4 l7 = tr_read<v_rd_off(1, 3, 0)>(vb), h7 = tr_read<v_rd_off(1, 3, 1)>(vb);
;   asm volatile("s_waitcnt lgkmcnt(8)" ::: "memory"); SBAR();
;   o[0] = __builtin_amdgcn_mfma_f32_32x32x16_bf16(pa3, PK(l3, h3), o[0], 0, 0, 0);
;   const s16x4 l8 = tr_read<v_rd_off(2, 0, 0)>(vb), h8 = tr_read<v_rd_off(2, 0, 1)>(vb);
;   asm volatile("s_waitcnt lgkmcnt(8)" ::: "memory"); SBAR();
;   o[1] = __builtin_amdgcn_mfma_f32_32x32x16_bf16(pa0, PK(l4, h4), o[1], 0, 0, 0);
;   const s16x4 l9 = tr_read<v_rd_off(2, 1, 0)>(vb), h9 = tr_read<v_rd_off(2, 1, 1)>(vb);
;   asm volatile("s_waitcnt lgkmcnt(8)" ::: "memory"); SBAR();
;   o[1] = __builtin_amdgcn_mfma_f32_32x32x16_bf16(pa1, PK(l5, h5), o[1], 0, 0, 0);
;   const s16x4 l10 = tr_read<v_rd_off(2, 2, 0)>(vb), h10 = tr_read<v_rd_off(2, 2, 1)>(vb);
;   asm volatile("s_waitcnt lgkmcnt(8)" ::: "memory"); SBAR();
;   o[1] = __builtin_amdgcn_mfma_f32_32x32x16_bf16(pa2, PK(l6, h6), o[1], 0, 0, 0);
;   const s16x4 l11 = tr_read<v_rd_off(2, 3, 0)>(vb), h11 = tr_read<v_rd_off(2, 3, 1)>(vb);
;   asm volatile("s_waitcnt lgkmcnt(8)" ::: "memory"); SBAR();
;   o[1] = __builtin_amdgcn_mfma_f32_32x32x16_bf16(pa3, PK(l7, h7), o[1], 0, 0, 0);
.LBB0_429:
	v_add_co_u32_e32 v162, vcc, s72, v188
	s_nop 1
	v_addc_co_u32_e32 v163, vcc, 0, v189, vcc
	v_add_co_u32_e32 v166, vcc, s73, v188
	s_nop 1
	v_addc_co_u32_e32 v167, vcc, 0, v189, vcc
	v_add_co_u32_e32 v170, vcc, s33, v190
	global_load_dwordx4 v[162:165], v[162:163], off offset:2176
	s_nop 0
	global_load_dwordx4 v[166:169], v[166:167], off offset:2176
	v_addc_co_u32_e32 v171, vcc, 0, v191, vcc
	v_add_co_u32_e32 v174, vcc, s52, v190
	s_nop 1
	v_addc_co_u32_e32 v175, vcc, 0, v191, vcc
	global_load_dwordx4 v[170:173], v[170:171], off
	s_nop 0
	global_load_dwordx4 v[174:177], v[174:175], off
	ds_read_b64_tr_b16 v[188:189], v198 offset:0
	ds_read_b64_tr_b16 v[190:191], v198 offset:0x800
	ds_read_b64_tr_b16 v[192:193], v198 offset:0x1000
	ds_read_b64_tr_b16 v[194:195], v198 offset:0x1800
	ds_read_b64_tr_b16 v[236:237], v198 offset:0x2000
	ds_read_b64_tr_b16 v[238:239], v198 offset:0x2800
	ds_read_b64_tr_b16 v[240:241], v198 offset:0x3000
	ds_read_b64_tr_b16 v[242:243], v198 offset:0x3800
	ds_read_b64_tr_b16 v[244:245], v198 offset:0x200
	ds_read_b64_tr_b16 v[246:247], v198 offset:0xa00
	s_waitcnt lgkmcnt(8)
	s_nop 0
	v_mfma_f32_32x32x16_bf16 v[2:17], v[146:149], v[188:191], v[2:17]
	ds_read_b64_tr_b16 v[188:189], v198 offset:0x1200
	ds_read_b64_tr_b16 v[190:191], v198 offset:0x1a00
	s_waitcnt lgkmcnt(8)
	v_mfma_f32_32x32x16_bf16 v[2:17], v[150:153], v[192:195], v[2:17]
	ds_read_b64_tr_b16 v[192:193], v198 offset:0x2200
	ds_read_b64_tr_b16 v[194:195], v198 offset:0x2a00
	s_waitcnt lgkmcnt(8)
	v_mfma_f32_32x32x16_bf16 v[2:17], v[158:161], v[236:239], v[2:17]
	ds_read_b64_tr_b16 v[236:237], v198 offset:0x3200
	ds_read_b64_tr_b16 v[238:239], v198 offset:0x3a00
	s_waitcnt lgkmcnt(8)
	v_mfma_f32_32x32x16_bf16 v[2:17], v[154:157], v[240:243], v[2:17]
	ds_read_b64_tr_b16 v[240:241], v198 offset:0x400
	ds_read_b64_tr_b16 v[242:243], v198 offset:0xc00
	s_waitcnt lgkmcnt(8)
	v_mfma_f32_32x32x16_bf16 v[50:65], v[146:149], v[244:247], v[50:65]
	ds_read_b64_tr_b16 v[244:245], v198 offset:0x1400
	ds_read_b64_tr_b16 v[246:247], v198 offset:0x1c00
	s_waitcnt lgkmcnt(8)
	v_mfma_f32_32x32x16_bf16 v[50:65], v[150:153], v[188:191], v[50:65]
	ds_read_b64_tr_b16 v[188:189], v198 offset:0x2400
	ds_read_b64_tr_b16 v[190:191], v198 offset:0x2c00
	s_waitcnt lgkmcnt(8)
	v_mfma_f32_32x32x16_bf16 v[50:65], v[158:161], v[192:195], v[50:65]
	ds_read_b64_tr_b16 v[192:193], v198 offset:0x3400
	ds_read_b64_tr_b16 v[194:195], v198 offset:0x3c00
	s_waitcnt lgkmcnt(8)
	v_mfma_f32_32x32x16_bf16 v[50:65], v[154:157], v[236:239], v[50:65]
	ds_read_b64_tr_b16 v[236:237], v198 offset:0x600
	ds_read_b64_tr_b16 v[238:239], v198 offset:0xe00
	s_waitcnt lgkmcnt(8)
	v_mfma_f32_32x32x16_bf16 v[34:49], v[146:149], v[240:243], v[34:49]
	ds_read_b64_tr_b16 v[240:241], v198 offset:0x1600
	ds_read_b64_tr_b16 v[242:243], v198 offset:0x1e00
	s_waitcnt lgkmcnt(8)
	v_mfma_f32_32x32x16_bf16 v[34:49], v[150:153], v[244:247], v[34:49]
	ds_read_b64_tr_b16 v[244:245], v198 offset:0x2600
	ds_read_b64_tr_b16 v[246:247], v198 offset:0x2e00
	s_waitcnt lgkmcnt(8)
	v_mfma_f32_32x32x16_bf16 v[34:49], v[158:161], v[188:191], v[34:49]
	ds_read_b64_tr_b16 v[188:189], v198 offset:0x3600
	ds_read_b64_tr_b16 v[190:191], v198 offset:0x3e00
	s_waitcnt lgkmcnt(8)
	v_mfma_f32_32x32x16_bf16 v[34:49], v[154:157], v[192:195], v[34:49]
	s_waitcnt lgkmcnt(6)
	v_mfma_f32_32x32x16_bf16 v[18:33], v[146:149], v[236:239], v[18:33]
	s_waitcnt lgkmcnt(4)
	v_mfma_f32_32x32x16_bf16 v[18:33], v[150:153], v[240:243], v[18:33]
	s_waitcnt lgkmcnt(2)
	v_mfma_f32_32x32x16_bf16 v[18:33], v[158:161], v[244:247], v[18:33]
	s_waitcnt lgkmcnt(0)
	v_mfma_f32_32x32x16_bf16 v[18:33], v[154:157], v[188:191], v[18:33]
	s_barrier
	s_waitcnt vmcnt(0)
	v_cmp_gt_f32_e32 vcc, 1.0, v226
	ds_write_b128 v201, v[162:165] offset:16384
	ds_write_b128 v207, v[166:169] offset:16384
	ds_write_b128 v208, v[170:173] offset:49152
	ds_write_b128 v209, v[174:177] offset:49152
	s_cbranch_vccz .LBB0_433
	s_and_saveexec_b64 s[10:11], s[4:5]
	ds_write_b32 v183, v226 offset:128
	s_or_b64 exec, exec, s[10:11]
	s_waitcnt lgkmcnt(0)
	ds_read_b128 v[146:149], v181 offset:224
	ds_read_b128 v[150:153], v181 offset:192
	ds_read_b128 v[154:157], v181 offset:160
	ds_read_b128 v[158:161], v181 offset:128
	s_waitcnt lgkmcnt(3)
	v_pk_mul_f32 v[16:17], v[16:17], v[148:149]
	s_waitcnt lgkmcnt(2)
	v_pk_mul_f32 v[12:13], v[12:13], v[152:153]
	s_waitcnt lgkmcnt(1)
	v_pk_mul_f32 v[8:9], v[8:9], v[156:157]
	s_waitcnt lgkmcnt(0)
	v_pk_mul_f32 v[4:5], v[4:5], v[160:161]
	v_pk_mul_f32 v[14:15], v[14:15], v[146:147]
	v_pk_mul_f32 v[10:11], v[10:11], v[150:151]
	v_pk_mul_f32 v[6:7], v[6:7], v[154:155]
	v_pk_mul_f32 v[2:3], v[2:3], v[158:159]
	v_pk_mul_f32 v[64:65], v[64:65], v[148:149]
	v_pk_mul_f32 v[60:61], v[60:61], v[152:153]
	v_pk_mul_f32 v[56:57], v[56:57], v[156:157]
	v_pk_mul_f32 v[52:53], v[52:53], v[160:161]
	v_pk_mul_f32 v[62:63], v[62:63], v[146:147]
	v_pk_mul_f32 v[58:59], v[58:59], v[150:151]
	v_pk_mul_f32 v[54:55], v[54:55], v[154:155]
	v_pk_mul_f32 v[50:51], v[50:51], v[158:159]
	v_pk_mul_f32 v[48:49], v[48:49], v[148:149]
	v_pk_mul_f32 v[44:45], v[44:45], v[152:153]
	v_pk_mul_f32 v[40:41], v[40:41], v[156:157]
	v_pk_mul_f32 v[36:37], v[36:37], v[160:161]
	v_pk_mul_f32 v[46:47], v[46:47], v[146:147]
	v_pk_mul_f32 v[42:43], v[42:43], v[150:151]
	v_pk_mul_f32 v[38:39], v[38:39], v[154:155]
	v_pk_mul_f32 v[34:35], v[34:35], v[158:159]
	v_pk_mul_f32 v[32:33], v[32:33], v[148:149]
	v_pk_mul_f32 v[28:29], v[28:29], v[152:153]
	v_pk_mul_f32 v[24:25], v[24:25], v[156:157]
	v_pk_mul_f32 v[20:21], v[20:21], v[160:161]
	v_pk_mul_f32 v[30:31], v[30:31], v[146:147]
	v_pk_mul_f32 v[26:27], v[26:27], v[150:151]
	v_pk_mul_f32 v[22:23], v[22:23], v[154:155]
	v_pk_mul_f32 v[18:19], v[18:19], v[158:159]

; __device__ __forceinline__ void qkt8_roll(f32x16& p0, f32x16& p1, const f32x16& negm, int kb, const bf16x8* qr) {
;   const int a0 = kb ^ (0 << 5); const bf16x8 x0 = lds_rd128<0>(a0), y0 = lds_rd128<8192>(a0);
;   const int a1 = kb ^ (1 << 5); const bf16x8 x1 = lds_rd128<0>(a1), y1 = lds_rd128<8192>(a1);
;   const int a2 = kb ^ (2 << 5); const bf16x8 x2 = lds_rd128<0>(a2), y2 = lds_rd128<8192>(a2);
;   asm volatile("s_waitcnt lgkmcnt(4)" ::: "memory"); SBAR_M();
;   p0 = __builtin_amdgcn_mfma_f32_32x32x16_bf16(x0, qr[0], negm, 0, 0, 0); p1 = __builtin_amdgcn_mfma_f32_32x32x16_bf16(y0, qr[0], negm, 0, 0, 0);
;   const int a3 = kb ^ (3 << 5); const bf16x8 x3 = lds_rd128<0>(a3), y3 = lds_rd128<8192>(a3);
;   asm volatile("s_waitcnt lgkmcnt(4)" ::: "memory"); SBAR_M();
;   p0 = __builtin_amdgcn_mfma_f32_32x32x16_bf16(x1, qr[1], p0, 0, 0, 0); p1 = __builtin_amdgcn_mfma_f32_32x32x16_bf16(y1, qr[1], p1, 0, 0, 0);
;   const int a4 = kb ^ (4 << 5); const bf16x8 x4 = lds_rd128<0>(a4), y4 = lds_rd128<8192>(a4);
;   asm volatile("s_waitcnt lgkmcnt(4)" ::: "memory"); SBAR_M();
;   p0 = __builtin_amdgcn_mfma_f32_32x32x16_bf16(x2, qr[2], p0, 0, 0, 0); p1 = __builtin_amdgcn_mfma_f32_32x32x16_bf16(y2, qr[2], p1, 0, 0, 0);
;   const int a5 = kb ^ (5 << 5); const bf16x8 x5 = lds_rd128<0>(a5), y5 = lds_rd128<8192>(a5);
;   asm volatile("s_waitcnt lgkmcnt(4)" ::: "memory"); SBAR_M();
;   p0 = __builtin_amdgcn_mfma_f32_32x32x16_bf16(x3, qr[3], p0, 0, 0, 0); p1 = __builtin_amdgcn_mfma_f32_32x32x16_bf16(y3, qr[3], p1, 0, 0, 0);
;   const int a6 = kb ^ (6 << 5); const bf16x8 x6 = lds_rd128<0>(a6), y6 = lds_rd128<8192>(a6);
;   asm volatile("s_waitcnt lgkmcnt(4)" ::: "memory"); SBAR_M();
;   p0 = __builtin_amdgcn_mfma_f32_32x32x16_bf16(x4, qr[4], p0, 0, 0, 0); p1 = __builtin_amdgcn_mfma_f32_32x32x16_bf16(y4, qr[4], p1, 0, 0, 0);
;   const int a7 = kb ^ (7 << 5); const bf16x8 x7 = lds_rd128<0>(a7), y7 = lds_rd128<8192>(a7);
;   asm volatile("s_waitcnt lgkmcnt(4)" ::: "memory"); SBAR_M();
;   p0 = __builtin_amdgcn_mfma_f32_32x32x16_bf16(x5, qr[5], p0, 0, 0, 0); p1 = __builtin_amdgcn_mfma_f32_32x32x16_bf16(y5, qr[5], p1, 0, 0, 0);
;   asm volatile("s_waitcnt lgkmcnt(2)" ::: "memory"); SBAR_M();
;   p0 = __builtin_amdgcn_mfma_f32_32x32x16_bf16(x6, qr[6], p0, 0, 0, 0); p1 = __builtin_amdgcn_mfma_f32_32x32x16_bf16(y6, qr[6], p1, 0, 0, 0);
.LBB0_447:
	v_cmp_neq_f32_e64 s[6:7], v231, -v228
	s_cmp_eq_u64 s[6:7], 0
	s_cselect_b64 s[6:7], -1, 0
	v_cndmask_b32_e64 v97, -v228, v97, s[6:7]
	v_cndmask_b32_e64 v96, -v228, v96, s[6:7]
	v_cndmask_b32_e64 v95, -v228, v95, s[6:7]
	v_cndmask_b32_e64 v94, -v228, v94, s[6:7]
	v_cndmask_b32_e64 v93, -v228, v93, s[6:7]
	v_cndmask_b32_e64 v92, -v228, v92, s[6:7]
	v_cndmask_b32_e64 v91, -v228, v91, s[6:7]
	v_cndmask_b32_e64 v90, -v228, v90, s[6:7]
	v_cndmask_b32_e64 v89, -v228, v89, s[6:7]
	v_cndmask_b32_e64 v88, -v228, v88, s[6:7]
	v_cndmask_b32_e64 v87, -v228, v87, s[6:7]
	v_cndmask_b32_e64 v86, -v228, v86, s[6:7]
	v_cndmask_b32_e64 v85, -v228, v85, s[6:7]
	v_cndmask_b32_e64 v84, -v228, v84, s[6:7]
	v_cndmask_b32_e64 v83, -v228, v83, s[6:7]
	v_cndmask_b32_e64 v82, -v228, v82, s[6:7]
	ds_read_b128 v[98:101], v224 offset:0
	ds_read_b128 v[232:235], v224 offset:0x2000
	ds_read_b128 v[236:239], v223 offset:0
	ds_read_b128 v[240:243], v223 offset:0x2000
	ds_read_b128 v[244:247], v222 offset:0
	ds_read_b128 v[248:251], v222 offset:0x2000
	s_waitcnt lgkmcnt(4)
	s_nop 1
	v_mfma_f32_32x32x16_bf16 v[114:129], v[98:101], v[158:161], v[82:97]
	v_mfma_f32_32x32x16_bf16 v[98:113], v[232:235], v[158:161], v[82:97]
	ds_read_b128 v[232:235], v221 offset:0
	ds_read_b128 v[190:193], v221 offset:0x2000
	s_waitcnt lgkmcnt(4)
	v_mfma_f32_32x32x16_bf16 v[114:129], v[236:239], v[154:157], v[114:129]
	ds_read_b128 v[236:239], v220 offset:0
	v_mfma_f32_32x32x16_bf16 v[98:113], v[240:243], v[154:157], v[98:113]
	ds_read_b128 v[240:243], v220 offset:0x2000
	s_waitcnt lgkmcnt(4)
	v_mfma_f32_32x32x16_bf16 v[114:129], v[244:247], v[150:153], v[114:129]
	ds_read_b128 v[244:247], v219 offset:0
	v_mfma_f32_32x32x16_bf16 v[98:113], v[248:251], v[150:153], v[98:113]
	ds_read_b128 v[248:251], v219 offset:0x2000
	s_waitcnt lgkmcnt(4)
	v_mfma_f32_32x32x16_bf16 v[114:129], v[232:235], v[146:149], v[114:129]
	v_mfma_f32_32x32x16_bf16 v[98:113], v[190:193], v[146:149], v[98:113]
	ds_read_b128 v[190:193], v218 offset:0
	ds_read_b128 v[232:235], v218 offset:0x2000
	s_waitcnt lgkmcnt(4)
	v_mfma_f32_32x32x16_bf16 v[114:129], v[236:239], v[142:145], v[114:129]
	ds_read_b128 v[236:239], v217 offset:0
	v_mfma_f32_32x32x16_bf16 v[98:113], v[240:243], v[142:145], v[98:113]
	ds_read_b128 v[240:243], v217 offset:0x2000
	s_waitcnt lgkmcnt(4)
	v_mfma_f32_32x32x16_bf16 v[114:129], v[244:247], v[138:141], v[114:129]
	s_waitcnt lgkmcnt(2)
	v_mfma_f32_32x32x16_bf16 v[98:113], v[248:251], v[138:141], v[98:113]
	v_mfma_f32_32x32x16_bf16 v[114:129], v[190:193], v[134:137], v[114:129]
	s_waitcnt lgkmcnt(0)
	v_mfma_f32_32x32x16_bf16 v[98:113], v[232:235], v[134:137], v[98:113]
	v_exp_f32_e32 v66, v66
	v_exp_f32_e32 v67, v67
	v_exp_f32_e32 v68, v68
	v_exp_f32_e32 v69, v69
	v_exp_f32_e32 v70, v70
	v_exp_f32_e32 v71, v71
	v_exp_f32_e32 v72, v72
	v_exp_f32_e32 v73, v73
	v_add_f32_e32 v162, v164, v176
	v_add_f32_e32 v189, v175, v188
	v_add_f32_e32 v190, v165, v163
	v_add_f32_e32 v191, v174, v177
	v_exp_f32_e32 v74, v74
	v_exp_f32_e32 v75, v75
	v_exp_f32_e32 v76, v76
	v_exp_f32_e32 v77, v77
	v_add_f32_e32 v162, v166, v162
	v_add_f32_e32 v189, v173, v189
	v_add_f32_e32 v190, v167, v190
	v_add_f32_e32 v191, v172, v191
	v_exp_f32_e32 v78, v78
	v_exp_f32_e32 v79, v79
	v_exp_f32_e32 v80, v80
	v_exp_f32_e32 v81, v81
	v_add_f32_e32 v162, v168, v162
	v_add_f32_e32 v189, v171, v189
	v_add_f32_e32 v190, v169, v190
	v_add_f32_e32 v191, v170, v191
	v_mfma_f32_32x32x16_bf16 v[114:129], v[236:239], v[130:133], v[114:129]
	v_add_f32_e32 v162, v66, v162
	v_add_f32_e32 v189, v67, v189
	v_add_f32_e32 v190, v68, v190
	v_add_f32_e32 v191, v69, v191
	v_add_f32_e32 v162, v70, v162
	v_add_f32_e32 v189, v71, v189
	v_add_f32_e32 v190, v72, v190
	v_mfma_f32_32x32x16_bf16 v[98:113], v[240:243], v[130:133], v[98:113]
	v_add_f32_e32 v191, v73, v191
	v_add_f32_e32 v162, v74, v162
	v_add_f32_e32 v189, v75, v189
	v_add_f32_e32 v190, v76, v190
	v_add_f32_e32 v191, v77, v191
	v_add_f32_e32 v162, v78, v162
	v_add_f32_e32 v189, v79, v189
	v_add_f32_e32 v190, v80, v190
	v_add_f32_e32 v191, v81, v191
	v_add_f32_e32 v162, v162, v189
	v_add_f32_e32 v189, v190, v191
	v_add_f32_e32 v226, v162, v189
	v_mov_b32_e32 v227, v226
	v_cvt_pk_bf16_f32 v162, v176, v188
	v_cvt_pk_bf16_f32 v163, v163, v177
	v_cvt_pk_bf16_f32 v164, v164, v175
	s_nop 1
	v_permlane32_swap_b32_e32 v226, v227
	v_cvt_pk_bf16_f32 v165, v165, v174
	v_permlane32_swap_b32_e32 v162, v164
	v_cvt_pk_bf16_f32 v166, v166, v173
	v_cvt_pk_bf16_f32 v167, v167, v172
	v_cvt_pk_bf16_f32 v168, v168, v171
	v_cvt_pk_bf16_f32 v169, v169, v170
	v_cvt_pk_bf16_f32 v170, v66, v67
	v_cvt_pk_bf16_f32 v171, v68, v69
	v_cvt_pk_bf16_f32 v172, v70, v71
	v_cvt_pk_bf16_f32 v173, v72, v73
	v_cvt_pk_bf16_f32 v174, v74, v75
	v_cvt_pk_bf16_f32 v175, v76, v77
	v_cvt_pk_bf16_f32 v176, v78, v79
	v_cvt_pk_bf16_f32 v177, v80, v81
	v_permlane32_swap_b32_e32 v163, v165
	v_permlane32_swap_b32_e32 v166, v168
	v_permlane32_swap_b32_e32 v167, v169
	v_permlane32_swap_b32_e32 v170, v172
	v_permlane32_swap_b32_e32 v171, v173
	v_permlane32_swap_b32_e32 v174, v176
	v_permlane32_swap_b32_e32 v175, v177
	v_lshl_add_u64 v[188:189], v[186:187], 0, v[0:1]
	v_add_co_u32_e32 v66, vcc, s78, v188
	v_lshl_add_u64 v[190:191], v[184:185], 0, v[0:1]
	s_nop 0
	v_addc_co_u32_e32 v67, vcc, 0, v189, vcc
	v_add_co_u32_e32 v70, vcc, s79, v188
	s_nop 1
	v_addc_co_u32_e32 v71, vcc, 0, v189, vcc
	v_add_co_u32_e32 v74, vcc, s70, v190
	global_load_dwordx4 v[66:69], v[66:67], off offset:2176
	s_nop 0
	global_load_dwordx4 v[70:73], v[70:71], off offset:2176
	v_addc_co_u32_e32 v75, vcc, 0, v191, vcc
	v_add_co_u32_e32 v78, vcc, s71, v190
	s_nop 1
	v_addc_co_u32_e32 v79, vcc, 0, v191, vcc
	global_load_dwordx4 v[74:77], v[74:75], off
	s_nop 0
	global_load_dwordx4 v[78:81], v[78:79], off
	ds_read_b64_tr_b16 v[232:233], v199 offset:0
	ds_read_b64_tr_b16 v[234:235], v199 offset:0x800
	ds_read_b64_tr_b16 v[236:237], v199 offset:0x1000
	ds_read_b64_tr_b16 v[238:239], v199 offset:0x1800
	ds_read_b64_tr_b16 v[240:241], v199 offset:0x2000
	ds_read_b64_tr_b16 v[242:243], v199 offset:0x2800
	ds_read_b64_tr_b16 v[244:245], v199 offset:0x3000
	ds_read_b64_tr_b16 v[246:247], v199 offset:0x3800
	ds_read_b64_tr_b16 v[248:249], v199 offset:0x200
	ds_read_b64_tr_b16 v[250:251], v199 offset:0xa00
	s_waitcnt lgkmcnt(8)
; __device__ __forceinline__ void pv_d0(f32x16* o, int vb, bf16x8 pa0, bf16x8 pa1, bf16x8 pa2, bf16x8 pa3) {
;     ...
;   const s16x4 l0 = tr_read<v_rd_off(0, 0, 0)>(vb), h0 = tr_read<v_rd_off(0, 0, 1)>(vb);
;   const s16x4 l1 = tr_read<v_rd_off(0, 1, 0)>(vb), h1 = tr_read<v_rd_off(0, 1, 1)>(vb);
;   const s16x4 l2 = tr_read<v_rd_off(0, 2, 0)>(vb), h2 = tr_read<v_rd_off(0, 2, 1)>(vb);
;   const s16x4 l3 = tr_read<v_rd_off(0, 3, 0)>(vb), h3 = tr_read<v_rd_off(0, 3, 1)>(vb);
;   const s16x4 l4 = tr_read<v_rd_off(1, 0, 0)>(vb), h4 = tr_read<v_rd_off(1, 0, 1)>(vb);
;   asm volatile("s_waitcnt lgkmcnt(8)" ::: "memory"); SBAR();
;   o[0] = __builtin_amdgcn_mfma_f32_32x32x16_bf16(pa0, PK(l0, h0), o[0], 0, 0, 0);
;   const s16x4 l5 = tr_read<v_rd_off(1, 1, 0)>(vb), h5 = tr_read<v_rd_off(1, 1, 1)>(vb);
;   asm volatile("s_waitcnt lgkmcnt(8)" ::: "memory"); SBAR();
;   o[0] = __builtin_amdgcn_mfma_f32_32x32x16_bf16(pa1, PK(l1, h1), o[0], 0, 0, 0);
;   const s16x4 l6 = tr_read<v_rd_off(1, 2, 0)>(vb), h6 = tr_read<v_rd_off(1, 2, 1)>(vb);
;   asm volatile("s_waitcnt lgkmcnt(8)" ::: "memory"); SBAR();
;   o[0] = __builtin_amdgcn_mfma_f32_32x32x16_bf16(pa2, PK(l2, h2), o[0], 0, 0, 0);
;   const s16x4 l7 = tr_read<v_rd_off(1, 3, 0)>(vb), h7 = tr_read<v_rd_off(1, 3, 1)>(vb);
;   asm volatile("s_waitcnt lgkmcnt(8)" ::: "memory"); SBAR();
;   o[0] = __builtin_amdgcn_mfma_f32_32x32x16_bf16(pa3, PK(l3, h3), o[0], 0, 0, 0);
;   const s16x4 l8 = tr_read<v_rd_off(2, 0, 0)>(vb), h8 = tr_read<v_rd_off(2, 0, 1)>(vb);
;   asm volatile("s_waitcnt lgkmcnt(8)" ::: "memory"); SBAR();
;   o[1] = __builtin_amdgcn_mfma_f32_32x32x16_bf16(pa0, PK(l4, h4), o[1], 0, 0, 0);
;   const s16x4 l9 = tr_read<v_rd_off(2, 1, 0)>(vb), h9 = tr_read<v_rd_off(2, 1, 1)>(vb);
;   asm volatile("s_waitcnt lgkmcnt(8)" ::: "memory"); SBAR();
;   o[1] = __builtin_amdgcn_mfma_f32_32x32x16_bf16(pa1, PK(l5, h5), o[1], 0, 0, 0);
;   const s16x4 l10 = tr_read<v_rd_off(2, 2, 0)>(vb), h10 = tr_read<v_rd_off(2, 2, 1)>(vb);
;   asm volatile("s_waitcnt lgkmcnt(8)" ::: "memory"); SBAR();
;   o[1] = __builtin_amdgcn_mfma_f32_32x32x16_bf16(pa2, PK(l6, h6), o[1], 0, 0, 0);
;   const s16x4 l11 = tr_read<v_rd_off(2, 3, 0)>(vb), h11 = tr_read<v_rd_off(2, 3, 1)>(vb);
;   asm volatile("s_waitcnt lgkmcnt(8)" ::: "memory"); SBAR();
;   o[1] = __builtin_amdgcn_mfma_f32_32x32x16_bf16(pa3, PK(l7, h7), o[1], 0, 0, 0);
	s_nop 0
	v_mfma_f32_32x32x16_bf16 v[2:17], v[162:165], v[232:235], v[2:17]
	ds_read_b64_tr_b16 v[232:233], v199 offset:0x1200
	ds_read_b64_tr_b16 v[234:235], v199 offset:0x1a00
	s_waitcnt lgkmcnt(8)
	v_mfma_f32_32x32x16_bf16 v[2:17], v[166:169], v[236:239], v[2:17]
	ds_read_b64_tr_b16 v[236:237], v199 offset:0x2200
	ds_read_b64_tr_b16 v[238:239], v199 offset:0x2a00
	s_waitcnt lgkmcnt(8)
	v_mfma_f32_32x32x16_bf16 v[2:17], v[170:173], v[240:243], v[2:17]
	ds_read_b64_tr_b16 v[240:241], v199 offset:0x3200
	ds_read_b64_tr_b16 v[242:243], v199 offset:0x3a00
	s_waitcnt lgkmcnt(8)
	v_mfma_f32_32x32x16_bf16 v[2:17], v[174:177], v[244:247], v[2:17]
	ds_read_b64_tr_b16 v[244:245], v199 offset:0x400
	ds_read_b64_tr_b16 v[246:247], v199 offset:0xc00
	s_waitcnt lgkmcnt(8)
	v_mfma_f32_32x32x16_bf16 v[50:65], v[162:165], v[248:251], v[50:65]
	ds_read_b64_tr_b16 v[248:249], v199 offset:0x1400
	ds_read_b64_tr_b16 v[250:251], v199 offset:0x1c00
	s_waitcnt lgkmcnt(8)
	v_mfma_f32_32x32x16_bf16 v[50:65], v[166:169], v[232:235], v[50:65]
	ds_read_b64_tr_b16 v[232:233], v199 offset:0x2400
	ds_read_b64_tr_b16 v[234:235], v199 offset:0x2c00
	s_waitcnt lgkmcnt(8)
	v_mfma_f32_32x32x16_bf16 v[50:65], v[170:173], v[236:239], v[50:65]
	ds_read_b64_tr_b16 v[236:237], v199 offset:0x3400
	ds_read_b64_tr_b16 v[238:239], v199 offset:0x3c00
	s_waitcnt lgkmcnt(8)
	v_mfma_f32_32x32x16_bf16 v[50:65], v[174:177], v[240:243], v[50:65]
	ds_read_b64_tr_b16 v[240:241], v199 offset:0x600
	ds_read_b64_tr_b16 v[242:243], v199 offset:0xe00
	s_waitcnt lgkmcnt(8)
	v_mfma_f32_32x32x16_bf16 v[34:49], v[162:165], v[244:247], v[34:49]
	ds_read_b64_tr_b16 v[244:245], v199 offset:0x1600
	ds_read_b64_tr_b16 v[246:247], v199 offset:0x1e00
	s_waitcnt lgkmcnt(8)
	v_mfma_f32_32x32x16_bf16 v[34:49], v[166:169], v[248:251], v[34:49]
	ds_read_b64_tr_b16 v[248:249], v199 offset:0x2600
	ds_read_b64_tr_b16 v[250:251], v199 offset:0x2e00
	s_waitcnt lgkmcnt(8)
	v_mfma_f32_32x32x16_bf16 v[34:49], v[170:173], v[232:235], v[34:49]
	ds_read_b64_tr_b16 v[232:233], v199 offset:0x3600
	ds_read_b64_tr_b16 v[234:235], v199 offset:0x3e00
	s_waitcnt lgkmcnt(8)
	v_mfma_f32_32x32x16_bf16 v[34:49], v[174:177], v[236:239], v[34:49]
	s_waitcnt lgkmcnt(6)
	v_mfma_f32_32x32x16_bf16 v[18:33], v[162:165], v[240:243], v[18:33]
	s_waitcnt lgkmcnt(4)
	v_mfma_f32_32x32x16_bf16 v[18:33], v[166:169], v[244:247], v[18:33]
	s_waitcnt lgkmcnt(2)
	v_mfma_f32_32x32x16_bf16 v[18:33], v[170:173], v[248:251], v[18:33]
	s_waitcnt lgkmcnt(0)
	v_max_f32_e32 v162, v114, v118
	v_max_f32_e32 v163, v115, v119
	v_max_f32_e32 v164, v117, v121
	v_max3_f32 v165, v116, v120, v124
	v_max3_f32 v164, v164, v125, v129
	v_max3_f32 v162, v162, v122, v126
	v_max3_f32 v163, v163, v123, v127
	v_max3_f32 v165, v165, v128, v100
	v_max3_f32 v164, v164, v101, v105
	v_max3_f32 v162, v162, v98, v102
	v_max3_f32 v163, v163, v99, v103
	v_max3_f32 v165, v165, v104, v108
	v_max3_f32 v164, v164, v109, v113
	v_mfma_f32_32x32x16_bf16 v[18:33], v[174:177], v[232:235], v[18:33]
	v_max3_f32 v162, v162, v106, v110
	v_max3_f32 v163, v163, v107, v111
	v_max3_f32 v164, v165, v112, v164
	v_max3_f32 v162, v162, v163, v164
	v_mov_b32_e32 v163, v162
	s_nop 1
	v_permlane32_swap_b32_e32 v162, v163
	v_max_f32_e32 v162, v162, v163
	v_cmp_ge_f32_e32 vcc, s48, v162
	s_cmp_eq_u64 vcc, exec
	s_cbranch_scc0 .LBB0_461
	v_mov_b32_e32 v230, v228
	v_mov_b32_e32 v229, 1.0
.LBB0_449:
	s_barrier
	s_waitcnt vmcnt(0)
	v_cmp_gt_f32_e32 vcc, 1.0, v229
	ds_write_b128 v201, v[66:69]
	ds_write_b128 v207, v[70:73]
	ds_write_b128 v208, v[74:77] offset:32768
	ds_write_b128 v209, v[78:81] offset:32768
	s_cbranch_vccz .LBB0_453
	s_and_saveexec_b64 s[10:11], s[4:5]
	ds_write_b32 v183, v229 offset:128
	s_or_b64 exec, exec, s[10:11]
	s_waitcnt lgkmcnt(0)
	ds_read_b128 v[66:69], v181 offset:224
	ds_read_b128 v[70:73], v181 offset:192
	ds_read_b128 v[74:77], v181 offset:160
	ds_read_b128 v[78:81], v181 offset:128
	s_waitcnt lgkmcnt(3)
	v_pk_mul_f32 v[16:17], v[16:17], v[68:69]
	s_waitcnt lgkmcnt(2)
	v_pk_mul_f32 v[12:13], v[12:13], v[72:73]
	s_waitcnt lgkmcnt(1)
	v_pk_mul_f32 v[8:9], v[8:9], v[76:77]
	s_waitcnt lgkmcnt(0)
	v_pk_mul_f32 v[4:5], v[4:5], v[80:81]
	v_pk_mul_f32 v[14:15], v[14:15], v[66:67]
	v_pk_mul_f32 v[10:11], v[10:11], v[70:71]
	v_pk_mul_f32 v[6:7], v[6:7], v[74:75]
	v_pk_mul_f32 v[2:3], v[2:3], v[78:79]
	v_pk_mul_f32 v[64:65], v[64:65], v[68:69]
	v_pk_mul_f32 v[60:61], v[60:61], v[72:73]
	v_pk_mul_f32 v[56:57], v[56:57], v[76:77]
	v_pk_mul_f32 v[52:53], v[52:53], v[80:81]
	v_pk_mul_f32 v[62:63], v[62:63], v[66:67]
	v_pk_mul_f32 v[58:59], v[58:59], v[70:71]
	v_pk_mul_f32 v[54:55], v[54:55], v[74:75]
	v_pk_mul_f32 v[50:51], v[50:51], v[78:79]
	v_pk_mul_f32 v[48:49], v[48:49], v[68:69]
	v_pk_mul_f32 v[44:45], v[44:45], v[72:73]
	v_pk_mul_f32 v[40:41], v[40:41], v[76:77]
	v_pk_mul_f32 v[36:37], v[36:37], v[80:81]
	v_pk_mul_f32 v[46:47], v[46:47], v[66:67]
	v_pk_mul_f32 v[42:43], v[42:43], v[70:71]
	v_pk_mul_f32 v[38:39], v[38:39], v[74:75]
	v_pk_mul_f32 v[34:35], v[34:35], v[78:79]
	v_pk_mul_f32 v[32:33], v[32:33], v[68:69]
	v_pk_mul_f32 v[28:29], v[28:29], v[72:73]
	v_pk_mul_f32 v[24:25], v[24:25], v[76:77]
	v_pk_mul_f32 v[20:21], v[20:21], v[80:81]
	v_pk_mul_f32 v[30:31], v[30:31], v[66:67]
	v_pk_mul_f32 v[26:27], v[26:27], v[70:71]
	v_pk_mul_f32 v[22:23], v[22:23], v[74:75]
	v_pk_mul_f32 v[18:19], v[18:19], v[78:79]
; __device__ __forceinline__ void qkt12_roll(f32x16& p0, f32x16& p1, const f32x16& negm, int kb, int qa, const bf16x8* qr) {
;   const int a0 = kb ^ (0 << 5); const bf16x8 x0 = lds_rd128<0>(a0), y0 = lds_rd128<12288>(a0);
;   const int a1 = kb ^ (1 << 5); const bf16x8 x1 = lds_rd128<0>(a1), y1 = lds_rd128<12288>(a1);
;   asm volatile("s_waitcnt lgkmcnt(2)" ::: "memory"); SBAR();
;   p0 = __builtin_amdgcn_mfma_f32_32x32x16_bf16(x0, qr[0], negm, 0, 0, 0); p1 = __builtin_amdgcn_mfma_f32_32x32x16_bf16(y0, qr[0], negm, 0, 0, 0);
;   const int a2 = kb ^ (2 << 5); const bf16x8 x2 = lds_rd128<0>(a2), y2 = lds_rd128<12288>(a2);
;   asm volatile("s_waitcnt lgkmcnt(2)" ::: "memory"); SBAR();
;   p0 = __builtin_amdgcn_mfma_f32_32x32x16_bf16(x1, qr[1], p0, 0, 0, 0); p1 = __builtin_amdgcn_mfma_f32_32x32x16_bf16(y1, qr[1], p1, 0, 0, 0);
;   const int a3 = kb ^ (3 << 5); const bf16x8 x3 = lds_rd128<0>(a3), y3 = lds_rd128<12288>(a3);
;   asm volatile("s_waitcnt lgkmcnt(2)" ::: "memory"); SBAR();
;   p0 = __builtin_amdgcn_mfma_f32_32x32x16_bf16(x2, qr[2], p0, 0, 0, 0); p1 = __builtin_amdgcn_mfma_f32_32x32x16_bf16(y2, qr[2], p1, 0, 0, 0);
;   const int a4 = kb ^ (0 << 5); const bf16x8 x4 = lds_rd128<128>(a4), y4 = lds_rd128<12416>(a4);
;   asm volatile("s_waitcnt lgkmcnt(2)" ::: "memory"); SBAR();
;   p0 = __builtin_amdgcn_mfma_f32_32x32x16_bf16(x3, qr[3], p0, 0, 0, 0); p1 = __builtin_amdgcn_mfma_f32_32x32x16_bf16(y3, qr[3], p1, 0, 0, 0);
;   const int a5 = kb ^ (1 << 5); const bf16x8 x5 = lds_rd128<128>(a5), y5 = lds_rd128<12416>(a5);
;   asm volatile("s_waitcnt lgkmcnt(2)" ::: "memory"); SBAR();
;   p0 = __builtin_amdgcn_mfma_f32_32x32x16_bf16(x4, qr[4], p0, 0, 0, 0); p1 = __builtin_amdgcn_mfma_f32_32x32x16_bf16(y4, qr[4], p1, 0, 0, 0);
;   const int a6 = kb ^ (2 << 5); const bf16x8 x6 = lds_rd128<128>(a6), y6 = lds_rd128<12416>(a6);
;   asm volatile("s_waitcnt lgkmcnt(2)" ::: "memory"); SBAR();
;   p0 = __builtin_amdgcn_mfma_f32_32x32x16_bf16(x5, qr[5], p0, 0, 0, 0); p1 = __builtin_amdgcn_mfma_f32_32x32x16_bf16(y5, qr[5], p1, 0, 0, 0);
;   const int a7 = kb ^ (3 << 5); const bf16x8 x7 = lds_rd128<128>(a7), y7 = lds_rd128<12416>(a7);
;   asm volatile("s_waitcnt lgkmcnt(2)" ::: "memory"); SBAR();
;   p0 = __builtin_amdgcn_mfma_f32_32x32x16_bf16(x6, qr[6], p0, 0, 0, 0); p1 = __builtin_amdgcn_mfma_f32_32x32x16_bf16(y6, qr[6], p1, 0, 0, 0);
.LBB0_453:
	v_xor_b32_e32 v66, 0x80000000, v228
	v_cndmask_b32_e64 v231, v66, v231, s[6:7]
	v_exp_f32_e32 v162, v114
	v_exp_f32_e32 v163, v116
	v_cmp_neq_f32_e64 s[6:7], v231, -v230
	s_cmp_eq_u64 s[6:7], 0
	s_cselect_b64 s[6:7], -1, 0
	v_cndmask_b32_e64 v97, -v230, v97, s[6:7]
	v_cndmask_b32_e64 v96, -v230, v96, s[6:7]
	v_cndmask_b32_e64 v95, -v230, v95, s[6:7]
	v_cndmask_b32_e64 v94, -v230, v94, s[6:7]
	v_cndmask_b32_e64 v93, -v230, v93, s[6:7]
	v_cndmask_b32_e64 v92, -v230, v92, s[6:7]
	v_cndmask_b32_e64 v91, -v230, v91, s[6:7]
	v_cndmask_b32_e64 v90, -v230, v90, s[6:7]
	v_cndmask_b32_e64 v89, -v230, v89, s[6:7]
	v_cndmask_b32_e64 v88, -v230, v88, s[6:7]
	v_cndmask_b32_e64 v87, -v230, v87, s[6:7]
	v_cndmask_b32_e64 v86, -v230, v86, s[6:7]
	v_cndmask_b32_e64 v85, -v230, v85, s[6:7]
	v_cndmask_b32_e64 v84, -v230, v84, s[6:7]
	v_cndmask_b32_e64 v83, -v230, v83, s[6:7]
	v_cndmask_b32_e64 v82, -v230, v82, s[6:7]
	v_exp_f32_e32 v177, v115
	v_exp_f32_e32 v176, v117
	v_exp_f32_e32 v164, v118
	v_exp_f32_e32 v175, v119
	v_exp_f32_e32 v165, v120
	v_exp_f32_e32 v174, v121
	v_exp_f32_e32 v166, v122
	v_exp_f32_e32 v173, v123
	v_exp_f32_e32 v167, v124
	v_exp_f32_e32 v172, v125
	v_exp_f32_e32 v168, v126
	v_exp_f32_e32 v171, v127
	v_exp_f32_e32 v169, v128
	v_exp_f32_e32 v170, v129
	s_waitcnt lgkmcnt(0)
	s_barrier
	ds_read_b128 v[66:69], v200 offset:0
	ds_read_b128 v[232:235], v200 offset:0x2000
	ds_read_b128 v[236:239], v210 offset:0
	ds_read_b128 v[240:243], v210 offset:0x2000
	ds_read_b128 v[244:247], v211 offset:0
	ds_read_b128 v[248:251], v211 offset:0x2000
	s_waitcnt lgkmcnt(4)
	s_nop 0
	v_mfma_f32_32x32x16_bf16 v[114:129], v[66:69], v[158:161], v[82:97]
	v_mfma_f32_32x32x16_bf16 v[66:81], v[232:235], v[158:161], v[82:97]
	ds_read_b128 v[232:235], v212 offset:0
	ds_read_b128 v[192:195], v212 offset:0x2000
	s_waitcnt lgkmcnt(4)
	v_mfma_f32_32x32x16_bf16 v[114:129], v[236:239], v[154:157], v[114:129]
	ds_read_b128 v[236:239], v213 offset:0
	v_mfma_f32_32x32x16_bf16 v[66:81], v[240:243], v[154:157], v[66:81]
	ds_read_b128 v[240:243], v213 offset:0x2000
	s_waitcnt lgkmcnt(4)
	v_mfma_f32_32x32x16_bf16 v[114:129], v[244:247], v[150:153], v[114:129]
	ds_read_b128 v[244:247], v214 offset:0
	v_mfma_f32_32x32x16_bf16 v[66:81], v[248:251], v[150:153], v[66:81]
	ds_read_b128 v[248:251], v214 offset:0x2000
	s_waitcnt lgkmcnt(4)
	v_mfma_f32_32x32x16_bf16 v[114:129], v[232:235], v[146:149], v[114:129]
	v_mfma_f32_32x32x16_bf16 v[66:81], v[192:195], v[146:149], v[66:81]
	ds_read_b128 v[192:195], v215 offset:0
	ds_read_b128 v[232:235], v215 offset:0x2000
	s_waitcnt lgkmcnt(4)
	v_mfma_f32_32x32x16_bf16 v[114:129], v[236:239], v[142:145], v[114:129]
	ds_read_b128 v[236:239], v216 offset:0
	v_mfma_f32_32x32x16_bf16 v[66:81], v[240:243], v[142:145], v[66:81]
	ds_read_b128 v[240:243], v216 offset:0x2000
	s_waitcnt lgkmcnt(4)
	v_mfma_f32_32x32x16_bf16 v[114:129], v[244:247], v[138:141], v[114:129]
	s_waitcnt lgkmcnt(2)
	v_mfma_f32_32x32x16_bf16 v[66:81], v[248:251], v[138:141], v[66:81]
	v_mfma_f32_32x32x16_bf16 v[114:129], v[192:195], v[134:137], v[114:129]
	s_waitcnt lgkmcnt(0)
	v_mfma_f32_32x32x16_bf16 v[66:81], v[232:235], v[134:137], v[66:81]
	v_exp_f32_e32 v98, v98
	v_exp_f32_e32 v99, v99
	v_exp_f32_e32 v100, v100
	v_exp_f32_e32 v101, v101
	v_exp_f32_e32 v102, v102
	v_exp_f32_e32 v103, v103
	v_exp_f32_e32 v104, v104
	v_exp_f32_e32 v105, v105
	v_add_f32_e32 v192, v164, v162
	v_add_f32_e32 v193, v175, v177
	v_add_f32_e32 v194, v165, v163
	v_add_f32_e32 v195, v174, v176
	v_exp_f32_e32 v106, v106
	v_exp_f32_e32 v107, v107
	v_exp_f32_e32 v108, v108
	v_exp_f32_e32 v109, v109
	v_add_f32_e32 v192, v166, v192
	v_add_f32_e32 v193, v173, v193
	v_add_f32_e32 v194, v167, v194
	v_add_f32_e32 v195, v172, v195
	v_exp_f32_e32 v110, v110
	v_exp_f32_e32 v111, v111
	v_exp_f32_e32 v112, v112
	v_exp_f32_e32 v113, v113
	v_add_f32_e32 v192, v168, v192
	v_add_f32_e32 v193, v171, v193
	v_add_f32_e32 v194, v169, v194
	v_add_f32_e32 v195, v170, v195
	v_mfma_f32_32x32x16_bf16 v[114:129], v[236:239], v[130:133], v[114:129]
	v_add_f32_e32 v192, v98, v192
	v_add_f32_e32 v193, v193, v99
	v_add_f32_e32 v194, v194, v100
	v_add_f32_e32 v195, v195, v101
	v_add_f32_e32 v192, v102, v192
	v_add_f32_e32 v193, v103, v193
	v_add_f32_e32 v194, v104, v194
	v_mfma_f32_32x32x16_bf16 v[66:81], v[240:243], v[130:133], v[66:81]
	v_add_f32_e32 v195, v105, v195
	v_add_f32_e32 v192, v106, v192
	v_add_f32_e32 v193, v107, v193
	v_add_f32_e32 v194, v108, v194
	v_add_f32_e32 v195, v109, v195
	v_add_f32_e32 v192, v110, v192
	v_add_f32_e32 v193, v111, v193
	v_add_f32_e32 v194, v112, v194
	v_add_f32_e32 v195, v113, v195
	v_add_f32_e32 v192, v192, v193
	v_add_f32_e32 v193, v194, v195
	v_add_f32_e32 v232, v192, v193
	v_mov_b32_e32 v233, v232
	v_cvt_pk_bf16_f32 v162, v162, v177
	v_cvt_pk_bf16_f32 v163, v163, v176
	v_cvt_pk_bf16_f32 v164, v164, v175
	v_cvt_pk_bf16_f32 v165, v165, v174
	s_nop 1
	v_permlane32_swap_b32_e32 v232, v233
	v_permlane32_swap_b32_e32 v162, v164
	v_permlane32_swap_b32_e32 v163, v165
	v_cvt_pk_bf16_f32 v166, v166, v173
	v_cvt_pk_bf16_f32 v167, v167, v172
	v_cvt_pk_bf16_f32 v168, v168, v171
	v_cvt_pk_bf16_f32 v169, v169, v170
	v_cvt_pk_bf16_f32 v170, v98, v99
	v_cvt_pk_bf16_f32 v171, v100, v101
	v_cvt_pk_bf16_f32 v172, v102, v103
	v_cvt_pk_bf16_f32 v173, v104, v105
	v_cvt_pk_bf16_f32 v174, v106, v107
	v_cvt_pk_bf16_f32 v175, v108, v109
	v_cvt_pk_bf16_f32 v176, v110, v111
	v_cvt_pk_bf16_f32 v177, v112, v113
	s_nop 0
	v_permlane32_swap_b32_e32 v166, v168
	v_permlane32_swap_b32_e32 v167, v169
	v_permlane32_swap_b32_e32 v170, v172
	v_permlane32_swap_b32_e32 v171, v173
	v_permlane32_swap_b32_e32 v174, v176
	v_permlane32_swap_b32_e32 v175, v177
	v_add_co_u32_e32 v98, vcc, s72, v188
	s_nop 1
	v_addc_co_u32_e32 v99, vcc, 0, v189, vcc
	v_add_co_u32_e32 v102, vcc, s73, v188
	s_nop 1
	v_addc_co_u32_e32 v103, vcc, 0, v189, vcc
	v_add_co_u32_e32 v106, vcc, s33, v190
	global_load_dwordx4 v[98:101], v[98:99], off offset:2176
	s_nop 0
	global_load_dwordx4 v[102:105], v[102:103], off offset:2176
	v_addc_co_u32_e32 v107, vcc, 0, v191, vcc
	v_add_co_u32_e32 v110, vcc, s52, v190
	s_nop 1
	v_addc_co_u32_e32 v111, vcc, 0, v191, vcc
	global_load_dwordx4 v[106:109], v[106:107], off
	s_nop 0
	global_load_dwordx4 v[110:113], v[110:111], off
	ds_read_b64_tr_b16 v[188:189], v198 offset:0
	ds_read_b64_tr_b16 v[190:191], v198 offset:0x800
	ds_read_b64_tr_b16 v[192:193], v198 offset:0x1000
	ds_read_b64_tr_b16 v[194:195], v198 offset:0x1800
	ds_read_b64_tr_b16 v[234:235], v198 offset:0x2000
	ds_read_b64_tr_b16 v[236:237], v198 offset:0x2800
	ds_read_b64_tr_b16 v[238:239], v198 offset:0x3000
	ds_read_b64_tr_b16 v[240:241], v198 offset:0x3800
	ds_read_b64_tr_b16 v[242:243], v198 offset:0x200
	ds_read_b64_tr_b16 v[244:245], v198 offset:0xa00
	s_waitcnt lgkmcnt(8)
; __device__ __forceinline__ void pv_d0(f32x16* o, int vb, bf16x8 pa0, bf16x8 pa1, bf16x8 pa2, bf16x8 pa3) {
;     ...
;   const s16x4 l0 = tr_read<v_rd_off(0, 0, 0)>(vb), h0 = tr_read<v_rd_off(0, 0, 1)>(vb);
;   const s16x4 l1 = tr_read<v_rd_off(0, 1, 0)>(vb), h1 = tr_read<v_rd_off(0, 1, 1)>(vb);
;   const s16x4 l2 = tr_read<v_rd_off(0, 2, 0)>(vb), h2 = tr_read<v_rd_off(0, 2, 1)>(vb);
;   const s16x4 l3 = tr_read<v_rd_off(0, 3, 0)>(vb), h3 = tr_read<v_rd_off(0, 3, 1)>(vb);
;   const s16x4 l4 = tr_read<v_rd_off(1, 0, 0)>(vb), h4 = tr_read<v_rd_off(1, 0, 1)>(vb);
;   asm volatile("s_waitcnt lgkmcnt(8)" ::: "memory"); SBAR();
;   o[0] = __builtin_amdgcn_mfma_f32_32x32x16_bf16(pa0, PK(l0, h0), o[0], 0, 0, 0);
;   const s16x4 l5 = tr_read<v_rd_off(1, 1, 0)>(vb), h5 = tr_read<v_rd_off(1, 1, 1)>(vb);
;   asm volatile("s_waitcnt lgkmcnt(8)" ::: "memory"); SBAR();
;   o[0] = __builtin_amdgcn_mfma_f32_32x32x16_bf16(pa1, PK(l1, h1), o[0], 0, 0, 0);
;   const s16x4 l6 = tr_read<v_rd_off(1, 2, 0)>(vb), h6 = tr_read<v_rd_off(1, 2, 1)>(vb);
;   asm volatile("s_waitcnt lgkmcnt(8)" ::: "memory"); SBAR();
;   o[0] = __builtin_amdgcn_mfma_f32_32x32x16_bf16(pa2, PK(l2, h2), o[0], 0, 0, 0);
;   const s16x4 l7 = tr_read<v_rd_off(1, 3, 0)>(vb), h7 = tr_read<v_rd_off(1, 3, 1)>(vb);
;   asm volatile("s_waitcnt lgkmcnt(8)" ::: "memory"); SBAR();
;   o[0] = __builtin_amdgcn_mfma_f32_32x32x16_bf16(pa3, PK(l3, h3), o[0], 0, 0, 0);
;   const s16x4 l8 = tr_read<v_rd_off(2, 0, 0)>(vb), h8 = tr_read<v_rd_off(2, 0, 1)>(vb);
;   asm volatile("s_waitcnt lgkmcnt(8)" ::: "memory"); SBAR();
;   o[1] = __builtin_amdgcn_mfma_f32_32x32x16_bf16(pa0, PK(l4, h4), o[1], 0, 0, 0);
;   const s16x4 l9 = tr_read<v_rd_off(2, 1, 0)>(vb), h9 = tr_read<v_rd_off(2, 1, 1)>(vb);
;   asm volatile("s_waitcnt lgkmcnt(8)" ::: "memory"); SBAR();
;   o[1] = __builtin_amdgcn_mfma_f32_32x32x16_bf16(pa1, PK(l5, h5), o[1], 0, 0, 0);
;   const s16x4 l10 = tr_read<v_rd_off(2, 2, 0)>(vb), h10 = tr_read<v_rd_off(2, 2, 1)>(vb);
;   asm volatile("s_waitcnt lgkmcnt(8)" ::: "memory"); SBAR();
;   o[1] = __builtin_amdgcn_mfma_f32_32x32x16_bf16(pa2, PK(l6, h6), o[1], 0, 0, 0);
;   const s16x4 l11 = tr_read<v_rd_off(2, 3, 0)>(vb), h11 = tr_read<v_rd_off(2, 3, 1)>(vb);
;   asm volatile("s_waitcnt lgkmcnt(8)" ::: "memory"); SBAR();
;   o[1] = __builtin_amdgcn_mfma_f32_32x32x16_bf16(pa3, PK(l7, h7), o[1], 0, 0, 0);
	s_nop 0
	v_mfma_f32_32x32x16_bf16 v[2:17], v[162:165], v[188:191], v[2:17]
	ds_read_b64_tr_b16 v[188:189], v198 offset:0x1200
	ds_read_b64_tr_b16 v[190:191], v198 offset:0x1a00
	s_waitcnt lgkmcnt(8)
	v_mfma_f32_32x32x16_bf16 v[2:17], v[166:169], v[192:195], v[2:17]
	ds_read_b64_tr_b16 v[192:193], v198 offset:0x2200
	ds_read_b64_tr_b16 v[194:195], v198 offset:0x2a00
	s_waitcnt lgkmcnt(8)
	v_mfma_f32_32x32x16_bf16 v[2:17], v[170:173], v[234:237], v[2:17]
	ds_read_b64_tr_b16 v[234:235], v198 offset:0x3200
	ds_read_b64_tr_b16 v[236:237], v198 offset:0x3a00
	s_waitcnt lgkmcnt(8)
	v_mfma_f32_32x32x16_bf16 v[2:17], v[174:177], v[238:241], v[2:17]
	ds_read_b64_tr_b16 v[238:239], v198 offset:0x400
	ds_read_b64_tr_b16 v[240:241], v198 offset:0xc00
	s_waitcnt lgkmcnt(8)
	v_mfma_f32_32x32x16_bf16 v[50:65], v[162:165], v[242:245], v[50:65]
	ds_read_b64_tr_b16 v[242:243], v198 offset:0x1400
	ds_read_b64_tr_b16 v[244:245], v198 offset:0x1c00
	s_waitcnt lgkmcnt(8)
	v_mfma_f32_32x32x16_bf16 v[50:65], v[166:169], v[188:191], v[50:65]
	ds_read_b64_tr_b16 v[188:189], v198 offset:0x2400
	ds_read_b64_tr_b16 v[190:191], v198 offset:0x2c00
	s_waitcnt lgkmcnt(8)
	v_mfma_f32_32x32x16_bf16 v[50:65], v[170:173], v[192:195], v[50:65]
	ds_read_b64_tr_b16 v[192:193], v198 offset:0x3400
	ds_read_b64_tr_b16 v[194:195], v198 offset:0x3c00
	s_waitcnt lgkmcnt(8)
	v_mfma_f32_32x32x16_bf16 v[50:65], v[174:177], v[234:237], v[50:65]
	ds_read_b64_tr_b16 v[234:235], v198 offset:0x600
	ds_read_b64_tr_b16 v[236:237], v198 offset:0xe00
	s_waitcnt lgkmcnt(8)
	v_mfma_f32_32x32x16_bf16 v[34:49], v[162:165], v[238:241], v[34:49]
	ds_read_b64_tr_b16 v[238:239], v198 offset:0x1600
	ds_read_b64_tr_b16 v[240:241], v198 offset:0x1e00
	s_waitcnt lgkmcnt(8)
	v_mfma_f32_32x32x16_bf16 v[34:49], v[166:169], v[242:245], v[34:49]
	ds_read_b64_tr_b16 v[242:243], v198 offset:0x2600
	ds_read_b64_tr_b16 v[244:245], v198 offset:0x2e00
	s_waitcnt lgkmcnt(8)
	v_mfma_f32_32x32x16_bf16 v[34:49], v[170:173], v[188:191], v[34:49]
	ds_read_b64_tr_b16 v[188:189], v198 offset:0x3600
	ds_read_b64_tr_b16 v[190:191], v198 offset:0x3e00
	s_waitcnt lgkmcnt(8)
	v_mfma_f32_32x32x16_bf16 v[34:49], v[174:177], v[192:195], v[34:49]
	s_waitcnt lgkmcnt(6)
	v_mfma_f32_32x32x16_bf16 v[18:33], v[162:165], v[234:237], v[18:33]
	s_waitcnt lgkmcnt(4)
	v_mfma_f32_32x32x16_bf16 v[18:33], v[166:169], v[238:241], v[18:33]
	s_waitcnt lgkmcnt(2)
	v_mfma_f32_32x32x16_bf16 v[18:33], v[170:173], v[242:245], v[18:33]
	s_waitcnt lgkmcnt(0)
	v_max_f32_e32 v162, v114, v118
	v_max_f32_e32 v163, v115, v119
	v_max_f32_e32 v164, v117, v121
	v_max3_f32 v165, v116, v120, v124
	v_max3_f32 v164, v164, v125, v129
	v_max3_f32 v162, v162, v122, v126
	v_max3_f32 v163, v163, v123, v127
	v_max3_f32 v165, v165, v128, v68
	v_max3_f32 v164, v164, v69, v73
	v_max3_f32 v162, v162, v66, v70
	v_max3_f32 v163, v163, v67, v71
	v_max3_f32 v165, v165, v72, v76
	v_max3_f32 v164, v164, v77, v81
	v_mfma_f32_32x32x16_bf16 v[18:33], v[174:177], v[188:191], v[18:33]
	v_max3_f32 v162, v162, v74, v78
	v_max3_f32 v163, v163, v75, v79
	v_max3_f32 v164, v165, v80, v164
	v_max3_f32 v162, v162, v163, v164
	v_mov_b32_e32 v163, v162
	s_nop 1
	v_permlane32_swap_b32_e32 v162, v163
	v_max_f32_e32 v163, v162, v163
	v_cmp_ge_f32_e32 vcc, s48, v163
	s_cmp_eq_u64 vcc, exec
	v_mov_b32_e32 v162, 1.0
	s_cbranch_scc0 .LBB0_462
	v_mov_b32_e32 v228, v230
.LBB0_455:
	s_barrier
	s_waitcnt vmcnt(0)
	v_cmp_gt_f32_e32 vcc, 1.0, v162
	ds_write_b128 v201, v[98:101] offset:16384
	ds_write_b128 v207, v[102:105] offset:16384
	ds_write_b128 v208, v[106:109] offset:49152
	ds_write_b128 v209, v[110:113] offset:49152
	s_cbranch_vccz .LBB0_459
	s_and_saveexec_b64 s[10:11], s[4:5]
	ds_write_b32 v183, v162 offset:128
	s_or_b64 exec, exec, s[10:11]
	s_waitcnt lgkmcnt(0)
	ds_read_b128 v[98:101], v181 offset:224
	ds_read_b128 v[102:105], v181 offset:192
	ds_read_b128 v[106:109], v181 offset:160
	ds_read_b128 v[110:113], v181 offset:128
	s_waitcnt lgkmcnt(3)
	v_pk_mul_f32 v[16:17], v[16:17], v[100:101]
	s_waitcnt lgkmcnt(2)
	v_pk_mul_f32 v[12:13], v[12:13], v[104:105]
	s_waitcnt lgkmcnt(1)
	v_pk_mul_f32 v[8:9], v[8:9], v[108:109]
	s_waitcnt lgkmcnt(0)
	v_pk_mul_f32 v[4:5], v[4:5], v[112:113]
	v_pk_mul_f32 v[14:15], v[14:15], v[98:99]
	v_pk_mul_f32 v[10:11], v[10:11], v[102:103]
	v_pk_mul_f32 v[6:7], v[6:7], v[106:107]
	v_pk_mul_f32 v[2:3], v[2:3], v[110:111]
	v_pk_mul_f32 v[64:65], v[64:65], v[100:101]
	v_pk_mul_f32 v[60:61], v[60:61], v[104:105]
	v_pk_mul_f32 v[56:57], v[56:57], v[108:109]
	v_pk_mul_f32 v[52:53], v[52:53], v[112:113]
	v_pk_mul_f32 v[62:63], v[62:63], v[98:99]
	v_pk_mul_f32 v[58:59], v[58:59], v[102:103]
	v_pk_mul_f32 v[54:55], v[54:55], v[106:107]
	v_pk_mul_f32 v[50:51], v[50:51], v[110:111]
	v_pk_mul_f32 v[48:49], v[48:49], v[100:101]
	v_pk_mul_f32 v[44:45], v[44:45], v[104:105]
	v_pk_mul_f32 v[40:41], v[40:41], v[108:109]
	v_pk_mul_f32 v[36:37], v[36:37], v[112:113]
	v_pk_mul_f32 v[46:47], v[46:47], v[98:99]
	v_pk_mul_f32 v[42:43], v[42:43], v[102:103]
	v_pk_mul_f32 v[38:39], v[38:39], v[106:107]
	v_pk_mul_f32 v[34:35], v[34:35], v[110:111]
	v_pk_mul_f32 v[32:33], v[32:33], v[100:101]
	v_pk_mul_f32 v[28:29], v[28:29], v[104:105]
	v_pk_mul_f32 v[24:25], v[24:25], v[108:109]
	v_pk_mul_f32 v[20:21], v[20:21], v[112:113]
	v_pk_mul_f32 v[30:31], v[30:31], v[98:99]
	v_pk_mul_f32 v[26:27], v[26:27], v[102:103]
	v_pk_mul_f32 v[22:23], v[22:23], v[106:107]
	v_pk_mul_f32 v[18:19], v[18:19], v[110:111]

; __device__ __forceinline__ void pv_psm(f32x16* o, int vb, bf16x8 pa0, bf16x8 pa1, bf16x8 pa2, bf16x8 pa3, f32x16& n0, f32x16& n1, float& mC, float& alpha) {
;     ...
;   const s16x4 l0 = tr_read<v_rd_off(0, 0, 0)>(vb), h0 = tr_read<v_rd_off(0, 0, 1)>(vb);
;   const s16x4 l1 = tr_read<v_rd_off(0, 1, 0)>(vb), h1 = tr_read<v_rd_off(0, 1, 1)>(vb);
;   const s16x4 l2 = tr_read<v_rd_off(0, 2, 0)>(vb), h2 = tr_read<v_rd_off(0, 2, 1)>(vb);
;   const s16x4 l3 = tr_read<v_rd_off(0, 3, 0)>(vb), h3 = tr_read<v_rd_off(0, 3, 1)>(vb);
;   asm volatile("s_waitcnt lgkmcnt(6)" ::: "memory"); SBAR();
;   o[0] = __builtin_amdgcn_mfma_f32_32x32x16_bf16(pa0, PK(l0, h0), o[0], 0, 0, 0);
;   psm_slice<0>(n0, n1, mC, alpha, mx); SBAR();
;   const s16x4 l4 = tr_read<v_rd_off(1, 0, 0)>(vb), h4 = tr_read<v_rd_off(1, 0, 1)>(vb);
;   asm volatile("s_waitcnt lgkmcnt(6)" ::: "memory"); SBAR();
;   o[0] = __builtin_amdgcn_mfma_f32_32x32x16_bf16(pa1, PK(l1, h1), o[0], 0, 0, 0);
;   psm_slice<1>(n0, n1, mC, alpha, mx); SBAR();
;   const s16x4 l5 = tr_read<v_rd_off(1, 1, 0)>(vb), h5 = tr_read<v_rd_off(1, 1, 1)>(vb);
;   asm volatile("s_waitcnt lgkmcnt(6)" ::: "memory"); SBAR();
;   o[0] = __builtin_amdgcn_mfma_f32_32x32x16_bf16(pa2, PK(l2, h2), o[0], 0, 0, 0);
;   psm_slice<2>(n0, n1, mC, alpha, mx); SBAR();
;   const s16x4 l6 = tr_read<v_rd_off(1, 2, 0)>(vb), h6 = tr_read<v_rd_off(1, 2, 1)>(vb);
;   asm volatile("s_waitcnt lgkmcnt(6)" ::: "memory"); SBAR();
;   o[0] = __builtin_amdgcn_mfma_f32_32x32x16_bf16(pa3, PK(l3, h3), o[0], 0, 0, 0);
;   psm_slice<3>(n0, n1, mC, alpha, mx); SBAR();
;   const s16x4 l7 = tr_read<v_rd_off(1, 3, 0)>(vb), h7 = tr_read<v_rd_off(1, 3, 1)>(vb);
;   asm volatile("s_waitcnt lgkmcnt(6)" ::: "memory"); SBAR();
;   o[1] = __builtin_amdgcn_mfma_f32_32x32x16_bf16(pa0, PK(l4, h4), o[1], 0, 0, 0);
;   psm_slice<4>(n0, n1, mC, alpha, mx); SBAR();
;   const s16x4 l8 = tr_read<v_rd_off(2, 0, 0)>(vb), h8 = tr_read<v_rd_off(2, 0, 1)>(vb);
;   asm volatile("s_waitcnt lgkmcnt(6)" ::: "memory"); SBAR();
;   o[1] = __builtin_amdgcn_mfma_f32_32x32x16_bf16(pa1, PK(l5, h5), o[1], 0, 0, 0);
;   psm_slice<5>(n0, n1, mC, alpha, mx); SBAR();
;   const s16x4 l9 = tr_read<v_rd_off(2, 1, 0)>(vb), h9 = tr_read<v_rd_off(2, 1, 1)>(vb);
;   asm volatile("s_waitcnt lgkmcnt(6)" ::: "memory"); SBAR();
;   o[1] = __builtin_amdgcn_mfma_f32_32x32x16_bf16(pa2, PK(l6, h6), o[1], 0, 0, 0);
.LBB0_488:
	ds_read_b64_tr_b16 v[178:179], v211 offset:0
	ds_read_b64_tr_b16 v[180:181], v211 offset:0x800
	ds_read_b64_tr_b16 v[182:183], v211 offset:0x1000
	ds_read_b64_tr_b16 v[184:185], v211 offset:0x1800
	ds_read_b64_tr_b16 v[186:187], v211 offset:0x2000
	ds_read_b64_tr_b16 v[188:189], v211 offset:0x2800
	ds_read_b64_tr_b16 v[192:193], v211 offset:0x3000
	ds_read_b64_tr_b16 v[194:195], v211 offset:0x3800
	s_waitcnt lgkmcnt(6)
	s_nop 0
	v_mfma_f32_32x32x16_bf16 v[50:65], v[146:149], v[178:181], v[50:65]
	ds_read_b64_tr_b16 v[178:179], v211 offset:0x200
	ds_read_b64_tr_b16 v[180:181], v211 offset:0xa00
	s_waitcnt lgkmcnt(6)
	v_mfma_f32_32x32x16_bf16 v[50:65], v[150:153], v[182:185], v[50:65]
	v_max_f32_e32 v182, v102, v102
	v_max_f32_e32 v202, v98, v182
	v_max_f32_e32 v182, v103, v103
	v_max_f32_e32 v203, v99, v182
	v_max_f32_e32 v182, v105, v105
	v_max_f32_e32 v204, v101, v182
	ds_read_b64_tr_b16 v[182:183], v211 offset:0x1200
	ds_read_b64_tr_b16 v[184:185], v211 offset:0x1a00
	s_waitcnt lgkmcnt(6)
	v_mfma_f32_32x32x16_bf16 v[50:65], v[154:157], v[186:189], v[50:65]
	v_max3_f32 v205, v100, v104, v108
	ds_read_b64_tr_b16 v[186:187], v211 offset:0x2200
	ds_read_b64_tr_b16 v[188:189], v211 offset:0x2a00
	s_waitcnt lgkmcnt(6)
	v_mfma_f32_32x32x16_bf16 v[50:65], v[158:161], v[192:195], v[50:65]
	v_max3_f32 v202, v202, v106, v110
	v_max3_f32 v203, v203, v107, v111
	v_max3_f32 v204, v204, v109, v113
	ds_read_b64_tr_b16 v[192:193], v211 offset:0x3200
	ds_read_b64_tr_b16 v[194:195], v211 offset:0x3a00
	s_waitcnt lgkmcnt(6)
	v_mfma_f32_32x32x16_bf16 v[34:49], v[146:149], v[178:181], v[34:49]
	v_max3_f32 v205, v205, v112, v84
	ds_read_b64_tr_b16 v[244:245], v211 offset:0x400
	ds_read_b64_tr_b16 v[246:247], v211 offset:0xc00
	s_waitcnt lgkmcnt(6)
	v_mfma_f32_32x32x16_bf16 v[34:49], v[150:153], v[182:185], v[34:49]
	v_max3_f32 v202, v202, v82, v86
	v_max3_f32 v203, v203, v83, v87
	v_max3_f32 v204, v204, v85, v89
	ds_read_b64_tr_b16 v[178:179], v211 offset:0x1400
	ds_read_b64_tr_b16 v[180:181], v211 offset:0x1c00
	s_waitcnt lgkmcnt(6)
	v_mfma_f32_32x32x16_bf16 v[34:49], v[154:157], v[186:189], v[34:49]
	v_max3_f32 v205, v205, v88, v92
	ds_read_b64_tr_b16 v[182:183], v211 offset:0x2400
	ds_read_b64_tr_b16 v[184:185], v211 offset:0x2c00
	s_waitcnt lgkmcnt(6)
	v_mfma_f32_32x32x16_bf16 v[34:49], v[158:161], v[192:195], v[34:49]
	v_max3_f32 v192, v202, v90, v94
	v_max3_f32 v193, v203, v91, v95
	v_max3_f32 v194, v204, v93, v97
	ds_read_b64_tr_b16 v[186:187], v211 offset:0x3400
	ds_read_b64_tr_b16 v[188:189], v211 offset:0x3c00
	s_waitcnt lgkmcnt(6)
	v_mfma_f32_32x32x16_bf16 v[18:33], v[146:149], v[244:247], v[18:33]
	v_max3_f32 v194, v205, v96, v194
	v_max3_f32 v192, v192, v193, v194
	v_mov_b32_e32 v193, v192
	s_nop 1
	v_permlane32_swap_b32_e32 v192, v193
	v_max_f32_e32 v193, v193, v193
	v_max_f32_e32 v244, v192, v193
	v_cmp_ge_f32_e32 vcc, s48, v244
	s_cmp_eq_u64 vcc, exec
	v_mov_b32_e32 v242, 1.0
	s_cbranch_scc0 .LBB0_502
.LBB0_489:
	ds_read_b64_tr_b16 v[192:193], v211 offset:0x600
	ds_read_b64_tr_b16 v[194:195], v211 offset:0xe00
	s_waitcnt lgkmcnt(6)
	v_mfma_f32_32x32x16_bf16 v[18:33], v[150:153], v[178:181], v[18:33]
	ds_read_b64_tr_b16 v[178:179], v211 offset:0x1600
	ds_read_b64_tr_b16 v[180:181], v211 offset:0x1e00
	s_waitcnt lgkmcnt(6)
	v_mfma_f32_32x32x16_bf16 v[18:33], v[154:157], v[182:185], v[18:33]
	ds_read_b64_tr_b16 v[182:183], v211 offset:0x2600
	ds_read_b64_tr_b16 v[184:185], v211 offset:0x2e00
	s_waitcnt lgkmcnt(6)
	v_mfma_f32_32x32x16_bf16 v[18:33], v[158:161], v[186:189], v[18:33]
	ds_read_b64_tr_b16 v[186:187], v211 offset:0x3600
	ds_read_b64_tr_b16 v[188:189], v211 offset:0x3e00
	s_waitcnt lgkmcnt(6)
	v_mfma_f32_32x32x16_bf16 v[2:17], v[146:149], v[192:195], v[2:17]
	s_waitcnt lgkmcnt(4)
	v_mfma_f32_32x32x16_bf16 v[2:17], v[150:153], v[178:181], v[2:17]
	s_waitcnt lgkmcnt(2)
	v_mfma_f32_32x32x16_bf16 v[2:17], v[154:157], v[182:185], v[2:17]
	s_waitcnt lgkmcnt(0)
	v_mfma_f32_32x32x16_bf16 v[2:17], v[158:161], v[186:189], v[2:17]
	s_barrier
	s_waitcnt vmcnt(0)
	v_cmp_gt_f32_e32 vcc, 1.0, v242
	ds_write_b128 v214, v[162:165]
	ds_write_b128 v215, v[166:169]
	ds_write_b128 v216, v[170:173] offset:32768
	ds_write_b128 v217, v[174:177] offset:32768
	s_cbranch_vccz .LBB0_493
	s_and_saveexec_b64 s[8:9], s[4:5]
	ds_write_b32 v234, v242 offset:128
	s_or_b64 exec, exec, s[8:9]
	s_waitcnt lgkmcnt(0)
	v_add_u32_e32 v158, v191, v196
	ds_read_b128 v[146:149], v158 offset:224
	ds_read_b128 v[150:153], v158 offset:192
	ds_read_b128 v[154:157], v158 offset:160
	ds_read_b128 v[158:161], v158 offset:128
	s_waitcnt lgkmcnt(3)
	v_pk_mul_f32 v[62:63], v[62:63], v[146:147]
	s_waitcnt lgkmcnt(2)
	v_pk_mul_f32 v[58:59], v[58:59], v[150:151]
	s_waitcnt lgkmcnt(1)
	v_pk_mul_f32 v[54:55], v[54:55], v[154:155]
	v_pk_mul_f32 v[64:65], v[64:65], v[148:149]
	v_pk_mul_f32 v[60:61], v[60:61], v[152:153]
	v_pk_mul_f32 v[56:57], v[56:57], v[156:157]
	s_waitcnt lgkmcnt(0)
	v_pk_mul_f32 v[52:53], v[52:53], v[160:161]
	v_pk_mul_f32 v[50:51], v[50:51], v[158:159]
	v_pk_mul_f32 v[46:47], v[46:47], v[146:147]
	v_pk_mul_f32 v[42:43], v[42:43], v[150:151]
	v_pk_mul_f32 v[38:39], v[38:39], v[154:155]
	v_pk_mul_f32 v[48:49], v[48:49], v[148:149]
	v_pk_mul_f32 v[44:45], v[44:45], v[152:153]
	v_pk_mul_f32 v[40:41], v[40:41], v[156:157]
	v_pk_mul_f32 v[36:37], v[36:37], v[160:161]
	v_pk_mul_f32 v[34:35], v[34:35], v[158:159]
	v_pk_mul_f32 v[30:31], v[30:31], v[146:147]
	v_pk_mul_f32 v[26:27], v[26:27], v[150:151]
	v_pk_mul_f32 v[22:23], v[22:23], v[154:155]
	v_pk_mul_f32 v[32:33], v[32:33], v[148:149]
	v_pk_mul_f32 v[28:29], v[28:29], v[152:153]
	v_pk_mul_f32 v[24:25], v[24:25], v[156:157]
	v_pk_mul_f32 v[20:21], v[20:21], v[160:161]
	v_pk_mul_f32 v[18:19], v[18:19], v[158:159]
	v_pk_mul_f32 v[14:15], v[14:15], v[146:147]
	v_pk_mul_f32 v[10:11], v[10:11], v[150:151]
	v_pk_mul_f32 v[6:7], v[6:7], v[154:155]
	v_pk_mul_f32 v[16:17], v[16:17], v[148:149]
	v_pk_mul_f32 v[12:13], v[12:13], v[152:153]
	v_pk_mul_f32 v[8:9], v[8:9], v[156:157]
	v_pk_mul_f32 v[4:5], v[4:5], v[160:161]
	v_pk_mul_f32 v[2:3], v[2:3], v[158:159]

; __device__ __forceinline__ void pv_psm(f32x16* o, int vb, bf16x8 pa0, bf16x8 pa1, bf16x8 pa2, bf16x8 pa3, f32x16& n0, f32x16& n1, float& mC, float& alpha) {
;     ...
;   asm volatile("s_waitcnt lgkmcnt(6)" ::: "memory"); SBAR();
;   o[0] = __builtin_amdgcn_mfma_f32_32x32x16_bf16(pa0, PK(l0, h0), o[0], 0, 0, 0);
;   psm_slice<0>(n0, n1, mC, alpha, mx); SBAR();
;   const s16x4 l4 = tr_read<v_rd_off(1, 0, 0)>(vb), h4 = tr_read<v_rd_off(1, 0, 1)>(vb);
;   asm volatile("s_waitcnt lgkmcnt(6)" ::: "memory"); SBAR();
;   o[0] = __builtin_amdgcn_mfma_f32_32x32x16_bf16(pa1, PK(l1, h1), o[0], 0, 0, 0);
;   psm_slice<1>(n0, n1, mC, alpha, mx); SBAR();
;   const s16x4 l5 = tr_read<v_rd_off(1, 1, 0)>(vb), h5 = tr_read<v_rd_off(1, 1, 1)>(vb);
;   asm volatile("s_waitcnt lgkmcnt(6)" ::: "memory"); SBAR();
;   o[0] = __builtin_amdgcn_mfma_f32_32x32x16_bf16(pa2, PK(l2, h2), o[0], 0, 0, 0);
;   psm_slice<2>(n0, n1, mC, alpha, mx); SBAR();
;   const s16x4 l6 = tr_read<v_rd_off(1, 2, 0)>(vb), h6 = tr_read<v_rd_off(1, 2, 1)>(vb);
;   asm volatile("s_waitcnt lgkmcnt(6)" ::: "memory"); SBAR();
;   o[0] = __builtin_amdgcn_mfma_f32_32x32x16_bf16(pa3, PK(l3, h3), o[0], 0, 0, 0);
;   psm_slice<3>(n0, n1, mC, alpha, mx); SBAR();
;   const s16x4 l7 = tr_read<v_rd_off(1, 3, 0)>(vb), h7 = tr_read<v_rd_off(1, 3, 1)>(vb);
;   asm volatile("s_waitcnt lgkmcnt(6)" ::: "memory"); SBAR();
;   o[1] = __builtin_amdgcn_mfma_f32_32x32x16_bf16(pa0, PK(l4, h4), o[1], 0, 0, 0);
;   psm_slice<4>(n0, n1, mC, alpha, mx); SBAR();
;   const s16x4 l8 = tr_read<v_rd_off(2, 0, 0)>(vb), h8 = tr_read<v_rd_off(2, 0, 1)>(vb);
;   asm volatile("s_waitcnt lgkmcnt(6)" ::: "memory"); SBAR();
;   o[1] = __builtin_amdgcn_mfma_f32_32x32x16_bf16(pa1, PK(l5, h5), o[1], 0, 0, 0);
;   psm_slice<5>(n0, n1, mC, alpha, mx); SBAR();
;   const s16x4 l9 = tr_read<v_rd_off(2, 1, 0)>(vb), h9 = tr_read<v_rd_off(2, 1, 1)>(vb);
;   asm volatile("s_waitcnt lgkmcnt(6)" ::: "memory"); SBAR();
;   o[1] = __builtin_amdgcn_mfma_f32_32x32x16_bf16(pa2, PK(l6, h6), o[1], 0, 0, 0);
;   psm_slice<6>(n0, n1, mC, alpha, mx); SBAR();
;   const s16x4 l10 = tr_read<v_rd_off(2, 2, 0)>(vb), h10 = tr_read<v_rd_off(2, 2, 1)>(vb);
;   asm volatile("s_waitcnt lgkmcnt(6)" ::: "memory"); SBAR();
;   o[1] = __builtin_amdgcn_mfma_f32_32x32x16_bf16(pa3, PK(l7, h7), o[1], 0, 0, 0);
;   psm_slice<7>(n0, n1, mC, alpha, mx); SBAR();
.LBB0_495:
	ds_read_b64_tr_b16 v[178:179], v235 offset:0
	ds_read_b64_tr_b16 v[180:181], v235 offset:0x800
	ds_read_b64_tr_b16 v[182:183], v235 offset:0x1000
	ds_read_b64_tr_b16 v[184:185], v235 offset:0x1800
	ds_read_b64_tr_b16 v[186:187], v235 offset:0x2000
	ds_read_b64_tr_b16 v[188:189], v235 offset:0x2800
	ds_read_b64_tr_b16 v[192:193], v235 offset:0x3000
	ds_read_b64_tr_b16 v[194:195], v235 offset:0x3800
	s_waitcnt lgkmcnt(6)
	s_nop 0
	v_mfma_f32_32x32x16_bf16 v[50:65], v[146:149], v[178:181], v[50:65]
	ds_read_b64_tr_b16 v[178:179], v235 offset:0x200
	ds_read_b64_tr_b16 v[180:181], v235 offset:0xa00
	s_waitcnt lgkmcnt(6)
	v_mfma_f32_32x32x16_bf16 v[50:65], v[150:153], v[182:185], v[50:65]
	v_max_f32_e32 v182, v102, v102
	v_max_f32_e32 v202, v98, v182
	v_max_f32_e32 v182, v103, v103
	v_max_f32_e32 v203, v99, v182
	v_max_f32_e32 v182, v105, v105
	v_max_f32_e32 v204, v101, v182
	ds_read_b64_tr_b16 v[182:183], v235 offset:0x1200
	ds_read_b64_tr_b16 v[184:185], v235 offset:0x1a00
	s_waitcnt lgkmcnt(6)
	v_mfma_f32_32x32x16_bf16 v[50:65], v[154:157], v[186:189], v[50:65]
	v_max3_f32 v205, v100, v104, v108
	ds_read_b64_tr_b16 v[186:187], v235 offset:0x2200
	ds_read_b64_tr_b16 v[188:189], v235 offset:0x2a00
	s_waitcnt lgkmcnt(6)
	v_mfma_f32_32x32x16_bf16 v[50:65], v[158:161], v[192:195], v[50:65]
	v_max3_f32 v238, v202, v106, v110
	v_max3_f32 v246, v203, v107, v111
	v_max3_f32 v247, v204, v109, v113
	ds_read_b64_tr_b16 v[192:193], v235 offset:0x3200
	ds_read_b64_tr_b16 v[194:195], v235 offset:0x3a00
	s_waitcnt lgkmcnt(6)
	v_mfma_f32_32x32x16_bf16 v[34:49], v[146:149], v[178:181], v[34:49]
	v_max3_f32 v248, v205, v112, v84
	ds_read_b64_tr_b16 v[202:203], v235 offset:0x400
	ds_read_b64_tr_b16 v[204:205], v235 offset:0xc00
	s_waitcnt lgkmcnt(6)
	v_mfma_f32_32x32x16_bf16 v[34:49], v[150:153], v[182:185], v[34:49]
	v_max3_f32 v238, v238, v82, v86
	v_max3_f32 v246, v246, v83, v87
	v_max3_f32 v247, v247, v85, v89
	ds_read_b64_tr_b16 v[178:179], v235 offset:0x1400
	ds_read_b64_tr_b16 v[180:181], v235 offset:0x1c00
	s_waitcnt lgkmcnt(6)
	v_mfma_f32_32x32x16_bf16 v[34:49], v[154:157], v[186:189], v[34:49]
	v_max3_f32 v248, v248, v88, v92
	ds_read_b64_tr_b16 v[182:183], v235 offset:0x2400
	ds_read_b64_tr_b16 v[184:185], v235 offset:0x2c00
	s_waitcnt lgkmcnt(6)
	v_mfma_f32_32x32x16_bf16 v[34:49], v[158:161], v[192:195], v[34:49]
	v_max3_f32 v192, v238, v90, v94
	v_max3_f32 v193, v246, v91, v95
	v_max3_f32 v194, v247, v93, v97
	ds_read_b64_tr_b16 v[186:187], v235 offset:0x3400
	ds_read_b64_tr_b16 v[188:189], v235 offset:0x3c00
	s_waitcnt lgkmcnt(6)
	v_mfma_f32_32x32x16_bf16 v[18:33], v[146:149], v[202:205], v[18:33]
	v_max3_f32 v194, v248, v96, v194
	v_max3_f32 v192, v192, v193, v194
	v_mov_b32_e32 v193, v192
	s_nop 1
	v_permlane32_swap_b32_e32 v192, v193
	v_max_f32_e32 v193, v193, v193
	v_max_f32_e32 v246, v192, v193
	v_cmp_ge_f32_e32 vcc, s48, v246
	s_cmp_eq_u64 vcc, exec
	v_mov_b32_e32 v238, 1.0
	s_cbranch_scc0 .LBB0_503
.LBB0_496:
	ds_read_b64_tr_b16 v[192:193], v235 offset:0x600
	ds_read_b64_tr_b16 v[194:195], v235 offset:0xe00
	s_waitcnt lgkmcnt(6)
	v_mfma_f32_32x32x16_bf16 v[18:33], v[150:153], v[178:181], v[18:33]
	ds_read_b64_tr_b16 v[178:179], v235 offset:0x1600
	ds_read_b64_tr_b16 v[180:181], v235 offset:0x1e00
	s_waitcnt lgkmcnt(6)
	v_mfma_f32_32x32x16_bf16 v[18:33], v[154:157], v[182:185], v[18:33]
	ds_read_b64_tr_b16 v[182:183], v235 offset:0x2600
	ds_read_b64_tr_b16 v[184:185], v235 offset:0x2e00
	s_waitcnt lgkmcnt(6)
	v_mfma_f32_32x32x16_bf16 v[18:33], v[158:161], v[186:189], v[18:33]
	ds_read_b64_tr_b16 v[186:187], v235 offset:0x3600
	ds_read_b64_tr_b16 v[188:189], v235 offset:0x3e00
	s_waitcnt lgkmcnt(6)
	v_mfma_f32_32x32x16_bf16 v[2:17], v[146:149], v[192:195], v[2:17]
	s_waitcnt lgkmcnt(4)
	v_mfma_f32_32x32x16_bf16 v[2:17], v[150:153], v[178:181], v[2:17]
	s_waitcnt lgkmcnt(2)
	v_mfma_f32_32x32x16_bf16 v[2:17], v[154:157], v[182:185], v[2:17]
	s_waitcnt lgkmcnt(0)
	v_mfma_f32_32x32x16_bf16 v[2:17], v[158:161], v[186:189], v[2:17]
	s_barrier
	s_waitcnt vmcnt(0)
	v_cmp_gt_f32_e32 vcc, 1.0, v238
	ds_write_b128 v214, v[162:165] offset:16384
	ds_write_b128 v215, v[166:169] offset:16384
	ds_write_b128 v216, v[170:173] offset:49152
	ds_write_b128 v217, v[174:177] offset:49152
	s_cbranch_vccz .LBB0_500
	s_and_saveexec_b64 s[8:9], s[4:5]
	ds_write_b32 v234, v238 offset:128
	s_or_b64 exec, exec, s[8:9]
	s_waitcnt lgkmcnt(0)
	v_add_u32_e32 v158, v191, v196
	ds_read_b128 v[146:149], v158 offset:224
	ds_read_b128 v[150:153], v158 offset:192
	ds_read_b128 v[154:157], v158 offset:128
	ds_read_b128 v[158:161], v158 offset:160
	s_waitcnt lgkmcnt(3)
	v_pk_mul_f32 v[64:65], v[64:65], v[148:149]
	v_pk_mul_f32 v[62:63], v[62:63], v[146:147]
	s_waitcnt lgkmcnt(2)
	v_pk_mul_f32 v[60:61], v[60:61], v[152:153]
	v_pk_mul_f32 v[58:59], v[58:59], v[150:151]
	s_waitcnt lgkmcnt(0)
	v_pk_mul_f32 v[56:57], v[56:57], v[160:161]
	v_pk_mul_f32 v[54:55], v[54:55], v[158:159]
	v_pk_mul_f32 v[52:53], v[52:53], v[156:157]
	v_pk_mul_f32 v[50:51], v[50:51], v[154:155]
	v_pk_mul_f32 v[48:49], v[48:49], v[148:149]
	v_pk_mul_f32 v[46:47], v[46:47], v[146:147]
	v_pk_mul_f32 v[44:45], v[44:45], v[152:153]
	v_pk_mul_f32 v[42:43], v[42:43], v[150:151]
	v_pk_mul_f32 v[40:41], v[40:41], v[160:161]
	v_pk_mul_f32 v[38:39], v[38:39], v[158:159]
	v_pk_mul_f32 v[36:37], v[36:37], v[156:157]
	v_pk_mul_f32 v[34:35], v[34:35], v[154:155]
	v_pk_mul_f32 v[32:33], v[32:33], v[148:149]
	v_pk_mul_f32 v[30:31], v[30:31], v[146:147]
	v_pk_mul_f32 v[28:29], v[28:29], v[152:153]
	v_pk_mul_f32 v[26:27], v[26:27], v[150:151]
	v_pk_mul_f32 v[24:25], v[24:25], v[160:161]
	v_pk_mul_f32 v[22:23], v[22:23], v[158:159]
	v_pk_mul_f32 v[20:21], v[20:21], v[156:157]
	v_pk_mul_f32 v[18:19], v[18:19], v[154:155]
	v_pk_mul_f32 v[16:17], v[16:17], v[148:149]
	v_pk_mul_f32 v[14:15], v[14:15], v[146:147]
	v_pk_mul_f32 v[12:13], v[12:13], v[152:153]
	v_pk_mul_f32 v[10:11], v[10:11], v[150:151]
	v_pk_mul_f32 v[8:9], v[8:9], v[160:161]
	v_pk_mul_f32 v[6:7], v[6:7], v[158:159]
	v_pk_mul_f32 v[4:5], v[4:5], v[156:157]
	v_pk_mul_f32 v[2:3], v[2:3], v[154:155]
